# nt loads also for the prologue's read-once streams (modulation weights, layer-0 f32 weights, input rows)
# speedup vs baseline: 1.0208x; 1.0105x over previous
.LBB0_8:
	v_mov_b32_e32 v19, v228
	s_nop 0
	v_and_b32_e32 v2, 0x3ff, v19
	v_cmp_lt_u32_e32 vcc, s30, v19
	v_lshlrev_b32_e32 v8, 2, v2
	s_barrier
	s_and_saveexec_b64 s[24:25], vcc
	s_xor_b64 s[24:25], exec, s[24:25]
	v_ashrrev_i32_e32 v2, 10, v19
	v_ashrrev_i32_e32 v3, 31, v2
	v_lshlrev_b64 v[2:3], 12, v[2:3]
	v_lshl_add_u64 v[2:3], s[4:5], 0, v[2:3]
	v_lshl_add_u64 v[2:3], v[2:3], 0, v[8:9]
	v_lshl_add_u64 v[2:3], v[2:3], 0, s[20:21]
	s_andn2_saveexec_b64 s[24:25], s[24:25]
	v_lshl_add_u64 v[2:3], s[8:9], 0, v[8:9]
	s_or_b64 exec, exec, s[24:25]
	global_load_dword v6, v[2:3], off nt
	v_add_u32_e32 v3, 0x200, v19
	v_and_b32_e32 v2, 0x3ff, v3
	v_cmp_lt_u32_e32 vcc, s30, v3
	v_lshlrev_b32_e32 v2, 2, v2
	s_and_saveexec_b64 s[24:25], vcc
	s_xor_b64 s[24:25], exec, s[24:25]
	v_ashrrev_i32_e32 v4, 10, v3
	v_ashrrev_i32_e32 v5, 31, v4
	v_lshlrev_b64 v[4:5], 12, v[4:5]
	v_lshl_add_u64 v[4:5], s[4:5], 0, v[4:5]
	v_mov_b32_e32 v3, v9
	v_lshl_add_u64 v[2:3], v[4:5], 0, v[2:3]
	v_lshl_add_u64 v[4:5], v[2:3], 0, s[20:21]
	s_andn2_saveexec_b64 s[24:25], s[24:25]
	v_mov_b32_e32 v3, v9
	v_lshl_add_u64 v[4:5], s[8:9], 0, v[2:3]
	s_or_b64 exec, exec, s[24:25]
	global_load_dword v7, v[4:5], off nt
	v_cmp_gt_u32_e32 vcc, s31, v19
	s_and_saveexec_b64 s[24:25], vcc
	s_xor_b64 s[24:25], exec, s[24:25]
	v_add_u32_e32 v2, 0x400, v19
	v_ashrrev_i32_e32 v2, 10, v2
	v_ashrrev_i32_e32 v3, 31, v2
	v_lshlrev_b64 v[2:3], 12, v[2:3]
	v_lshl_add_u64 v[2:3], s[4:5], 0, v[2:3]
	v_lshl_add_u64 v[2:3], v[2:3], 0, v[8:9]
	v_lshl_add_u64 v[2:3], v[2:3], 0, s[20:21]
	s_andn2_saveexec_b64 s[24:25], s[24:25]
	v_lshl_add_u64 v[2:3], s[8:9], 0, v[8:9]
	s_or_b64 exec, exec, s[24:25]
	global_load_dword v10, v[2:3], off nt
	v_add_u32_e32 v3, 0x600, v19
	v_and_b32_e32 v2, 0x3ff, v3
	v_cmp_lt_u32_e32 vcc, s30, v3
	v_lshlrev_b32_e32 v2, 2, v2
	s_and_saveexec_b64 s[24:25], vcc
	s_xor_b64 s[24:25], exec, s[24:25]
	v_ashrrev_i32_e32 v4, 10, v3
	v_ashrrev_i32_e32 v5, 31, v4
	v_lshlrev_b64 v[4:5], 12, v[4:5]
	v_lshl_add_u64 v[4:5], s[4:5], 0, v[4:5]
	v_mov_b32_e32 v3, v9
	v_lshl_add_u64 v[2:3], v[4:5], 0, v[2:3]
	v_lshl_add_u64 v[4:5], v[2:3], 0, s[20:21]
	s_andn2_saveexec_b64 s[24:25], s[24:25]
	v_mov_b32_e32 v3, v9
	v_lshl_add_u64 v[4:5], s[8:9], 0, v[2:3]
	s_or_b64 exec, exec, s[24:25]
	global_load_dword v11, v[4:5], off nt
	v_add_u32_e32 v4, 0x800, v19
	v_cmp_lt_u32_e32 vcc, s30, v4
	s_and_saveexec_b64 s[24:25], vcc
	s_xor_b64 s[24:25], exec, s[24:25]
	v_ashrrev_i32_e32 v2, 10, v4
	v_ashrrev_i32_e32 v3, 31, v2
	v_lshlrev_b64 v[2:3], 12, v[2:3]
	v_lshl_add_u64 v[2:3], s[4:5], 0, v[2:3]
	v_lshl_add_u64 v[2:3], v[2:3], 0, v[8:9]
	v_lshl_add_u64 v[2:3], v[2:3], 0, s[20:21]
	s_andn2_saveexec_b64 s[24:25], s[24:25]
	v_lshl_add_u64 v[2:3], s[8:9], 0, v[8:9]
	s_or_b64 exec, exec, s[24:25]
	global_load_dword v12, v[2:3], off nt
	v_add_u32_e32 v3, 0xa00, v19
	v_and_b32_e32 v2, 0x3ff, v3
	v_cmp_lt_u32_e32 vcc, s30, v3
	v_lshlrev_b32_e32 v2, 2, v2
	s_and_saveexec_b64 s[24:25], vcc
	s_xor_b64 s[24:25], exec, s[24:25]
	v_ashrrev_i32_e32 v4, 10, v3
	v_ashrrev_i32_e32 v5, 31, v4
	v_lshlrev_b64 v[4:5], 12, v[4:5]
	v_lshl_add_u64 v[4:5], s[4:5], 0, v[4:5]
	v_mov_b32_e32 v3, v9
	v_lshl_add_u64 v[2:3], v[4:5], 0, v[2:3]
	v_lshl_add_u64 v[4:5], v[2:3], 0, s[20:21]
	s_andn2_saveexec_b64 s[24:25], s[24:25]
	v_mov_b32_e32 v3, v9
	v_lshl_add_u64 v[4:5], s[8:9], 0, v[2:3]
	s_or_b64 exec, exec, s[24:25]
	global_load_dword v13, v[4:5], off nt
	v_add_u32_e32 v4, 0xc00, v19
	v_cmp_lt_u32_e32 vcc, s30, v4
	s_and_saveexec_b64 s[24:25], vcc
	s_xor_b64 s[24:25], exec, s[24:25]
	v_ashrrev_i32_e32 v2, 10, v4
	v_ashrrev_i32_e32 v3, 31, v2
	v_lshlrev_b64 v[2:3], 12, v[2:3]
	v_lshl_add_u64 v[2:3], s[4:5], 0, v[2:3]
	v_lshl_add_u64 v[2:3], v[2:3], 0, v[8:9]
	v_lshl_add_u64 v[2:3], v[2:3], 0, s[20:21]
	s_andn2_saveexec_b64 s[24:25], s[24:25]
	v_lshl_add_u64 v[2:3], s[8:9], 0, v[8:9]
	s_or_b64 exec, exec, s[24:25]
	global_load_dword v14, v[2:3], off nt
	v_add_u32_e32 v3, 0xe00, v19
	v_and_b32_e32 v2, 0x3ff, v3
	v_cmp_lt_u32_e32 vcc, s30, v3
	v_lshlrev_b32_e32 v2, 2, v2
	s_and_saveexec_b64 s[24:25], vcc
	s_xor_b64 s[24:25], exec, s[24:25]
	v_ashrrev_i32_e32 v4, 10, v3
	v_ashrrev_i32_e32 v5, 31, v4
	v_lshlrev_b64 v[4:5], 12, v[4:5]
	v_lshl_add_u64 v[4:5], s[4:5], 0, v[4:5]
	v_mov_b32_e32 v3, v9
	v_lshl_add_u64 v[2:3], v[4:5], 0, v[2:3]
	v_lshl_add_u64 v[4:5], v[2:3], 0, s[20:21]
	s_andn2_saveexec_b64 s[24:25], s[24:25]
	v_mov_b32_e32 v3, v9
	v_lshl_add_u64 v[4:5], s[8:9], 0, v[2:3]
	s_or_b64 exec, exec, s[24:25]
	global_load_dword v15, v[4:5], off nt
	v_add_u32_e32 v4, 0x1000, v19
	v_cmp_lt_u32_e32 vcc, s30, v4
	s_and_saveexec_b64 s[24:25], vcc
	s_xor_b64 s[24:25], exec, s[24:25]
	v_ashrrev_i32_e32 v2, 10, v4
	v_ashrrev_i32_e32 v3, 31, v2
	v_lshlrev_b64 v[2:3], 12, v[2:3]
	v_lshl_add_u64 v[2:3], s[4:5], 0, v[2:3]
	v_lshl_add_u64 v[2:3], v[2:3], 0, v[8:9]
	v_lshl_add_u64 v[2:3], v[2:3], 0, s[20:21]
	s_andn2_saveexec_b64 s[24:25], s[24:25]
	v_lshl_add_u64 v[2:3], s[8:9], 0, v[8:9]
	s_or_b64 exec, exec, s[24:25]
	global_load_dword v16, v[2:3], off nt
	v_add_u32_e32 v3, 0x1200, v19
	v_and_b32_e32 v2, 0x3ff, v3
	v_cmp_lt_u32_e32 vcc, s30, v3
	v_lshlrev_b32_e32 v2, 2, v2
	s_and_saveexec_b64 s[24:25], vcc
	s_xor_b64 s[24:25], exec, s[24:25]
	v_ashrrev_i32_e32 v4, 10, v3
	v_ashrrev_i32_e32 v5, 31, v4
	v_lshlrev_b64 v[4:5], 12, v[4:5]
	v_lshl_add_u64 v[4:5], s[4:5], 0, v[4:5]
	v_mov_b32_e32 v3, v9
	v_lshl_add_u64 v[2:3], v[4:5], 0, v[2:3]
	v_lshl_add_u64 v[4:5], v[2:3], 0, s[20:21]
	s_andn2_saveexec_b64 s[24:25], s[24:25]
	v_mov_b32_e32 v3, v9
	v_lshl_add_u64 v[4:5], s[8:9], 0, v[2:3]
	s_or_b64 exec, exec, s[24:25]
	global_load_dword v17, v[4:5], off nt
	v_add_u32_e32 v4, 0x1400, v19
	v_cmp_lt_u32_e32 vcc, s30, v4
	s_and_saveexec_b64 s[24:25], vcc
	s_xor_b64 s[24:25], exec, s[24:25]
	v_ashrrev_i32_e32 v2, 10, v4
	v_ashrrev_i32_e32 v3, 31, v2
	v_lshlrev_b64 v[2:3], 12, v[2:3]
	v_lshl_add_u64 v[2:3], s[4:5], 0, v[2:3]
	v_lshl_add_u64 v[2:3], v[2:3], 0, v[8:9]
	v_lshl_add_u64 v[2:3], v[2:3], 0, s[20:21]
	s_andn2_saveexec_b64 s[24:25], s[24:25]
	v_lshl_add_u64 v[2:3], s[8:9], 0, v[8:9]
	s_or_b64 exec, exec, s[24:25]
	global_load_dword v18, v[2:3], off nt
	v_add_u32_e32 v3, 0x1600, v19
	v_and_b32_e32 v2, 0x3ff, v3
	v_cmp_lt_u32_e32 vcc, s30, v3
	v_lshlrev_b32_e32 v2, 2, v2
	s_and_saveexec_b64 s[24:25], vcc
	s_xor_b64 s[24:25], exec, s[24:25]
	v_ashrrev_i32_e32 v4, 10, v3
	v_ashrrev_i32_e32 v5, 31, v4
	v_lshlrev_b64 v[4:5], 12, v[4:5]
	v_lshl_add_u64 v[4:5], s[4:5], 0, v[4:5]
	v_mov_b32_e32 v3, v9
	v_lshl_add_u64 v[2:3], v[4:5], 0, v[2:3]
	v_lshl_add_u64 v[4:5], v[2:3], 0, s[20:21]
	s_andn2_saveexec_b64 s[24:25], s[24:25]
	v_mov_b32_e32 v3, v9
	v_lshl_add_u64 v[4:5], s[8:9], 0, v[2:3]
	s_or_b64 exec, exec, s[24:25]
	global_load_dword v20, v[4:5], off nt
	v_add_u32_e32 v4, 0x1800, v19
	v_cmp_lt_u32_e32 vcc, s30, v4
	s_and_saveexec_b64 s[24:25], vcc
	s_xor_b64 s[24:25], exec, s[24:25]
	v_ashrrev_i32_e32 v2, 10, v4
	v_ashrrev_i32_e32 v3, 31, v2
	v_lshlrev_b64 v[2:3], 12, v[2:3]
	v_lshl_add_u64 v[2:3], s[4:5], 0, v[2:3]
	v_lshl_add_u64 v[2:3], v[2:3], 0, v[8:9]
	v_lshl_add_u64 v[2:3], v[2:3], 0, s[20:21]
	s_andn2_saveexec_b64 s[24:25], s[24:25]
	v_lshl_add_u64 v[2:3], s[8:9], 0, v[8:9]
	s_or_b64 exec, exec, s[24:25]
	global_load_dword v21, v[2:3], off nt
	v_add_u32_e32 v3, 0x1a00, v19
	v_and_b32_e32 v2, 0x3ff, v3
	v_cmp_lt_u32_e32 vcc, s30, v3
	v_lshlrev_b32_e32 v2, 2, v2
	s_and_saveexec_b64 s[24:25], vcc
	s_xor_b64 s[24:25], exec, s[24:25]
	v_ashrrev_i32_e32 v4, 10, v3
	v_ashrrev_i32_e32 v5, 31, v4
	v_lshlrev_b64 v[4:5], 12, v[4:5]
	v_lshl_add_u64 v[4:5], s[4:5], 0, v[4:5]
	v_mov_b32_e32 v3, v9
	v_lshl_add_u64 v[2:3], v[4:5], 0, v[2:3]
	v_lshl_add_u64 v[4:5], v[2:3], 0, s[20:21]
	s_andn2_saveexec_b64 s[24:25], s[24:25]
	v_mov_b32_e32 v3, v9
	v_lshl_add_u64 v[4:5], s[8:9], 0, v[2:3]
	s_or_b64 exec, exec, s[24:25]
	global_load_dword v22, v[4:5], off nt
	v_add_u32_e32 v4, 0x1c00, v19
	v_cmp_lt_u32_e32 vcc, s30, v4
	s_and_saveexec_b64 s[24:25], vcc
	s_xor_b64 s[24:25], exec, s[24:25]
	v_ashrrev_i32_e32 v2, 10, v4
	v_ashrrev_i32_e32 v3, 31, v2
	v_lshlrev_b64 v[2:3], 12, v[2:3]
	v_lshl_add_u64 v[2:3], s[4:5], 0, v[2:3]
	v_lshl_add_u64 v[2:3], v[2:3], 0, v[8:9]
	v_lshl_add_u64 v[2:3], v[2:3], 0, s[20:21]
	s_andn2_saveexec_b64 s[24:25], s[24:25]
	v_lshl_add_u64 v[2:3], s[8:9], 0, v[8:9]
	s_or_b64 exec, exec, s[24:25]
	global_load_dword v24, v[2:3], off nt
	v_add_u32_e32 v3, 0x1e00, v19
	v_and_b32_e32 v2, 0x3ff, v3
	v_cmp_lt_u32_e32 vcc, s30, v3
	v_lshlrev_b32_e32 v2, 2, v2
	s_and_saveexec_b64 s[24:25], vcc
	s_xor_b64 s[24:25], exec, s[24:25]
	v_ashrrev_i32_e32 v4, 10, v3
	v_ashrrev_i32_e32 v5, 31, v4
	v_lshlrev_b64 v[4:5], 12, v[4:5]
	v_lshl_add_u64 v[4:5], s[4:5], 0, v[4:5]
	v_mov_b32_e32 v3, v9
	v_lshl_add_u64 v[2:3], v[4:5], 0, v[2:3]
	v_lshl_add_u64 v[4:5], v[2:3], 0, s[20:21]
	s_andn2_saveexec_b64 s[24:25], s[24:25]
	v_mov_b32_e32 v3, v9
	v_lshl_add_u64 v[4:5], s[8:9], 0, v[2:3]
	s_or_b64 exec, exec, s[24:25]
	global_load_dword v4, v[4:5], off nt
	v_add_u32_e32 v5, 0x2000, v19
	v_cmp_lt_u32_e32 vcc, s30, v5
	s_and_saveexec_b64 s[24:25], vcc
	s_xor_b64 s[24:25], exec, s[24:25]
	v_ashrrev_i32_e32 v2, 10, v5
	v_ashrrev_i32_e32 v3, 31, v2
	v_lshlrev_b64 v[2:3], 12, v[2:3]
	v_lshl_add_u64 v[2:3], s[4:5], 0, v[2:3]
	v_lshl_add_u64 v[2:3], v[2:3], 0, v[8:9]
	v_lshl_add_u64 v[2:3], v[2:3], 0, s[20:21]
	s_andn2_saveexec_b64 s[24:25], s[24:25]
	v_lshl_add_u64 v[2:3], s[8:9], 0, v[8:9]
	s_or_b64 exec, exec, s[24:25]
	global_load_dword v5, v[2:3], off nt
	v_add_u32_e32 v23, 0x2200, v19
	v_and_b32_e32 v2, 0x3ff, v23
	v_cmp_lt_u32_e32 vcc, s30, v23
	v_lshlrev_b32_e32 v8, 2, v2
	s_and_saveexec_b64 s[24:25], vcc
	s_xor_b64 s[24:25], exec, s[24:25]
	v_ashrrev_i32_e32 v2, 10, v23
	v_ashrrev_i32_e32 v3, 31, v2
	v_lshlrev_b64 v[2:3], 12, v[2:3]
	v_lshl_add_u64 v[2:3], s[4:5], 0, v[2:3]
	v_lshl_add_u64 v[2:3], v[2:3], 0, v[8:9]
	v_lshl_add_u64 v[2:3], v[2:3], 0, s[20:21]
	s_andn2_saveexec_b64 s[24:25], s[24:25]
	v_lshl_add_u64 v[2:3], s[8:9], 0, v[8:9]
	s_or_b64 exec, exec, s[24:25]
	global_load_dword v2, v[2:3], off nt
	s_waitcnt vmcnt(17)
	v_mul_f32_e32 v8, 0xbfb8aa3b, v6
	s_waitcnt vmcnt(16)
	v_mul_f32_e32 v23, 0xbfb8aa3b, v7
	v_exp_f32_e32 v8, v8
	v_exp_f32_e32 v25, v23
	v_lshl_add_u32 v3, v19, 2, 0
	s_mul_hi_i32 s24, s46, 0x2aaaaaab
	v_add_f32_e32 v8, 1.0, v8
	v_add_f32_e32 v25, 1.0, v25
	v_rcp_f32_e32 v8, v8
	v_rcp_f32_e32 v25, v25
	s_lshr_b32 s25, s24, 31
	s_ashr_i32 s24, s24, 4
	v_mul_f32_e32 v6, v6, v8
	v_mul_f32_e32 v7, v7, v25
	s_waitcnt vmcnt(15)
	v_mul_f32_e32 v8, 0xbfb8aa3b, v10
	s_waitcnt vmcnt(14)
	v_mul_f32_e32 v25, 0xbfb8aa3b, v11
	v_exp_f32_e32 v8, v8
	v_exp_f32_e32 v25, v25
	ds_write2st64_b32 v3, v6, v7 offset1:8
	s_add_i32 s47, s24, s25
	v_add_f32_e32 v6, 1.0, v8
	v_add_f32_e32 v7, 1.0, v25
	v_rcp_f32_e32 v6, v6
	v_rcp_f32_e32 v7, v7
	s_waitcnt vmcnt(13)
	v_mul_f32_e32 v8, 0xbfb8aa3b, v12
	v_exp_f32_e32 v8, v8
	v_mul_f32_e32 v6, v10, v6
	v_mul_f32_e32 v7, v11, v7
	ds_write2st64_b32 v3, v6, v7 offset0:16 offset1:24
	s_waitcnt vmcnt(12)
	v_mul_f32_e32 v7, 0xbfb8aa3b, v13
	v_add_f32_e32 v6, 1.0, v8
	v_exp_f32_e32 v7, v7
	s_waitcnt vmcnt(11)
	v_mul_f32_e32 v8, 0xbfb8aa3b, v14
	v_exp_f32_e32 v8, v8
	v_rcp_f32_e32 v6, v6
	v_add_f32_e32 v7, 1.0, v7
	v_rcp_f32_e32 v7, v7
	v_add_f32_e32 v8, 1.0, v8
	s_waitcnt vmcnt(10)
	v_mul_f32_e32 v10, 0xbfb8aa3b, v15
	v_rcp_f32_e32 v8, v8
	v_exp_f32_e32 v10, v10
	v_mul_f32_e32 v6, v12, v6
	v_mul_f32_e32 v7, v13, v7
	ds_write2st64_b32 v3, v6, v7 offset0:32 offset1:40
	v_mul_f32_e32 v6, v14, v8
	v_add_f32_e32 v7, 1.0, v10
	s_waitcnt vmcnt(9)
	v_mul_f32_e32 v8, 0xbfb8aa3b, v16
	s_waitcnt vmcnt(8)
	v_mul_f32_e32 v10, 0xbfb8aa3b, v17
	v_exp_f32_e32 v8, v8
	v_exp_f32_e32 v10, v10
	v_rcp_f32_e32 v7, v7
	s_mul_i32 s24, s47, 0x60
	v_add_f32_e32 v8, 1.0, v8
	v_add_f32_e32 v10, 1.0, v10
	v_rcp_f32_e32 v8, v8
	v_rcp_f32_e32 v10, v10
	v_mul_f32_e32 v7, v15, v7
	ds_write2st64_b32 v3, v6, v7 offset0:48 offset1:56
	v_mul_f32_e32 v6, v16, v8
	v_mul_f32_e32 v7, v17, v10
	s_waitcnt vmcnt(7)
	v_mul_f32_e32 v8, 0xbfb8aa3b, v18
	s_waitcnt vmcnt(6)
	v_mul_f32_e32 v10, 0xbfb8aa3b, v20
	v_exp_f32_e32 v8, v8
	v_exp_f32_e32 v10, v10
	ds_write2st64_b32 v3, v6, v7 offset0:64 offset1:72
	s_sub_i32 s24, s46, s24
	v_add_f32_e32 v6, 1.0, v8
	v_add_f32_e32 v7, 1.0, v10
	v_rcp_f32_e32 v6, v6
	v_rcp_f32_e32 v7, v7
	s_waitcnt vmcnt(5)
	v_mul_f32_e32 v8, 0xbfb8aa3b, v21
	v_exp_f32_e32 v8, v8
	v_mul_f32_e32 v6, v18, v6
	v_mul_f32_e32 v7, v20, v7
	ds_write2st64_b32 v3, v6, v7 offset0:80 offset1:88
	s_waitcnt vmcnt(4)
	v_mul_f32_e32 v7, 0xbfb8aa3b, v22
	v_add_f32_e32 v6, 1.0, v8
	v_exp_f32_e32 v7, v7
	s_waitcnt vmcnt(3)
	v_mul_f32_e32 v8, 0xbfb8aa3b, v24
	v_exp_f32_e32 v8, v8
	v_rcp_f32_e32 v6, v6
	v_add_f32_e32 v7, 1.0, v7
	v_rcp_f32_e32 v7, v7
	v_add_f32_e32 v8, 1.0, v8
	s_waitcnt vmcnt(2)
	v_mul_f32_e32 v10, 0xbfb8aa3b, v4
	v_rcp_f32_e32 v8, v8
	v_exp_f32_e32 v10, v10
	v_mul_f32_e32 v6, v21, v6
	v_mul_f32_e32 v7, v22, v7
	ds_write2st64_b32 v3, v6, v7 offset0:96 offset1:104
	v_mul_f32_e32 v6, v24, v8
	v_add_f32_e32 v7, 1.0, v10
	s_waitcnt vmcnt(1)
	v_mul_f32_e32 v8, 0xbfb8aa3b, v5
	s_waitcnt vmcnt(0)
	v_mul_f32_e32 v10, 0xbfb8aa3b, v2
	v_exp_f32_e32 v8, v8
	v_exp_f32_e32 v10, v10
	v_rcp_f32_e32 v7, v7
	s_lshl_b32 s24, s24, 6
	v_add_f32_e32 v8, 1.0, v8
	v_add_f32_e32 v10, 1.0, v10
	v_rcp_f32_e32 v8, v8
	v_rcp_f32_e32 v10, v10
	s_mul_i32 s28, s47, 0x1800000
	s_mul_hi_i32 s25, s47, 0x1800000
	s_add_u32 s28, s10, s28
	v_mul_f32_e32 v4, v4, v7
	s_addc_u32 s29, s11, s25
	ds_write2st64_b32 v3, v6, v4 offset0:112 offset1:120
	v_mul_f32_e32 v4, v5, v8
	v_mul_f32_e32 v2, v2, v10
	v_ashrrev_i32_e32 v43, 6, v19
	ds_write2st64_b32 v3, v4, v2 offset0:128 offset1:136
	v_lshlrev_b32_e32 v4, 7, v43
	v_mov_b64_e32 v[2:3], s[28:29]
	v_and_b32_e32 v23, 63, v19
	v_mad_i64_i32 v[2:3], s[28:29], v4, s34, v[2:3]
	s_ashr_i32 s25, s24, 31
	v_lshl_add_u64 v[2:3], s[24:25], 2, v[2:3]
	v_lshlrev_b32_e32 v8, 2, v23
	v_mov_b32_e32 v10, 0
	v_lshl_add_u64 v[14:15], v[2:3], 0, v[8:9]
	v_lshl_add_u32 v47, v43, 9, 0
	s_movk_i32 s25, 0xffe0
	v_mov_b32_e32 v11, v10
	v_mov_b32_e32 v30, v10
	v_mov_b32_e32 v31, v10
	v_mov_b32_e32 v32, v10
	v_mov_b32_e32 v33, v10
	v_mov_b32_e32 v34, v10
	v_mov_b32_e32 v35, v10
	v_mov_b32_e32 v17, v10
	s_waitcnt lgkmcnt(0)
	s_barrier
.LBB0_81:
	v_add_co_u32_e32 v2, vcc, 0x6000, v14
	global_load_dword v70, v[14:15], off nt
	s_nop 0
	v_addc_co_u32_e32 v3, vcc, 0, v15, vcc
	global_load_dword v72, v[2:3], off nt
	v_add_co_u32_e32 v2, vcc, 0xc000, v14
	v_add_u32_e32 v41, 0x402c, v47
	s_nop 0
	v_addc_co_u32_e32 v3, vcc, 0, v15, vcc
	global_load_dword v74, v[2:3], off nt
	v_add_co_u32_e32 v2, vcc, 0x12000, v14
	v_add_u32_e32 v39, 0x302c, v47
	s_nop 0
	v_addc_co_u32_e32 v3, vcc, 0, v15, vcc
	global_load_dword v76, v[2:3], off nt
	v_add_co_u32_e32 v2, vcc, 0x18000, v14
	v_add_u32_e32 v55, 0x1034, v47
	s_nop 0
	v_addc_co_u32_e32 v3, vcc, 0, v15, vcc
	global_load_dword v58, v[2:3], off nt
	v_add_co_u32_e32 v2, vcc, 0x1e000, v14
	v_add_u32_e32 v49, 0x502c, v47
	s_nop 0
	v_addc_co_u32_e32 v3, vcc, 0, v15, vcc
	global_load_dword v60, v[2:3], off nt
	v_add_co_u32_e32 v2, vcc, 0x24000, v14
	v_add_u32_e32 v53, 0x702c, v47
	s_nop 0
	v_addc_co_u32_e32 v3, vcc, 0, v15, vcc
	global_load_dword v62, v[2:3], off nt
	v_add_co_u32_e32 v2, vcc, 0x2a000, v14
	v_add_u32_e32 v51, 0x602c, v47
	s_nop 0
	v_addc_co_u32_e32 v3, vcc, 0, v15, vcc
	global_load_dword v66, v[2:3], off nt
	v_add_co_u32_e32 v2, vcc, 0x30000, v14
	v_add_u32_e32 v57, 0x2034, v47
	s_nop 0
	v_addc_co_u32_e32 v3, vcc, 0, v15, vcc
	global_load_dword v64, v[2:3], off nt
	v_add_co_u32_e32 v2, vcc, 0x36000, v14
	v_add_u32_e32 v37, 0x202c, v47
	s_nop 0
	v_addc_co_u32_e32 v3, vcc, 0, v15, vcc
	global_load_dword v68, v[2:3], off nt
	v_add_co_u32_e32 v2, vcc, 0x3c000, v14
	s_add_i32 s25, s25, 32
	s_nop 0
	v_addc_co_u32_e32 v3, vcc, 0, v15, vcc
	global_load_dword v40, v[2:3], off nt
	v_add_co_u32_e32 v2, vcc, 0x42000, v14
	s_cmpk_gt_u32 s25, 0x5f
	s_nop 0
	v_addc_co_u32_e32 v3, vcc, 0, v15, vcc
	global_load_dword v38, v[2:3], off nt
	v_add_co_u32_e32 v2, vcc, 0x48000, v14
	s_nop 1
	v_addc_co_u32_e32 v3, vcc, 0, v15, vcc
	global_load_dword v44, v[2:3], off nt
	v_add_co_u32_e32 v2, vcc, 0x4e000, v14
	s_nop 1
	v_addc_co_u32_e32 v3, vcc, 0, v15, vcc
	global_load_dword v42, v[2:3], off nt
	v_add_co_u32_e32 v2, vcc, 0x54000, v14
	s_nop 1
	v_addc_co_u32_e32 v3, vcc, 0, v15, vcc
	global_load_dword v48, v[2:3], off nt
	v_add_co_u32_e32 v2, vcc, 0x5a000, v14
	s_nop 1
	v_addc_co_u32_e32 v3, vcc, 0, v15, vcc
	global_load_dword v46, v[2:3], off nt
	v_add_co_u32_e32 v2, vcc, 0x60000, v14
	s_nop 1
	v_addc_co_u32_e32 v3, vcc, 0, v15, vcc
	global_load_dword v52, v[2:3], off nt
	v_add_co_u32_e32 v2, vcc, 0x66000, v14
	s_nop 1
	v_addc_co_u32_e32 v3, vcc, 0, v15, vcc
	global_load_dword v50, v[2:3], off nt
	v_add_co_u32_e32 v2, vcc, 0x6c000, v14
	s_nop 1
	v_addc_co_u32_e32 v3, vcc, 0, v15, vcc
	global_load_dword v56, v[2:3], off nt
	v_add_co_u32_e32 v2, vcc, 0x72000, v14
	s_nop 1
	v_addc_co_u32_e32 v3, vcc, 0, v15, vcc
	global_load_dword v54, v[2:3], off nt
	v_add_co_u32_e32 v2, vcc, 0x78000, v14
	s_nop 1
	v_addc_co_u32_e32 v3, vcc, 0, v15, vcc
	global_load_dword v36, v[2:3], off nt
	v_add_co_u32_e32 v2, vcc, 0x7e000, v14
	s_nop 1
	v_addc_co_u32_e32 v3, vcc, 0, v15, vcc
	global_load_dword v22, v[2:3], off nt
	v_add_co_u32_e32 v2, vcc, 0x84000, v14
	s_nop 1
	v_addc_co_u32_e32 v3, vcc, 0, v15, vcc
	global_load_dword v20, v[2:3], off nt
	v_add_co_u32_e32 v2, vcc, 0x8a000, v14
	s_nop 1
	v_addc_co_u32_e32 v3, vcc, 0, v15, vcc
	global_load_dword v21, v[2:3], off nt
	v_add_co_u32_e32 v2, vcc, 0x90000, v14
	s_nop 1
	v_addc_co_u32_e32 v3, vcc, 0, v15, vcc
	global_load_dword v24, v[2:3], off nt
	v_add_co_u32_e32 v2, vcc, 0x96000, v14
	s_nop 1
	v_addc_co_u32_e32 v3, vcc, 0, v15, vcc
	global_load_dword v25, v[2:3], off nt
	v_add_co_u32_e32 v2, vcc, 0x9c000, v14
	s_nop 1
	v_addc_co_u32_e32 v3, vcc, 0, v15, vcc
	global_load_dword v26, v[2:3], off nt
	v_add_co_u32_e32 v2, vcc, 0xa2000, v14
	s_nop 1
	v_addc_co_u32_e32 v3, vcc, 0, v15, vcc
	global_load_dword v27, v[2:3], off nt
	v_add_co_u32_e32 v2, vcc, 0xa8000, v14
	s_nop 1
	v_addc_co_u32_e32 v3, vcc, 0, v15, vcc
	global_load_dword v28, v[2:3], off nt
	v_add_co_u32_e32 v2, vcc, 0xae000, v14
	s_nop 1
	v_addc_co_u32_e32 v3, vcc, 0, v15, vcc
	global_load_dword v29, v[2:3], off nt
	v_add_co_u32_e32 v2, vcc, 0xb4000, v14
	s_nop 1
	v_addc_co_u32_e32 v3, vcc, 0, v15, vcc
	global_load_dword v16, v[2:3], off nt
	v_add_co_u32_e32 v2, vcc, 0xba000, v14
	s_nop 1
	v_addc_co_u32_e32 v3, vcc, 0, v15, vcc
	global_load_dword v18, v[2:3], off nt
	ds_read_b128 v[2:5], v47 offset:32768
	v_lshl_add_u64 v[14:15], v[14:15], 0, s[22:23]
	s_waitcnt vmcnt(31) lgkmcnt(0)
	v_fmac_f32_e32 v17, v70, v2
	s_waitcnt vmcnt(30)
	v_fmac_f32_e32 v17, v72, v3
	s_waitcnt vmcnt(29)
	v_fmac_f32_e32 v17, v74, v4
	s_waitcnt vmcnt(28)
	v_fmac_f32_e32 v17, v76, v5
	ds_read_b128 v[2:5], v47 offset:32784
	s_waitcnt vmcnt(27) lgkmcnt(0)
	v_fmac_f32_e32 v17, v58, v2
	s_waitcnt vmcnt(26)
	v_fmac_f32_e32 v17, v60, v3
	s_waitcnt vmcnt(25)
	v_fmac_f32_e32 v17, v62, v4
	s_waitcnt vmcnt(24)
	v_fmac_f32_e32 v17, v66, v5
	ds_read_b128 v[2:5], v47 offset:32800
	ds_read_b128 v[78:81], v47
	ds_read_b128 v[82:85], v47 offset:16
	ds_read_b96 v[6:8], v47 offset:32
	ds_read_b128 v[86:89], v47 offset:4096
	s_waitcnt lgkmcnt(3)
	v_mov_b32_e32 v12, v78
	s_waitcnt vmcnt(23)
	v_fmac_f32_e32 v17, v64, v2
	s_waitcnt lgkmcnt(0)
	v_mov_b32_e32 v13, v86
	v_pk_fma_f32 v[10:11], v[70:71], v[12:13], v[10:11] op_sel_hi:[0,1,1]
	v_mov_b32_e32 v86, v79
	v_pk_fma_f32 v[10:11], v[72:73], v[86:87], v[10:11] op_sel_hi:[0,1,1]
	v_mov_b32_e32 v12, v80
	v_mov_b32_e32 v13, v88
	v_pk_fma_f32 v[10:11], v[74:75], v[12:13], v[10:11] op_sel_hi:[0,1,1]
	v_mov_b32_e32 v88, v81
	v_pk_fma_f32 v[78:79], v[76:77], v[88:89], v[10:11] op_sel_hi:[0,1,1]
	ds_read_b128 v[10:13], v47 offset:4112
	v_mov_b32_e32 v80, v82
	s_waitcnt vmcnt(22)
	v_fmac_f32_e32 v17, v68, v3
	s_waitcnt vmcnt(21)
	v_fmac_f32_e32 v17, v40, v4
	s_waitcnt vmcnt(20)
	v_fmac_f32_e32 v17, v38, v5
	s_waitcnt lgkmcnt(0)
	v_mov_b32_e32 v81, v10
	v_pk_fma_f32 v[78:79], v[58:59], v[80:81], v[78:79] op_sel_hi:[0,1,1]
	v_mov_b32_e32 v10, v83
	v_pk_fma_f32 v[10:11], v[60:61], v[10:11], v[78:79] op_sel_hi:[0,1,1]
	v_mov_b32_e32 v78, v84
	v_mov_b32_e32 v79, v12
	v_pk_fma_f32 v[10:11], v[62:63], v[78:79], v[10:11] op_sel_hi:[0,1,1]
	v_mov_b32_e32 v12, v85
	v_pk_fma_f32 v[78:79], v[66:67], v[12:13], v[10:11] op_sel_hi:[0,1,1]
	ds_read_b96 v[10:12], v47 offset:4128
	v_mov_b32_e32 v80, v6
	v_add_u32_e32 v87, 0x504c, v47
	s_waitcnt lgkmcnt(0)
	v_mov_b32_e32 v81, v10
	v_pk_fma_f32 v[78:79], v[64:65], v[80:81], v[78:79] op_sel_hi:[0,1,1]
	v_mov_b32_e32 v10, v7
	v_pk_fma_f32 v[10:11], v[68:69], v[10:11], v[78:79] op_sel_hi:[0,1,1]
	ds_read_b128 v[78:81], v47 offset:8192
	ds_read_b128 v[82:85], v47 offset:12288
	s_waitcnt lgkmcnt(1)
	v_mov_b32_e32 v6, v78
	s_waitcnt lgkmcnt(0)
	v_mov_b32_e32 v7, v82
	v_pk_fma_f32 v[6:7], v[70:71], v[6:7], v[30:31] op_sel_hi:[0,1,1]
	v_mov_b32_e32 v82, v79
	v_pk_fma_f32 v[6:7], v[72:73], v[82:83], v[6:7] op_sel_hi:[0,1,1]
	v_mov_b32_e32 v30, v80
	v_mov_b32_e32 v31, v84
	v_pk_fma_f32 v[6:7], v[74:75], v[30:31], v[6:7] op_sel_hi:[0,1,1]
	v_mov_b32_e32 v84, v81
	v_pk_fma_f32 v[6:7], v[76:77], v[84:85], v[6:7] op_sel_hi:[0,1,1]
	ds_read_b128 v[78:81], v47 offset:8208
	ds_read_b128 v[82:85], v47 offset:12304
	s_waitcnt lgkmcnt(1)
	v_mov_b32_e32 v30, v78
	s_waitcnt lgkmcnt(0)
	v_mov_b32_e32 v31, v82
	v_pk_fma_f32 v[6:7], v[58:59], v[30:31], v[6:7] op_sel_hi:[0,1,1]
	v_mov_b32_e32 v82, v79
	v_pk_fma_f32 v[6:7], v[60:61], v[82:83], v[6:7] op_sel_hi:[0,1,1]
	v_mov_b32_e32 v30, v80
	v_mov_b32_e32 v31, v84
	v_pk_fma_f32 v[6:7], v[62:63], v[30:31], v[6:7] op_sel_hi:[0,1,1]
	v_mov_b32_e32 v84, v81
	v_pk_fma_f32 v[6:7], v[66:67], v[84:85], v[6:7] op_sel_hi:[0,1,1]
	ds_read_b96 v[84:86], v47 offset:8224
	ds_read_b96 v[88:90], v47 offset:12320
	s_waitcnt lgkmcnt(1)
	v_mov_b32_e32 v30, v84
	s_waitcnt lgkmcnt(0)
	v_mov_b32_e32 v31, v88
	v_mov_b32_e32 v88, v85
	ds_read_b128 v[78:81], v47 offset:16384
	ds_read_b128 v[82:85], v47 offset:20480
	v_pk_fma_f32 v[6:7], v[64:65], v[30:31], v[6:7] op_sel_hi:[0,1,1]
	v_pk_fma_f32 v[6:7], v[68:69], v[88:89], v[6:7] op_sel_hi:[0,1,1]
	v_add_u32_e32 v88, 0x604c, v47
	s_waitcnt lgkmcnt(1)
	v_mov_b32_e32 v30, v78
	s_waitcnt lgkmcnt(0)
	v_mov_b32_e32 v31, v82
	v_pk_fma_f32 v[30:31], v[70:71], v[30:31], v[32:33] op_sel_hi:[0,1,1]
	v_mov_b32_e32 v82, v79
	v_pk_fma_f32 v[30:31], v[72:73], v[82:83], v[30:31] op_sel_hi:[0,1,1]
	v_mov_b32_e32 v32, v80
	v_mov_b32_e32 v33, v84
	v_pk_fma_f32 v[30:31], v[74:75], v[32:33], v[30:31] op_sel_hi:[0,1,1]
	v_mov_b32_e32 v84, v81
	v_pk_fma_f32 v[82:83], v[76:77], v[84:85], v[30:31] op_sel_hi:[0,1,1]
	ds_read_b128 v[30:33], v47 offset:16400
	ds_read_b128 v[78:81], v47 offset:20496
	ds_read_b96 v[92:94], v47 offset:16416
	ds_read_b96 v[96:98], v47 offset:20512
	v_add_u32_e32 v89, 0x704c, v47
	s_waitcnt lgkmcnt(3)
	v_mov_b32_e32 v84, v30
	s_waitcnt lgkmcnt(2)
	v_mov_b32_e32 v85, v78
	v_pk_fma_f32 v[82:83], v[58:59], v[84:85], v[82:83] op_sel_hi:[0,1,1]
	v_mov_b32_e32 v78, v31
	v_pk_fma_f32 v[30:31], v[60:61], v[78:79], v[82:83] op_sel_hi:[0,1,1]
	v_mov_b32_e32 v78, v32
	v_mov_b32_e32 v79, v80
	v_pk_fma_f32 v[30:31], v[62:63], v[78:79], v[30:31] op_sel_hi:[0,1,1]
	v_mov_b32_e32 v80, v33
	v_pk_fma_f32 v[30:31], v[66:67], v[80:81], v[30:31] op_sel_hi:[0,1,1]
	ds_read_b128 v[78:81], v47 offset:24576
	ds_read_b128 v[82:85], v47 offset:28672
	s_waitcnt lgkmcnt(3)
	v_mov_b32_e32 v32, v92
	s_waitcnt lgkmcnt(2)
	v_mov_b32_e32 v33, v96
	v_pk_fma_f32 v[30:31], v[64:65], v[32:33], v[30:31] op_sel_hi:[0,1,1]
	v_mov_b32_e32 v96, v93
	v_pk_fma_f32 v[32:33], v[68:69], v[96:97], v[30:31] op_sel_hi:[0,1,1]
	s_waitcnt lgkmcnt(1)
	v_mov_b32_e32 v30, v78
	s_waitcnt lgkmcnt(0)
	v_mov_b32_e32 v31, v82
	v_pk_fma_f32 v[30:31], v[70:71], v[30:31], v[34:35] op_sel_hi:[0,1,1]
	v_mov_b32_e32 v82, v79
	v_pk_fma_f32 v[30:31], v[72:73], v[82:83], v[30:31] op_sel_hi:[0,1,1]
	v_mov_b32_e32 v34, v80
	v_mov_b32_e32 v35, v84
	v_pk_fma_f32 v[30:31], v[74:75], v[34:35], v[30:31] op_sel_hi:[0,1,1]
	v_mov_b32_e32 v84, v81
	v_pk_fma_f32 v[30:31], v[76:77], v[84:85], v[30:31] op_sel_hi:[0,1,1]
	ds_read_b128 v[70:73], v47 offset:24592
	ds_read_b128 v[74:77], v47 offset:28688
	v_add_u32_e32 v83, 0x104c, v47
	v_add_u32_e32 v78, 0x3044, v47
	v_add_u32_e32 v84, 0x204c, v47
	s_waitcnt lgkmcnt(1)
	v_mov_b32_e32 v34, v70
	s_waitcnt lgkmcnt(0)
	v_mov_b32_e32 v35, v74
	v_pk_fma_f32 v[30:31], v[58:59], v[34:35], v[30:31] op_sel_hi:[0,1,1]
	v_mov_b32_e32 v74, v71
	v_pk_fma_f32 v[30:31], v[60:61], v[74:75], v[30:31] op_sel_hi:[0,1,1]
	v_mov_b32_e32 v34, v72
	ds_read_b96 v[58:60], v47 offset:24608
	ds_read_b96 v[70:72], v47 offset:28704
	v_mov_b32_e32 v35, v76
	v_pk_fma_f32 v[30:31], v[62:63], v[34:35], v[30:31] op_sel_hi:[0,1,1]
	v_mov_b32_e32 v62, v8
	s_waitcnt lgkmcnt(1)
	v_mov_b32_e32 v34, v58
	s_waitcnt lgkmcnt(0)
	v_mov_b32_e32 v35, v70
	v_mov_b32_e32 v70, v59
	v_mov_b32_e32 v2, v60
	ds_read_b128 v[58:61], v47 offset:32816
	v_mov_b32_e32 v63, v12
	v_add_u32_e32 v8, 0x102c, v47
	v_pk_fma_f32 v[4:5], v[40:41], v[62:63], v[10:11] op_sel_hi:[0,1,1]
	v_mov_b32_e32 v76, v73
	s_waitcnt vmcnt(19) lgkmcnt(0)
	v_fmac_f32_e32 v17, v44, v58
	s_waitcnt vmcnt(18)
	v_fmac_f32_e32 v17, v42, v59
	s_waitcnt vmcnt(17)
	v_fmac_f32_e32 v17, v48, v60
	s_waitcnt vmcnt(16)
	v_fmac_f32_e32 v17, v46, v61
	ds_read_b128 v[58:61], v47 offset:32832
	v_pk_fma_f32 v[30:31], v[66:67], v[76:77], v[30:31] op_sel_hi:[0,1,1]
	v_pk_fma_f32 v[30:31], v[64:65], v[34:35], v[30:31] op_sel_hi:[0,1,1]
	v_pk_fma_f32 v[34:35], v[68:69], v[70:71], v[30:31] op_sel_hi:[0,1,1]
	v_add_u32_e32 v69, 0x103c, v47
	s_waitcnt vmcnt(15) lgkmcnt(0)
	v_fmac_f32_e32 v17, v52, v58
	s_waitcnt vmcnt(14)
	v_fmac_f32_e32 v17, v50, v59
	ds_read2_b32 v[10:11], v47 offset0:11 offset1:12
	ds_read2_b32 v[58:59], v8 offset1:1
	s_waitcnt vmcnt(13)
	v_fmac_f32_e32 v17, v56, v60
	s_waitcnt vmcnt(12)
	v_fmac_f32_e32 v17, v54, v61
	v_add_u32_e32 v76, 0x1044, v47
	s_waitcnt lgkmcnt(1)
	v_mov_b32_e32 v60, v10
	s_waitcnt lgkmcnt(0)
	v_mov_b32_e32 v61, v58
	v_pk_fma_f32 v[4:5], v[38:39], v[60:61], v[4:5] op_sel_hi:[0,1,1]
	v_mov_b32_e32 v58, v11
	v_pk_fma_f32 v[4:5], v[44:45], v[58:59], v[4:5] op_sel_hi:[0,1,1]
	ds_read2_b32 v[10:11], v47 offset0:13 offset1:14
	ds_read2_b32 v[58:59], v55 offset1:1
	v_mov_b32_e32 v30, v86
	v_mov_b32_e32 v31, v90
	v_add_u32_e32 v64, 0x3034, v47
	s_waitcnt lgkmcnt(1)
	v_mov_b32_e32 v60, v10
	s_waitcnt lgkmcnt(0)
	v_mov_b32_e32 v61, v58
	v_pk_fma_f32 v[4:5], v[42:43], v[60:61], v[4:5] op_sel_hi:[0,1,1]
	v_mov_b32_e32 v58, v11
	v_pk_fma_f32 v[4:5], v[48:49], v[58:59], v[4:5] op_sel_hi:[0,1,1]
	ds_read2_b32 v[10:11], v47 offset0:15 offset1:16
	ds_read2_b32 v[58:59], v69 offset1:1
	v_add_u32_e32 v70, 0x203c, v47
	v_add_u32_e32 v71, 0x303c, v47
	v_add_u32_e32 v77, 0x2044, v47
	s_waitcnt lgkmcnt(1)
	v_mov_b32_e32 v60, v10
	s_waitcnt lgkmcnt(0)
	v_mov_b32_e32 v61, v58
	v_pk_fma_f32 v[4:5], v[46:47], v[60:61], v[4:5] op_sel_hi:[0,1,1]
	v_mov_b32_e32 v58, v11
	v_pk_fma_f32 v[4:5], v[52:53], v[58:59], v[4:5] op_sel_hi:[0,1,1]
	ds_read2_b32 v[10:11], v47 offset0:17 offset1:18
	ds_read2_b32 v[58:59], v76 offset1:1
	v_add_u32_e32 v85, 0x304c, v47
	v_mov_b32_e32 v12, v94
	v_mov_b32_e32 v13, v98
	s_waitcnt lgkmcnt(1)
	v_mov_b32_e32 v60, v10
	s_waitcnt lgkmcnt(0)
	v_mov_b32_e32 v61, v58
	v_pk_fma_f32 v[4:5], v[50:51], v[60:61], v[4:5] op_sel_hi:[0,1,1]
	v_mov_b32_e32 v58, v11
	v_pk_fma_f32 v[4:5], v[56:57], v[58:59], v[4:5] op_sel_hi:[0,1,1]
	ds_read2_b32 v[10:11], v47 offset0:19 offset1:20
	ds_read2_b32 v[58:59], v83 offset1:1
	v_add_u32_e32 v65, 0x4034, v47
	v_add_u32_e32 v66, 0x5034, v47
	v_mov_b32_e32 v3, v72
	s_waitcnt lgkmcnt(1)
	v_mov_b32_e32 v60, v10
	s_waitcnt lgkmcnt(0)
	v_mov_b32_e32 v61, v58
	v_pk_fma_f32 v[4:5], v[54:55], v[60:61], v[4:5] op_sel_hi:[0,1,1]
	v_mov_b32_e32 v58, v11
	s_waitcnt vmcnt(11)
	v_pk_fma_f32 v[10:11], v[36:37], v[58:59], v[4:5] op_sel_hi:[0,1,1]
	v_pk_fma_f32 v[4:5], v[40:41], v[30:31], v[6:7] op_sel_hi:[0,1,1]
	ds_read2_b32 v[6:7], v37 offset1:1
	ds_read2_b32 v[30:31], v39 offset1:1
	v_add_u32_e32 v72, 0x403c, v47
	v_add_u32_e32 v73, 0x503c, v47
	v_add_u32_e32 v79, 0x4044, v47
	s_waitcnt lgkmcnt(1)
	v_mov_b32_e32 v58, v6
	s_waitcnt lgkmcnt(0)
	v_mov_b32_e32 v59, v30
	v_pk_fma_f32 v[4:5], v[38:39], v[58:59], v[4:5] op_sel_hi:[0,1,1]
	v_mov_b32_e32 v30, v7
	v_pk_fma_f32 v[4:5], v[44:45], v[30:31], v[4:5] op_sel_hi:[0,1,1]
	ds_read2_b32 v[6:7], v57 offset1:1
	ds_read2_b32 v[30:31], v64 offset1:1
	v_add_u32_e32 v80, 0x5044, v47
	v_add_u32_e32 v86, 0x404c, v47
	v_pk_fma_f32 v[2:3], v[40:41], v[2:3], v[34:35] op_sel_hi:[0,1,1]
	s_waitcnt lgkmcnt(1)
	v_mov_b32_e32 v58, v6
	s_waitcnt lgkmcnt(0)
	v_mov_b32_e32 v59, v30
	v_pk_fma_f32 v[4:5], v[42:43], v[58:59], v[4:5] op_sel_hi:[0,1,1]
	v_mov_b32_e32 v30, v7
	v_pk_fma_f32 v[4:5], v[48:49], v[30:31], v[4:5] op_sel_hi:[0,1,1]
	ds_read2_b32 v[6:7], v70 offset1:1
	ds_read2_b32 v[30:31], v71 offset1:1
	v_add_u32_e32 v67, 0x6034, v47
	v_add_u32_e32 v68, 0x7034, v47
	v_add_u32_e32 v74, 0x603c, v47
	s_waitcnt lgkmcnt(1)
	v_mov_b32_e32 v58, v6
	s_waitcnt lgkmcnt(0)
	v_mov_b32_e32 v59, v30
	v_pk_fma_f32 v[4:5], v[46:47], v[58:59], v[4:5] op_sel_hi:[0,1,1]
	v_mov_b32_e32 v30, v7
	v_pk_fma_f32 v[4:5], v[52:53], v[30:31], v[4:5] op_sel_hi:[0,1,1]
	ds_read2_b32 v[6:7], v77 offset1:1
	ds_read2_b32 v[30:31], v78 offset1:1
	v_add_u32_e32 v75, 0x703c, v47
	v_add_u32_e32 v81, 0x6044, v47
	v_add_u32_e32 v82, 0x7044, v47
	s_waitcnt lgkmcnt(1)
	v_mov_b32_e32 v58, v6
	s_waitcnt lgkmcnt(0)
	v_mov_b32_e32 v59, v30
	v_pk_fma_f32 v[4:5], v[50:51], v[58:59], v[4:5] op_sel_hi:[0,1,1]
	v_mov_b32_e32 v30, v7
	v_pk_fma_f32 v[4:5], v[56:57], v[30:31], v[4:5] op_sel_hi:[0,1,1]
	ds_read2_b32 v[6:7], v84 offset1:1
	ds_read2_b32 v[30:31], v85 offset1:1
	v_add_u32_e32 v60, 0x3068, v47
	v_add_u32_e32 v61, 0x4068, v47
	v_add_u32_e32 v62, 0x5068, v47
	s_waitcnt lgkmcnt(1)
	v_mov_b32_e32 v58, v6
	s_waitcnt lgkmcnt(0)
	v_mov_b32_e32 v59, v30
	v_pk_fma_f32 v[4:5], v[54:55], v[58:59], v[4:5] op_sel_hi:[0,1,1]
	v_mov_b32_e32 v30, v7
	v_pk_fma_f32 v[30:31], v[36:37], v[30:31], v[4:5] op_sel_hi:[0,1,1]
	v_pk_fma_f32 v[4:5], v[40:41], v[12:13], v[32:33] op_sel_hi:[0,1,1]
	ds_read2_b32 v[6:7], v41 offset1:1
	ds_read2_b32 v[12:13], v49 offset1:1
	v_add_u32_e32 v59, 0x2068, v47
	v_add_u32_e32 v58, 0x7058, v47
	v_add_u32_e32 v63, 0x6068, v47
	s_waitcnt lgkmcnt(1)
	v_mov_b32_e32 v32, v6
	s_waitcnt lgkmcnt(0)
	v_mov_b32_e32 v33, v12
	v_pk_fma_f32 v[4:5], v[38:39], v[32:33], v[4:5] op_sel_hi:[0,1,1]
	v_mov_b32_e32 v12, v7
	v_pk_fma_f32 v[4:5], v[44:45], v[12:13], v[4:5] op_sel_hi:[0,1,1]
	ds_read2_b32 v[6:7], v65 offset1:1
	ds_read2_b32 v[12:13], v66 offset1:1
	v_add_u32_e32 v64, 0x7068, v47
	s_waitcnt lgkmcnt(1)
	v_mov_b32_e32 v32, v6
	s_waitcnt lgkmcnt(0)
	v_mov_b32_e32 v33, v12
	v_pk_fma_f32 v[4:5], v[42:43], v[32:33], v[4:5] op_sel_hi:[0,1,1]
	v_mov_b32_e32 v12, v7
	v_pk_fma_f32 v[4:5], v[48:49], v[12:13], v[4:5] op_sel_hi:[0,1,1]
	ds_read2_b32 v[6:7], v72 offset1:1
	ds_read2_b32 v[12:13], v73 offset1:1
	s_waitcnt lgkmcnt(1)
	v_mov_b32_e32 v32, v6
	s_waitcnt lgkmcnt(0)
	v_mov_b32_e32 v33, v12
	v_pk_fma_f32 v[4:5], v[46:47], v[32:33], v[4:5] op_sel_hi:[0,1,1]
	v_mov_b32_e32 v12, v7
	v_pk_fma_f32 v[4:5], v[52:53], v[12:13], v[4:5] op_sel_hi:[0,1,1]
	ds_read2_b32 v[6:7], v79 offset1:1
	ds_read2_b32 v[12:13], v80 offset1:1
	s_waitcnt lgkmcnt(1)
	v_mov_b32_e32 v32, v6
	s_waitcnt lgkmcnt(0)
	v_mov_b32_e32 v33, v12
	v_pk_fma_f32 v[4:5], v[50:51], v[32:33], v[4:5] op_sel_hi:[0,1,1]
	v_mov_b32_e32 v12, v7
	v_pk_fma_f32 v[4:5], v[56:57], v[12:13], v[4:5] op_sel_hi:[0,1,1]
	ds_read2_b32 v[6:7], v86 offset1:1
	ds_read2_b32 v[12:13], v87 offset1:1
	s_waitcnt lgkmcnt(1)
	v_mov_b32_e32 v32, v6
	s_waitcnt lgkmcnt(0)
	v_mov_b32_e32 v33, v12
	v_pk_fma_f32 v[4:5], v[54:55], v[32:33], v[4:5] op_sel_hi:[0,1,1]
	v_mov_b32_e32 v12, v7
	v_pk_fma_f32 v[32:33], v[36:37], v[12:13], v[4:5] op_sel_hi:[0,1,1]
	ds_read2_b32 v[4:5], v51 offset1:1
	ds_read2_b32 v[6:7], v53 offset1:1
	s_waitcnt lgkmcnt(1)
	v_mov_b32_e32 v12, v4
	s_waitcnt lgkmcnt(0)
	v_mov_b32_e32 v13, v6
	v_pk_fma_f32 v[2:3], v[38:39], v[12:13], v[2:3] op_sel_hi:[0,1,1]
	v_mov_b32_e32 v6, v5
	v_pk_fma_f32 v[2:3], v[44:45], v[6:7], v[2:3] op_sel_hi:[0,1,1]
	ds_read2_b32 v[4:5], v67 offset1:1
	ds_read2_b32 v[6:7], v68 offset1:1
	v_add_u32_e32 v44, 0x3058, v47
	s_waitcnt lgkmcnt(1)
	v_mov_b32_e32 v12, v4
	s_waitcnt lgkmcnt(0)
	v_mov_b32_e32 v13, v6
	v_pk_fma_f32 v[2:3], v[42:43], v[12:13], v[2:3] op_sel_hi:[0,1,1]
	v_mov_b32_e32 v6, v5
	v_pk_fma_f32 v[2:3], v[48:49], v[6:7], v[2:3] op_sel_hi:[0,1,1]
	ds_read2_b32 v[4:5], v74 offset1:1
	ds_read2_b32 v[6:7], v75 offset1:1
	v_add_u32_e32 v42, 0x2058, v47
	s_waitcnt lgkmcnt(1)
	v_mov_b32_e32 v12, v4
	s_waitcnt lgkmcnt(0)
	v_mov_b32_e32 v13, v6
	v_pk_fma_f32 v[2:3], v[46:47], v[12:13], v[2:3] op_sel_hi:[0,1,1]
	v_mov_b32_e32 v6, v5
	v_pk_fma_f32 v[2:3], v[52:53], v[6:7], v[2:3] op_sel_hi:[0,1,1]
	ds_read2_b32 v[4:5], v81 offset1:1
	ds_read2_b32 v[6:7], v82 offset1:1
	v_add_u32_e32 v46, 0x4058, v47
	s_waitcnt lgkmcnt(1)
	v_mov_b32_e32 v12, v4
	s_waitcnt lgkmcnt(0)
	v_mov_b32_e32 v13, v6
	v_pk_fma_f32 v[2:3], v[50:51], v[12:13], v[2:3] op_sel_hi:[0,1,1]
	v_mov_b32_e32 v6, v5
	v_pk_fma_f32 v[2:3], v[56:57], v[6:7], v[2:3] op_sel_hi:[0,1,1]
	ds_read2_b32 v[4:5], v88 offset1:1
	ds_read2_b32 v[6:7], v89 offset1:1
	v_add_u32_e32 v56, 0x5058, v47
	v_add_u32_e32 v57, 0x6058, v47
	s_waitcnt lgkmcnt(1)
	v_mov_b32_e32 v12, v4
	s_waitcnt lgkmcnt(0)
	v_mov_b32_e32 v13, v6
	v_pk_fma_f32 v[2:3], v[54:55], v[12:13], v[2:3] op_sel_hi:[0,1,1]
	v_mov_b32_e32 v6, v5
	v_pk_fma_f32 v[6:7], v[36:37], v[6:7], v[2:3] op_sel_hi:[0,1,1]
	ds_read_b32 v40, v47 offset:84
	ds_read_b32 v41, v47 offset:4180
	ds_read_b32 v38, v47 offset:8276
	ds_read_b32 v39, v47 offset:12372
	ds_read_b32 v34, v47 offset:16468
	ds_read_b32 v35, v47 offset:20564
	ds_read_b32 v12, v47 offset:24660
	ds_read_b32 v13, v47 offset:28756
	ds_read_b128 v[2:5], v47 offset:32848
	s_waitcnt vmcnt(10)
	v_mov_b32_e32 v37, v22
	s_waitcnt lgkmcnt(5)
	v_pk_fma_f32 v[30:31], v[22:23], v[38:39], v[30:31] op_sel_hi:[0,1,1]
	s_waitcnt lgkmcnt(1)
	v_pk_fma_f32 v[6:7], v[22:23], v[12:13], v[6:7] op_sel_hi:[0,1,1]
	s_waitcnt lgkmcnt(0)
	v_pk_mul_f32 v[2:3], v[36:37], v[2:3]
	v_add_u32_e32 v36, 0x1068, v47
	v_add_f32_e32 v2, v17, v2
	v_add_f32_e32 v8, v2, v3
	s_waitcnt vmcnt(8)
	v_pk_mul_f32 v[2:3], v[20:21], v[4:5]
	v_add_u32_e32 v17, 0x1058, v47
	v_add_f32_e32 v2, v8, v2
	v_add_f32_e32 v8, v2, v3
	ds_read_b128 v[2:5], v47 offset:32864
	s_waitcnt vmcnt(6) lgkmcnt(0)
	v_pk_mul_f32 v[2:3], v[24:25], v[2:3]
	s_nop 0
	v_add_f32_e32 v2, v8, v2
	v_add_f32_e32 v8, v2, v3
	s_waitcnt vmcnt(4)
	v_pk_mul_f32 v[2:3], v[26:27], v[4:5]
	s_nop 0
	v_add_f32_e32 v2, v8, v2
	v_add_f32_e32 v8, v2, v3
	ds_read_b128 v[2:5], v47 offset:32880
	ds_read2_b64 v[48:51], v47 offset0:11 offset1:12
	ds_read2_b64 v[52:55], v17 offset1:1
	s_waitcnt vmcnt(2) lgkmcnt(2)
	v_pk_mul_f32 v[2:3], v[28:29], v[2:3]
	s_nop 0
	v_add_f32_e32 v2, v8, v2
	v_add_f32_e32 v37, v2, v3
	v_pk_fma_f32 v[2:3], v[22:23], v[40:41], v[10:11] op_sel_hi:[0,1,1]
	s_waitcnt lgkmcnt(1)
	v_mov_b32_e32 v10, v48
	s_waitcnt lgkmcnt(0)
	v_mov_b32_e32 v11, v52
	v_pk_fma_f32 v[10:11], v[20:21], v[10:11], v[2:3] op_sel_hi:[0,1,1]
	v_mov_b32_e32 v2, v21
	v_mov_b32_e32 v52, v49
	v_pk_fma_f32 v[10:11], v[2:3], v[52:53], v[10:11] op_sel_hi:[0,1,1]
	v_mov_b32_e32 v40, v50
	v_mov_b32_e32 v41, v54
	v_pk_fma_f32 v[10:11], v[24:25], v[40:41], v[10:11] op_sel_hi:[0,1,1]
	v_mov_b32_e32 v8, v25
	v_mov_b32_e32 v54, v51
	v_pk_fma_f32 v[10:11], v[8:9], v[54:55], v[10:11] op_sel_hi:[0,1,1]
	ds_read2_b64 v[48:51], v47 offset0:13 offset1:14
	ds_read2_b64 v[52:55], v36 offset1:1
	v_mov_b32_e32 v36, v27
	s_waitcnt lgkmcnt(1)
	v_mov_b32_e32 v40, v48
	s_waitcnt lgkmcnt(0)
	v_mov_b32_e32 v41, v52
	v_pk_fma_f32 v[10:11], v[26:27], v[40:41], v[10:11] op_sel_hi:[0,1,1]
	v_mov_b32_e32 v52, v49
	v_mov_b32_e32 v40, v50
	v_mov_b32_e32 v41, v54
	v_mov_b32_e32 v54, v51
	ds_read_b64 v[48:49], v47 offset:120
	ds_read_b64 v[50:51], v47 offset:4216
	v_pk_fma_f32 v[10:11], v[36:37], v[52:53], v[10:11] op_sel_hi:[0,1,1]
	v_pk_fma_f32 v[10:11], v[28:29], v[40:41], v[10:11] op_sel_hi:[0,1,1]
	v_mov_b32_e32 v40, v29
	v_pk_fma_f32 v[10:11], v[40:41], v[54:55], v[10:11] op_sel_hi:[0,1,1]
	s_waitcnt lgkmcnt(1)
	v_mov_b32_e32 v52, v48
	s_waitcnt lgkmcnt(0)
	v_mov_b32_e32 v53, v50
	s_waitcnt vmcnt(1)
	v_pk_fma_f32 v[10:11], v[16:17], v[52:53], v[10:11] op_sel_hi:[0,1,1]
	v_mov_b32_e32 v50, v49
	s_waitcnt vmcnt(0)
	v_pk_fma_f32 v[10:11], v[18:19], v[50:51], v[10:11] op_sel_hi:[0,1,1]
	ds_read2_b64 v[48:51], v42 offset1:1
	ds_read2_b64 v[52:55], v44 offset1:1
	s_waitcnt lgkmcnt(1)
	v_mov_b32_e32 v38, v48
	s_waitcnt lgkmcnt(0)
	v_mov_b32_e32 v39, v52
	v_pk_fma_f32 v[30:31], v[20:21], v[38:39], v[30:31] op_sel_hi:[0,1,1]
	v_mov_b32_e32 v52, v49
	v_pk_fma_f32 v[30:31], v[2:3], v[52:53], v[30:31] op_sel_hi:[0,1,1]
	v_mov_b32_e32 v38, v50
	v_mov_b32_e32 v39, v54
	v_pk_fma_f32 v[30:31], v[24:25], v[38:39], v[30:31] op_sel_hi:[0,1,1]
	v_mov_b32_e32 v54, v51
	v_pk_fma_f32 v[30:31], v[8:9], v[54:55], v[30:31] op_sel_hi:[0,1,1]
	ds_read2_b64 v[48:51], v59 offset1:1
	ds_read2_b64 v[52:55], v60 offset1:1
	s_waitcnt lgkmcnt(1)
	v_mov_b32_e32 v38, v48
	s_waitcnt lgkmcnt(0)
	v_mov_b32_e32 v39, v52
	v_pk_fma_f32 v[30:31], v[26:27], v[38:39], v[30:31] op_sel_hi:[0,1,1]
	v_mov_b32_e32 v52, v49
	v_pk_fma_f32 v[30:31], v[36:37], v[52:53], v[30:31] op_sel_hi:[0,1,1]
	v_mov_b32_e32 v38, v50
	v_mov_b32_e32 v39, v54
	v_pk_fma_f32 v[30:31], v[28:29], v[38:39], v[30:31] op_sel_hi:[0,1,1]
	ds_read_b64 v[38:39], v47 offset:8312
	ds_read_b64 v[48:49], v47 offset:12408
	v_mov_b32_e32 v54, v51
	v_pk_fma_f32 v[30:31], v[40:41], v[54:55], v[30:31] op_sel_hi:[0,1,1]
	s_waitcnt lgkmcnt(1)
	v_mov_b32_e32 v50, v38
	s_waitcnt lgkmcnt(0)
	v_mov_b32_e32 v51, v48
	v_pk_fma_f32 v[30:31], v[16:17], v[50:51], v[30:31] op_sel_hi:[0,1,1]
	v_mov_b32_e32 v48, v39
	v_pk_fma_f32 v[30:31], v[18:19], v[48:49], v[30:31] op_sel_hi:[0,1,1]
	v_pk_fma_f32 v[38:39], v[22:23], v[34:35], v[32:33] op_sel_hi:[0,1,1]
	ds_read2_b64 v[32:35], v46 offset1:1
	ds_read2_b64 v[48:51], v56 offset1:1
	s_waitcnt lgkmcnt(1)
	v_mov_b32_e32 v52, v32
	s_waitcnt lgkmcnt(0)
	v_mov_b32_e32 v53, v48
	v_pk_fma_f32 v[38:39], v[20:21], v[52:53], v[38:39] op_sel_hi:[0,1,1]
	v_mov_b32_e32 v48, v33
	v_pk_fma_f32 v[32:33], v[2:3], v[48:49], v[38:39] op_sel_hi:[0,1,1]
	v_mov_b32_e32 v38, v34
	v_mov_b32_e32 v39, v50
	v_pk_fma_f32 v[32:33], v[24:25], v[38:39], v[32:33] op_sel_hi:[0,1,1]
	v_mov_b32_e32 v50, v35
	v_pk_fma_f32 v[38:39], v[8:9], v[50:51], v[32:33] op_sel_hi:[0,1,1]
	ds_read2_b64 v[32:35], v61 offset1:1
	ds_read2_b64 v[48:51], v62 offset1:1
	s_waitcnt lgkmcnt(1)
	v_mov_b32_e32 v52, v32
	s_waitcnt lgkmcnt(0)
	v_mov_b32_e32 v53, v48
	v_pk_fma_f32 v[38:39], v[26:27], v[52:53], v[38:39] op_sel_hi:[0,1,1]
	v_mov_b32_e32 v48, v33
	v_pk_fma_f32 v[32:33], v[36:37], v[48:49], v[38:39] op_sel_hi:[0,1,1]
	v_mov_b32_e32 v38, v34
	v_mov_b32_e32 v39, v50
	v_pk_fma_f32 v[32:33], v[28:29], v[38:39], v[32:33] op_sel_hi:[0,1,1]
	v_mov_b32_e32 v50, v35
	ds_read_b64 v[34:35], v47 offset:16504
	ds_read_b64 v[38:39], v47 offset:20600
	v_pk_fma_f32 v[32:33], v[40:41], v[50:51], v[32:33] op_sel_hi:[0,1,1]
	s_waitcnt lgkmcnt(1)
	v_mov_b32_e32 v48, v34
	s_waitcnt lgkmcnt(0)
	v_mov_b32_e32 v49, v38
	v_pk_fma_f32 v[32:33], v[16:17], v[48:49], v[32:33] op_sel_hi:[0,1,1]
	ds_read2_b64 v[48:51], v57 offset1:1
	ds_read2_b64 v[52:55], v58 offset1:1
	v_mov_b32_e32 v38, v35
	v_pk_fma_f32 v[32:33], v[18:19], v[38:39], v[32:33] op_sel_hi:[0,1,1]
	s_waitcnt lgkmcnt(1)
	v_mov_b32_e32 v12, v48
	s_waitcnt lgkmcnt(0)
	v_mov_b32_e32 v13, v52
	v_pk_fma_f32 v[6:7], v[20:21], v[12:13], v[6:7] op_sel_hi:[0,1,1]
	v_mov_b32_e32 v52, v49
	v_pk_fma_f32 v[2:3], v[2:3], v[52:53], v[6:7] op_sel_hi:[0,1,1]
	v_mov_b32_e32 v6, v50
	v_mov_b32_e32 v7, v54
	v_pk_fma_f32 v[2:3], v[24:25], v[6:7], v[2:3] op_sel_hi:[0,1,1]
	v_mov_b32_e32 v54, v51
	v_pk_fma_f32 v[2:3], v[8:9], v[54:55], v[2:3] op_sel_hi:[0,1,1]
	ds_read2_b64 v[48:51], v63 offset1:1
	ds_read2_b64 v[52:55], v64 offset1:1
	s_waitcnt lgkmcnt(1)
	v_mov_b32_e32 v6, v48
	s_waitcnt lgkmcnt(0)
	v_mov_b32_e32 v7, v52
	v_pk_fma_f32 v[2:3], v[26:27], v[6:7], v[2:3] op_sel_hi:[0,1,1]
	v_mov_b32_e32 v52, v49
	v_pk_fma_f32 v[2:3], v[36:37], v[52:53], v[2:3] op_sel_hi:[0,1,1]
	v_mov_b32_e32 v6, v50
	v_mov_b32_e32 v7, v54
	v_pk_fma_f32 v[2:3], v[28:29], v[6:7], v[2:3] op_sel_hi:[0,1,1]
	ds_read_b64 v[6:7], v47 offset:24696
	ds_read_b64 v[12:13], v47 offset:28792
	v_mov_b32_e32 v54, v51
	v_pk_fma_f32 v[2:3], v[40:41], v[54:55], v[2:3] op_sel_hi:[0,1,1]
	v_add_u32_e32 v47, 0x80, v47
	s_waitcnt lgkmcnt(1)
	v_mov_b32_e32 v20, v6
	s_waitcnt lgkmcnt(0)
	v_mov_b32_e32 v21, v12
	v_pk_fma_f32 v[2:3], v[16:17], v[20:21], v[2:3] op_sel_hi:[0,1,1]
	v_mov_b32_e32 v12, v7
	v_mov_b32_e32 v17, v18
	v_pk_fma_f32 v[34:35], v[18:19], v[12:13], v[2:3] op_sel_hi:[0,1,1]
	v_pk_mul_f32 v[2:3], v[16:17], v[4:5]
	s_nop 0
	v_add_f32_e32 v2, v37, v2
	v_add_f32_e32 v17, v2, v3
	s_cbranch_scc0 .LBB0_81
	v_lshl_add_u32 v2, v23, 2, 0
	v_mad_u64_u32 v[4:5], s[28:29], v43, s35, v[2:3]
	v_cmp_gt_i32_e32 vcc, s45, v19
	ds_write2st64_b32 v4, v10, v11 offset0:144 offset1:145
	ds_write2st64_b32 v4, v30, v31 offset0:146 offset1:147
	ds_write2st64_b32 v4, v32, v33 offset0:148 offset1:149
	ds_write2st64_b32 v4, v34, v35 offset0:150 offset1:151
	ds_write_b32 v4, v17 offset:38912
	s_waitcnt lgkmcnt(0)
	s_barrier
	s_and_saveexec_b64 s[28:29], vcc
	s_cbranch_execz .LBB0_7
	s_mul_i32 s48, s47, 0x6000
	s_mul_hi_i32 s25, s47, 0x6000
	s_add_u32 s48, s12, s48
	s_addc_u32 s49, s13, s25
	s_mul_hi_i32 s25, s47, 0x36000
	s_mul_i32 s47, s47, 0x36000
	v_or_b32_e32 v4, s24, v23
	s_add_u32 s50, s74, s47
	v_ashrrev_i32_e32 v5, 31, v4
	s_addc_u32 s51, s75, s25
	v_lshlrev_b64 v[6:7], 2, v[4:5]
	v_lshl_add_u64 v[4:5], s[48:49], 0, v[6:7]
	v_lshl_add_u64 v[6:7], s[50:51], 0, v[6:7]
	s_mov_b64 s[24:25], 0
	s_branch .LBB0_86
.LBB0_84:
	global_load_dword v8, v[4:5], off nt

.LBB0_92:
	v_cmp_lt_i32_e32 vcc, s30, v2
	s_and_saveexec_b64 s[4:5], vcc
	s_xor_b64 s[4:5], exec, s[4:5]
	s_cbranch_execz .LBB0_102
	v_cmp_lt_u32_e32 vcc, s31, v2
	v_add_u32_e32 v4, 0x600, v16
	s_and_saveexec_b64 s[6:7], vcc
	s_xor_b64 s[6:7], exec, s[6:7]
	s_cbranch_execz .LBB0_99
	v_cmp_lt_u32_e32 vcc, s34, v2
	s_and_saveexec_b64 s[22:23], vcc
	s_xor_b64 s[22:23], exec, s[22:23]
	s_cbranch_execz .LBB0_96
	v_and_b32_e32 v51, 0x1ffc0, v42
	s_load_dwordx8 s[52:59], s[80:81], 0xd0
	v_and_b32_e32 v62, 0x3e0, v4
	v_or_b32_e32 v4, v51, v3
	v_lshlrev_b32_e32 v4, 10, v4
	v_or3_b32 v4, v4, v17, v62
	v_lshlrev_b32_e32 v4, 2, v4
	s_waitcnt lgkmcnt(0)
	v_lshl_add_u64 v[18:19], s[58:59], 0, v[4:5]
	v_add_co_u32_e32 v20, vcc, 0x2000, v18
	global_load_dword v4, v4, s[58:59]
	s_nop 0
	v_addc_co_u32_e32 v21, vcc, 0, v19, vcc
	v_add_co_u32_e32 v22, vcc, 0x4000, v18
	s_nop 1
	v_addc_co_u32_e32 v23, vcc, 0, v19, vcc
	v_add_co_u32_e32 v24, vcc, 0x6000, v18
	s_nop 1
	v_addc_co_u32_e32 v25, vcc, 0, v19, vcc
	v_add_co_u32_e32 v26, vcc, 0x8000, v18
	s_nop 1
	v_addc_co_u32_e32 v27, vcc, 0, v19, vcc
	v_add_co_u32_e32 v28, vcc, 0xa000, v18
	s_nop 1
	v_addc_co_u32_e32 v29, vcc, 0, v19, vcc
	v_add_co_u32_e32 v30, vcc, 0xc000, v18
	s_nop 1
	v_addc_co_u32_e32 v31, vcc, 0, v19, vcc
	v_add_co_u32_e32 v52, vcc, 0xe000, v18
	s_nop 1
	v_addc_co_u32_e32 v53, vcc, 0, v19, vcc
	v_add_co_u32_e32 v54, vcc, 0x10000, v18
	s_nop 1
	v_addc_co_u32_e32 v55, vcc, 0, v19, vcc
	global_load_dword v56, v[20:21], off nt
	global_load_dword v57, v[22:23], off nt
	global_load_dword v58, v[24:25], off nt
	global_load_dword v59, v[26:27], off nt
	global_load_dword v60, v[28:29], off nt
	global_load_dword v61, v[30:31], off nt
	global_load_dword v63, v[52:53], off nt
	global_load_dword v64, v[54:55], off nt
	v_add_co_u32_e32 v20, vcc, 0x12000, v18
	s_nop 1
	v_addc_co_u32_e32 v21, vcc, 0, v19, vcc
	v_add_co_u32_e32 v22, vcc, 0x14000, v18
	s_nop 1
	v_addc_co_u32_e32 v23, vcc, 0, v19, vcc
	v_add_co_u32_e32 v24, vcc, 0x16000, v18
	s_nop 1
	v_addc_co_u32_e32 v25, vcc, 0, v19, vcc
	v_add_co_u32_e32 v26, vcc, 0x18000, v18
	s_nop 1
	v_addc_co_u32_e32 v27, vcc, 0, v19, vcc
	v_add_co_u32_e32 v28, vcc, 0x1a000, v18
	s_nop 1
	v_addc_co_u32_e32 v29, vcc, 0, v19, vcc
	v_add_co_u32_e32 v30, vcc, 0x1c000, v18
	s_nop 1
	v_addc_co_u32_e32 v31, vcc, 0, v19, vcc
	v_add_co_u32_e32 v52, vcc, 0x1e000, v18
	s_nop 1
	v_addc_co_u32_e32 v53, vcc, 0, v19, vcc
	v_add_co_u32_e32 v54, vcc, 0x20000, v18
	s_nop 1
	v_addc_co_u32_e32 v55, vcc, 0, v19, vcc
	global_load_dword v65, v[20:21], off nt
	global_load_dword v66, v[22:23], off nt
	global_load_dword v67, v[24:25], off nt
	global_load_dword v68, v[26:27], off nt
	global_load_dword v69, v[28:29], off nt
	global_load_dword v70, v[30:31], off nt
	global_load_dword v71, v[52:53], off nt
	global_load_dword v72, v[54:55], off nt
	v_add_co_u32_e32 v20, vcc, 0x22000, v18
	s_nop 1
	v_addc_co_u32_e32 v21, vcc, 0, v19, vcc
	v_add_co_u32_e32 v22, vcc, 0x24000, v18
	s_nop 1
	v_addc_co_u32_e32 v23, vcc, 0, v19, vcc
	v_add_co_u32_e32 v24, vcc, 0x26000, v18
	s_nop 1
	v_addc_co_u32_e32 v25, vcc, 0, v19, vcc
	v_add_co_u32_e32 v26, vcc, 0x28000, v18
	s_nop 1
	v_addc_co_u32_e32 v27, vcc, 0, v19, vcc
	v_add_co_u32_e32 v28, vcc, 0x2a000, v18
	s_nop 1
	v_addc_co_u32_e32 v29, vcc, 0, v19, vcc
	v_add_co_u32_e32 v30, vcc, 0x2c000, v18
	s_nop 1
	v_addc_co_u32_e32 v31, vcc, 0, v19, vcc
	v_add_co_u32_e32 v52, vcc, 0x2e000, v18
	s_nop 1
	v_addc_co_u32_e32 v53, vcc, 0, v19, vcc
	v_add_co_u32_e32 v54, vcc, 0x30000, v18
	s_nop 1
	v_addc_co_u32_e32 v55, vcc, 0, v19, vcc
	global_load_dword v73, v[20:21], off nt
	global_load_dword v74, v[22:23], off nt
	global_load_dword v75, v[24:25], off nt
	global_load_dword v76, v[26:27], off nt
	global_load_dword v77, v[28:29], off nt
	global_load_dword v78, v[30:31], off nt
	s_nop 0
	global_load_dword v52, v[52:53], off nt
	s_nop 0
	global_load_dword v53, v[54:55], off nt
	v_add_co_u32_e32 v20, vcc, 0x32000, v18
	s_nop 1
	v_addc_co_u32_e32 v21, vcc, 0, v19, vcc
	v_add_co_u32_e32 v22, vcc, 0x34000, v18
	s_nop 1
	v_addc_co_u32_e32 v23, vcc, 0, v19, vcc
	v_add_co_u32_e32 v24, vcc, 0x36000, v18
	s_nop 1
	v_addc_co_u32_e32 v25, vcc, 0, v19, vcc
	v_add_co_u32_e32 v26, vcc, 0x38000, v18
	s_nop 1
	v_addc_co_u32_e32 v27, vcc, 0, v19, vcc
	v_add_co_u32_e32 v28, vcc, 0x3a000, v18
	s_nop 1
	v_addc_co_u32_e32 v29, vcc, 0, v19, vcc
	v_add_co_u32_e32 v30, vcc, 0x3c000, v18
	s_nop 1
	v_addc_co_u32_e32 v31, vcc, 0, v19, vcc
	v_add_co_u32_e32 v18, vcc, 0x3e000, v18
	s_nop 1
	v_addc_co_u32_e32 v19, vcc, 0, v19, vcc
	global_load_dword v20, v[20:21], off nt
	s_nop 0
	global_load_dword v21, v[22:23], off nt
	s_nop 0
	global_load_dword v22, v[24:25], off nt
	global_load_dword v23, v[26:27], off nt
	s_nop 0
	global_load_dword v24, v[28:29], off nt
	global_load_dword v25, v[30:31], off nt
	s_nop 0
	global_load_dword v18, v[18:19], off nt
	s_waitcnt vmcnt(30)
	ds_write2_b32 v32, v4, v56 offset1:66
	s_waitcnt vmcnt(28)
	ds_write2_b32 v32, v57, v58 offset0:132 offset1:198
	s_waitcnt vmcnt(26)
	ds_write2_b32 v43, v59, v60 offset0:8 offset1:74
	s_waitcnt vmcnt(24)
	ds_write2_b32 v43, v61, v63 offset0:140 offset1:206
	s_waitcnt vmcnt(22)
	ds_write2_b32 v44, v64, v65 offset0:16 offset1:82
	s_waitcnt vmcnt(20)
	ds_write2_b32 v44, v66, v67 offset0:148 offset1:214
	s_waitcnt vmcnt(18)
	ds_write2_b32 v46, v68, v69 offset0:24 offset1:90
	s_waitcnt vmcnt(16)
	ds_write2_b32 v46, v70, v71 offset0:156 offset1:222
	s_waitcnt vmcnt(14)
	ds_write2_b32 v47, v72, v73 offset0:32 offset1:98
	s_waitcnt vmcnt(12)
	ds_write2_b32 v47, v74, v75 offset0:164 offset1:230
	s_waitcnt vmcnt(10)
	ds_write2_b32 v48, v76, v77 offset0:40 offset1:106
	s_waitcnt vmcnt(8)
	ds_write2_b32 v48, v78, v52 offset0:172 offset1:238
	s_waitcnt vmcnt(6)
	ds_write2_b32 v49, v53, v20 offset0:48 offset1:114
	s_waitcnt vmcnt(4)
	ds_write2_b32 v49, v21, v22 offset0:180 offset1:246
	s_waitcnt vmcnt(2)
	ds_write2_b32 v50, v23, v24 offset0:56 offset1:122
	s_waitcnt vmcnt(0)
	ds_write2_b32 v50, v25, v18 offset0:188 offset1:254
	s_waitcnt lgkmcnt(0)
	ds_read2_b32 v[22:23], v34 offset0:33 offset1:41
	ds_read2_b32 v[24:25], v34 offset1:8
	ds_read2_b32 v[26:27], v34 offset0:66 offset1:74
	ds_read2_b32 v[28:29], v34 offset0:99 offset1:107
	ds_read2_b32 v[30:31], v34 offset0:132 offset1:140
	ds_read2_b32 v[52:53], v34 offset0:165 offset1:173
	ds_read2_b32 v[54:55], v34 offset0:198 offset1:206
	ds_read2_b32 v[56:57], v34 offset0:231 offset1:239
	v_lshlrev_b32_e32 v4, 1, v51
	v_lshl_add_u64 v[58:59], v[6:7], 0, v[4:5]
	v_or_b32_e32 v4, v62, v33
	v_lshlrev_b32_e32 v4, 13, v4
	s_waitcnt lgkmcnt(6)
	v_cvt_pk_bf16_f32 v18, v24, v22
	s_waitcnt lgkmcnt(4)
	v_cvt_pk_bf16_f32 v19, v26, v28
	s_waitcnt lgkmcnt(2)
	v_cvt_pk_bf16_f32 v20, v30, v52
	s_waitcnt lgkmcnt(0)
	v_cvt_pk_bf16_f32 v21, v54, v56
	v_lshl_add_u64 v[60:61], v[58:59], 0, v[4:5]
	global_store_dwordx4 v[60:61], v[18:21], off
	v_or_b32_e32 v4, v62, v35
	v_lshlrev_b32_e32 v4, 13, v4
	v_cvt_pk_bf16_f32 v18, v25, v23
	v_cvt_pk_bf16_f32 v19, v27, v29
	v_cvt_pk_bf16_f32 v20, v31, v53
	v_cvt_pk_bf16_f32 v21, v55, v57
	ds_read2_b32 v[24:25], v34 offset0:49 offset1:57
	ds_read2_b32 v[26:27], v34 offset0:16 offset1:24
	ds_read2_b32 v[28:29], v34 offset0:82 offset1:90
	ds_read2_b32 v[30:31], v34 offset0:115 offset1:123
	ds_read2_b32 v[52:53], v34 offset0:148 offset1:156
	ds_read2_b32 v[54:55], v34 offset0:181 offset1:189
	ds_read2_b32 v[56:57], v34 offset0:214 offset1:222
	ds_read2_b32 v[60:61], v34 offset0:247 offset1:255
	v_lshl_add_u64 v[22:23], v[58:59], 0, v[4:5]
	v_or_b32_e32 v4, v62, v36
	v_lshlrev_b32_e32 v4, 13, v4
	global_store_dwordx4 v[22:23], v[18:21], off
	v_lshl_add_u64 v[22:23], v[58:59], 0, v[4:5]
	v_or_b32_e32 v4, v62, v37
	s_waitcnt lgkmcnt(6)
	v_cvt_pk_bf16_f32 v18, v26, v24
	s_waitcnt lgkmcnt(4)
	v_cvt_pk_bf16_f32 v19, v28, v30
	s_waitcnt lgkmcnt(2)
	v_cvt_pk_bf16_f32 v20, v52, v54
	s_waitcnt lgkmcnt(0)
	v_cvt_pk_bf16_f32 v21, v56, v60
	v_lshlrev_b32_e32 v4, 13, v4
	global_store_dwordx4 v[22:23], v[18:21], off
	v_lshl_add_u64 v[22:23], v[58:59], 0, v[4:5]
	s_nop 0
	v_cvt_pk_bf16_f32 v18, v27, v25
	v_cvt_pk_bf16_f32 v19, v29, v31
	v_cvt_pk_bf16_f32 v20, v53, v55
	v_cvt_pk_bf16_f32 v21, v57, v61
	global_store_dwordx4 v[22:23], v[18:21], off
	s_waitcnt lgkmcnt(0)
.LBB0_96:
	s_andn2_saveexec_b64 s[22:23], s[22:23]
	s_cbranch_execz .LBB0_98
	v_add_u32_e32 v18, 0xf880, v2
	v_lshrrev_b32_e32 v18, 1, v18
	v_and_b32_e32 v51, 0x7fc0, v18
	s_load_dwordx8 s[52:59], s[80:81], 0xd0
	v_and_b32_e32 v62, 0xfe0, v4
	v_or_b32_e32 v4, v51, v3
	v_lshlrev_b32_e32 v4, 12, v4
	v_or3_b32 v4, v4, v17, v62
	v_lshlrev_b32_e32 v4, 2, v4
	s_waitcnt lgkmcnt(0)
	v_lshl_add_u64 v[18:19], s[56:57], 0, v[4:5]
	v_add_co_u32_e32 v20, vcc, 0x8000, v18
	global_load_dword v4, v4, s[56:57]
	s_nop 0
	v_addc_co_u32_e32 v21, vcc, 0, v19, vcc
	v_add_co_u32_e32 v22, vcc, 0x10000, v18
	s_nop 1
	v_addc_co_u32_e32 v23, vcc, 0, v19, vcc
	v_add_co_u32_e32 v24, vcc, 0x18000, v18
	s_nop 1
	v_addc_co_u32_e32 v25, vcc, 0, v19, vcc
	v_add_co_u32_e32 v26, vcc, 0x20000, v18
	s_nop 1
	v_addc_co_u32_e32 v27, vcc, 0, v19, vcc
	v_add_co_u32_e32 v28, vcc, 0x28000, v18
	s_nop 1
	v_addc_co_u32_e32 v29, vcc, 0, v19, vcc
	v_add_co_u32_e32 v30, vcc, 0x30000, v18
	s_nop 1
	v_addc_co_u32_e32 v31, vcc, 0, v19, vcc
	v_add_co_u32_e32 v52, vcc, 0x38000, v18
	s_nop 1
	v_addc_co_u32_e32 v53, vcc, 0, v19, vcc
	v_add_co_u32_e32 v54, vcc, 0x40000, v18
	s_nop 1
	v_addc_co_u32_e32 v55, vcc, 0, v19, vcc
	global_load_dword v56, v[20:21], off nt
	global_load_dword v57, v[22:23], off nt
	global_load_dword v58, v[24:25], off nt
	global_load_dword v59, v[26:27], off nt
	global_load_dword v60, v[28:29], off nt
	global_load_dword v61, v[30:31], off nt
	global_load_dword v63, v[52:53], off nt
	global_load_dword v64, v[54:55], off nt
	v_add_co_u32_e32 v20, vcc, 0x48000, v18
	s_nop 1
	v_addc_co_u32_e32 v21, vcc, 0, v19, vcc
	v_add_co_u32_e32 v22, vcc, 0x50000, v18
	s_nop 1
	v_addc_co_u32_e32 v23, vcc, 0, v19, vcc
	v_add_co_u32_e32 v24, vcc, 0x58000, v18
	s_nop 1
	v_addc_co_u32_e32 v25, vcc, 0, v19, vcc
	v_add_co_u32_e32 v26, vcc, 0x60000, v18
	s_nop 1
	v_addc_co_u32_e32 v27, vcc, 0, v19, vcc
	v_add_co_u32_e32 v28, vcc, 0x68000, v18
	s_nop 1
	v_addc_co_u32_e32 v29, vcc, 0, v19, vcc
	v_add_co_u32_e32 v30, vcc, 0x70000, v18
	s_nop 1
	v_addc_co_u32_e32 v31, vcc, 0, v19, vcc
	v_add_co_u32_e32 v52, vcc, 0x78000, v18
	s_nop 1
	v_addc_co_u32_e32 v53, vcc, 0, v19, vcc
	v_add_co_u32_e32 v54, vcc, 0x80000, v18
	s_nop 1
	v_addc_co_u32_e32 v55, vcc, 0, v19, vcc
	global_load_dword v65, v[20:21], off nt
	global_load_dword v66, v[22:23], off nt
	global_load_dword v67, v[24:25], off nt
	global_load_dword v68, v[26:27], off nt
	global_load_dword v69, v[28:29], off nt
	global_load_dword v70, v[30:31], off nt
	global_load_dword v71, v[52:53], off nt
	global_load_dword v72, v[54:55], off nt
	v_add_co_u32_e32 v20, vcc, 0x88000, v18
	s_nop 1
	v_addc_co_u32_e32 v21, vcc, 0, v19, vcc
	v_add_co_u32_e32 v22, vcc, 0x90000, v18
	s_nop 1
	v_addc_co_u32_e32 v23, vcc, 0, v19, vcc
	v_add_co_u32_e32 v24, vcc, 0x98000, v18
	s_nop 1
	v_addc_co_u32_e32 v25, vcc, 0, v19, vcc
	v_add_co_u32_e32 v26, vcc, 0xa0000, v18
	s_nop 1
	v_addc_co_u32_e32 v27, vcc, 0, v19, vcc
	v_add_co_u32_e32 v28, vcc, 0xa8000, v18
	s_nop 1
	v_addc_co_u32_e32 v29, vcc, 0, v19, vcc
	v_add_co_u32_e32 v30, vcc, 0xb0000, v18
	s_nop 1
	v_addc_co_u32_e32 v31, vcc, 0, v19, vcc
	v_add_co_u32_e32 v52, vcc, 0xb8000, v18
	s_nop 1
	v_addc_co_u32_e32 v53, vcc, 0, v19, vcc
	v_add_co_u32_e32 v54, vcc, 0xc0000, v18
	s_nop 1
	v_addc_co_u32_e32 v55, vcc, 0, v19, vcc
	global_load_dword v73, v[20:21], off nt
	global_load_dword v74, v[22:23], off nt
	global_load_dword v75, v[24:25], off nt
	global_load_dword v76, v[26:27], off nt
	global_load_dword v77, v[28:29], off nt
	global_load_dword v78, v[30:31], off nt
	s_nop 0
	global_load_dword v52, v[52:53], off nt
	s_nop 0
	global_load_dword v53, v[54:55], off nt
	v_add_co_u32_e32 v20, vcc, 0xc8000, v18
	s_nop 1
	v_addc_co_u32_e32 v21, vcc, 0, v19, vcc
	v_add_co_u32_e32 v22, vcc, 0xd0000, v18
	s_nop 1
	v_addc_co_u32_e32 v23, vcc, 0, v19, vcc
	v_add_co_u32_e32 v24, vcc, 0xd8000, v18
	s_nop 1
	v_addc_co_u32_e32 v25, vcc, 0, v19, vcc
	v_add_co_u32_e32 v26, vcc, 0xe0000, v18
	s_nop 1
	v_addc_co_u32_e32 v27, vcc, 0, v19, vcc
	v_add_co_u32_e32 v28, vcc, 0xe8000, v18
	s_nop 1
	v_addc_co_u32_e32 v29, vcc, 0, v19, vcc
	v_add_co_u32_e32 v30, vcc, 0xf0000, v18
	s_nop 1
	v_addc_co_u32_e32 v31, vcc, 0, v19, vcc
	v_add_co_u32_e32 v18, vcc, 0xf8000, v18
	s_nop 1
	v_addc_co_u32_e32 v19, vcc, 0, v19, vcc
	global_load_dword v20, v[20:21], off nt
	s_nop 0
	global_load_dword v21, v[22:23], off nt
	s_nop 0
	global_load_dword v22, v[24:25], off nt
	global_load_dword v23, v[26:27], off nt
	s_nop 0
	global_load_dword v24, v[28:29], off nt
	global_load_dword v25, v[30:31], off nt
	s_nop 0
	global_load_dword v18, v[18:19], off nt
	s_waitcnt vmcnt(30)
	ds_write2_b32 v32, v4, v56 offset1:66
	s_waitcnt vmcnt(28)
	ds_write2_b32 v32, v57, v58 offset0:132 offset1:198
	s_waitcnt vmcnt(26)
	ds_write2_b32 v43, v59, v60 offset0:8 offset1:74
	s_waitcnt vmcnt(24)
	ds_write2_b32 v43, v61, v63 offset0:140 offset1:206
	s_waitcnt vmcnt(22)
	ds_write2_b32 v44, v64, v65 offset0:16 offset1:82
	s_waitcnt vmcnt(20)
	ds_write2_b32 v44, v66, v67 offset0:148 offset1:214
	s_waitcnt vmcnt(18)
	ds_write2_b32 v46, v68, v69 offset0:24 offset1:90
	s_waitcnt vmcnt(16)
	ds_write2_b32 v46, v70, v71 offset0:156 offset1:222
	s_waitcnt vmcnt(14)
	ds_write2_b32 v47, v72, v73 offset0:32 offset1:98
	s_waitcnt vmcnt(12)
	ds_write2_b32 v47, v74, v75 offset0:164 offset1:230
	s_waitcnt vmcnt(10)
	ds_write2_b32 v48, v76, v77 offset0:40 offset1:106
	s_waitcnt vmcnt(8)
	ds_write2_b32 v48, v78, v52 offset0:172 offset1:238
	s_waitcnt vmcnt(6)
	ds_write2_b32 v49, v53, v20 offset0:48 offset1:114
	s_waitcnt vmcnt(4)
	ds_write2_b32 v49, v21, v22 offset0:180 offset1:246
	s_waitcnt vmcnt(2)
	ds_write2_b32 v50, v23, v24 offset0:56 offset1:122
	s_waitcnt vmcnt(0)
	ds_write2_b32 v50, v25, v18 offset0:188 offset1:254
	s_waitcnt lgkmcnt(0)
	ds_read2_b32 v[22:23], v34 offset0:33 offset1:41
	ds_read2_b32 v[24:25], v34 offset1:8
	ds_read2_b32 v[26:27], v34 offset0:66 offset1:74
	ds_read2_b32 v[28:29], v34 offset0:99 offset1:107
	ds_read2_b32 v[30:31], v34 offset0:132 offset1:140
	ds_read2_b32 v[52:53], v34 offset0:165 offset1:173
	ds_read2_b32 v[54:55], v34 offset0:198 offset1:206
	ds_read2_b32 v[56:57], v34 offset0:231 offset1:239
	v_lshlrev_b32_e32 v4, 1, v51
	v_lshl_add_u64 v[58:59], v[8:9], 0, v[4:5]
	v_or_b32_e32 v4, v62, v33
	v_lshlrev_b32_e32 v4, 11, v4
	s_waitcnt lgkmcnt(6)
	v_cvt_pk_bf16_f32 v18, v24, v22
	s_waitcnt lgkmcnt(4)
	v_cvt_pk_bf16_f32 v19, v26, v28
	s_waitcnt lgkmcnt(2)
	v_cvt_pk_bf16_f32 v20, v30, v52
	s_waitcnt lgkmcnt(0)
	v_cvt_pk_bf16_f32 v21, v54, v56
	v_lshl_add_u64 v[60:61], v[58:59], 0, v[4:5]
	global_store_dwordx4 v[60:61], v[18:21], off
	v_or_b32_e32 v4, v62, v35
	v_lshlrev_b32_e32 v4, 11, v4
	v_cvt_pk_bf16_f32 v18, v25, v23
	v_cvt_pk_bf16_f32 v19, v27, v29
	v_cvt_pk_bf16_f32 v20, v31, v53
	v_cvt_pk_bf16_f32 v21, v55, v57
	ds_read2_b32 v[24:25], v34 offset0:49 offset1:57
	ds_read2_b32 v[26:27], v34 offset0:16 offset1:24
	ds_read2_b32 v[28:29], v34 offset0:82 offset1:90
	ds_read2_b32 v[30:31], v34 offset0:115 offset1:123
	ds_read2_b32 v[52:53], v34 offset0:148 offset1:156
	ds_read2_b32 v[54:55], v34 offset0:181 offset1:189
	ds_read2_b32 v[56:57], v34 offset0:214 offset1:222
	ds_read2_b32 v[60:61], v34 offset0:247 offset1:255
	v_lshl_add_u64 v[22:23], v[58:59], 0, v[4:5]
	v_or_b32_e32 v4, v62, v36
	v_lshlrev_b32_e32 v4, 11, v4
	global_store_dwordx4 v[22:23], v[18:21], off
	v_lshl_add_u64 v[22:23], v[58:59], 0, v[4:5]
	v_or_b32_e32 v4, v62, v37
	s_waitcnt lgkmcnt(6)
	v_cvt_pk_bf16_f32 v18, v26, v24
	s_waitcnt lgkmcnt(4)
	v_cvt_pk_bf16_f32 v19, v28, v30
	s_waitcnt lgkmcnt(2)
	v_cvt_pk_bf16_f32 v20, v52, v54
	s_waitcnt lgkmcnt(0)
	v_cvt_pk_bf16_f32 v21, v56, v60
	v_lshlrev_b32_e32 v4, 11, v4
	global_store_dwordx4 v[22:23], v[18:21], off
	v_lshl_add_u64 v[22:23], v[58:59], 0, v[4:5]
	s_nop 0
	v_cvt_pk_bf16_f32 v18, v27, v25
	v_cvt_pk_bf16_f32 v19, v29, v31
	v_cvt_pk_bf16_f32 v20, v53, v55
	v_cvt_pk_bf16_f32 v21, v57, v61
	global_store_dwordx4 v[22:23], v[18:21], off
	s_waitcnt lgkmcnt(0)

.LBB0_99:
	s_andn2_saveexec_b64 s[6:7], s[6:7]
	s_cbranch_execz .LBB0_101
	v_add_u32_e32 v18, 0x1400, v42
	v_and_b32_e32 v51, 0x1ffc0, v18
	s_load_dwordx8 s[52:59], s[80:81], 0xd0
	v_and_b32_e32 v62, 0x3e0, v4
	v_or_b32_e32 v4, v51, v3
	v_lshlrev_b32_e32 v4, 10, v4
	v_or3_b32 v4, v4, v17, v62
	v_lshlrev_b32_e32 v4, 2, v4
	s_waitcnt lgkmcnt(0)
	v_lshl_add_u64 v[18:19], s[52:53], 0, v[4:5]
	v_add_co_u32_e32 v20, vcc, 0x2000, v18
	global_load_dword v4, v4, s[52:53]
	s_nop 0
	v_addc_co_u32_e32 v21, vcc, 0, v19, vcc
	v_add_co_u32_e32 v22, vcc, 0x4000, v18
	s_nop 1
	v_addc_co_u32_e32 v23, vcc, 0, v19, vcc
	v_add_co_u32_e32 v24, vcc, 0x6000, v18
	s_nop 1
	v_addc_co_u32_e32 v25, vcc, 0, v19, vcc
	v_add_co_u32_e32 v26, vcc, 0x8000, v18
	s_nop 1
	v_addc_co_u32_e32 v27, vcc, 0, v19, vcc
	v_add_co_u32_e32 v28, vcc, 0xa000, v18
	s_nop 1
	v_addc_co_u32_e32 v29, vcc, 0, v19, vcc
	v_add_co_u32_e32 v30, vcc, 0xc000, v18
	s_nop 1
	v_addc_co_u32_e32 v31, vcc, 0, v19, vcc
	v_add_co_u32_e32 v52, vcc, 0xe000, v18
	s_nop 1
	v_addc_co_u32_e32 v53, vcc, 0, v19, vcc
	v_add_co_u32_e32 v54, vcc, 0x10000, v18
	s_nop 1
	v_addc_co_u32_e32 v55, vcc, 0, v19, vcc
	global_load_dword v56, v[20:21], off nt
	global_load_dword v57, v[22:23], off nt
	global_load_dword v58, v[24:25], off nt
	global_load_dword v59, v[26:27], off nt
	global_load_dword v60, v[28:29], off nt
	global_load_dword v61, v[30:31], off nt
	global_load_dword v63, v[52:53], off nt
	global_load_dword v64, v[54:55], off nt
	v_add_co_u32_e32 v20, vcc, 0x12000, v18
	s_nop 1
	v_addc_co_u32_e32 v21, vcc, 0, v19, vcc
	v_add_co_u32_e32 v22, vcc, 0x14000, v18
	s_nop 1
	v_addc_co_u32_e32 v23, vcc, 0, v19, vcc
	v_add_co_u32_e32 v24, vcc, 0x16000, v18
	s_nop 1
	v_addc_co_u32_e32 v25, vcc, 0, v19, vcc
	v_add_co_u32_e32 v26, vcc, 0x18000, v18
	s_nop 1
	v_addc_co_u32_e32 v27, vcc, 0, v19, vcc
	v_add_co_u32_e32 v28, vcc, 0x1a000, v18
	s_nop 1
	v_addc_co_u32_e32 v29, vcc, 0, v19, vcc
	v_add_co_u32_e32 v30, vcc, 0x1c000, v18
	s_nop 1
	v_addc_co_u32_e32 v31, vcc, 0, v19, vcc
	v_add_co_u32_e32 v52, vcc, 0x1e000, v18
	s_nop 1
	v_addc_co_u32_e32 v53, vcc, 0, v19, vcc
	v_add_co_u32_e32 v54, vcc, 0x20000, v18
	s_nop 1
	v_addc_co_u32_e32 v55, vcc, 0, v19, vcc
	global_load_dword v65, v[20:21], off nt
	global_load_dword v66, v[22:23], off nt
	global_load_dword v67, v[24:25], off nt
	global_load_dword v68, v[26:27], off nt
	global_load_dword v69, v[28:29], off nt
	global_load_dword v70, v[30:31], off nt
	global_load_dword v71, v[52:53], off nt
	global_load_dword v72, v[54:55], off nt
	v_add_co_u32_e32 v20, vcc, 0x22000, v18
	s_nop 1
	v_addc_co_u32_e32 v21, vcc, 0, v19, vcc
	v_add_co_u32_e32 v22, vcc, 0x24000, v18
	s_nop 1
	v_addc_co_u32_e32 v23, vcc, 0, v19, vcc
	v_add_co_u32_e32 v24, vcc, 0x26000, v18
	s_nop 1
	v_addc_co_u32_e32 v25, vcc, 0, v19, vcc
	v_add_co_u32_e32 v26, vcc, 0x28000, v18
	s_nop 1
	v_addc_co_u32_e32 v27, vcc, 0, v19, vcc
	v_add_co_u32_e32 v28, vcc, 0x2a000, v18
	s_nop 1
	v_addc_co_u32_e32 v29, vcc, 0, v19, vcc
	v_add_co_u32_e32 v30, vcc, 0x2c000, v18
	s_nop 1
	v_addc_co_u32_e32 v31, vcc, 0, v19, vcc
	v_add_co_u32_e32 v52, vcc, 0x2e000, v18
	s_nop 1
	v_addc_co_u32_e32 v53, vcc, 0, v19, vcc
	v_add_co_u32_e32 v54, vcc, 0x30000, v18
	s_nop 1
	v_addc_co_u32_e32 v55, vcc, 0, v19, vcc
	global_load_dword v73, v[20:21], off nt
	global_load_dword v74, v[22:23], off nt
	global_load_dword v75, v[24:25], off nt
	global_load_dword v76, v[26:27], off nt
	global_load_dword v77, v[28:29], off nt
	global_load_dword v78, v[30:31], off nt
	s_nop 0
	global_load_dword v52, v[52:53], off nt
	s_nop 0
	global_load_dword v53, v[54:55], off nt
	v_add_co_u32_e32 v20, vcc, 0x32000, v18
	s_nop 1
	v_addc_co_u32_e32 v21, vcc, 0, v19, vcc
	v_add_co_u32_e32 v22, vcc, 0x34000, v18
	s_nop 1
	v_addc_co_u32_e32 v23, vcc, 0, v19, vcc
	v_add_co_u32_e32 v24, vcc, 0x36000, v18
	s_nop 1
	v_addc_co_u32_e32 v25, vcc, 0, v19, vcc
	v_add_co_u32_e32 v26, vcc, 0x38000, v18
	s_nop 1
	v_addc_co_u32_e32 v27, vcc, 0, v19, vcc
	v_add_co_u32_e32 v28, vcc, 0x3a000, v18
	s_nop 1
	v_addc_co_u32_e32 v29, vcc, 0, v19, vcc
	v_add_co_u32_e32 v30, vcc, 0x3c000, v18
	s_nop 1
	v_addc_co_u32_e32 v31, vcc, 0, v19, vcc
	v_add_co_u32_e32 v18, vcc, 0x3e000, v18
	s_nop 1
	v_addc_co_u32_e32 v19, vcc, 0, v19, vcc
	global_load_dword v20, v[20:21], off nt
	s_nop 0
	global_load_dword v21, v[22:23], off nt
	s_nop 0
	global_load_dword v22, v[24:25], off nt
	global_load_dword v23, v[26:27], off nt
	s_nop 0
	global_load_dword v24, v[28:29], off nt
	global_load_dword v25, v[30:31], off nt
	s_nop 0
	global_load_dword v18, v[18:19], off nt
	s_waitcnt vmcnt(30)
	ds_write2_b32 v32, v4, v56 offset1:66
	s_waitcnt vmcnt(28)
	ds_write2_b32 v32, v57, v58 offset0:132 offset1:198
	s_waitcnt vmcnt(26)
	ds_write2_b32 v43, v59, v60 offset0:8 offset1:74
	s_waitcnt vmcnt(24)
	ds_write2_b32 v43, v61, v63 offset0:140 offset1:206
	s_waitcnt vmcnt(22)
	ds_write2_b32 v44, v64, v65 offset0:16 offset1:82
	s_waitcnt vmcnt(20)
	ds_write2_b32 v44, v66, v67 offset0:148 offset1:214
	s_waitcnt vmcnt(18)
	ds_write2_b32 v46, v68, v69 offset0:24 offset1:90
	s_waitcnt vmcnt(16)
	ds_write2_b32 v46, v70, v71 offset0:156 offset1:222
	s_waitcnt vmcnt(14)
	ds_write2_b32 v47, v72, v73 offset0:32 offset1:98
	s_waitcnt vmcnt(12)
	ds_write2_b32 v47, v74, v75 offset0:164 offset1:230
	s_waitcnt vmcnt(10)
	ds_write2_b32 v48, v76, v77 offset0:40 offset1:106
	s_waitcnt vmcnt(8)
	ds_write2_b32 v48, v78, v52 offset0:172 offset1:238
	s_waitcnt vmcnt(6)
	ds_write2_b32 v49, v53, v20 offset0:48 offset1:114
	s_waitcnt vmcnt(4)
	ds_write2_b32 v49, v21, v22 offset0:180 offset1:246
	s_waitcnt vmcnt(2)
	ds_write2_b32 v50, v23, v24 offset0:56 offset1:122
	s_waitcnt vmcnt(0)
	ds_write2_b32 v50, v25, v18 offset0:188 offset1:254
	s_waitcnt lgkmcnt(0)
	ds_read2_b32 v[22:23], v34 offset0:33 offset1:41
	ds_read2_b32 v[24:25], v34 offset1:8
	ds_read2_b32 v[26:27], v34 offset0:66 offset1:74
	ds_read2_b32 v[28:29], v34 offset0:99 offset1:107
	ds_read2_b32 v[30:31], v34 offset0:132 offset1:140
	ds_read2_b32 v[52:53], v34 offset0:165 offset1:173
	ds_read2_b32 v[54:55], v34 offset0:198 offset1:206
	ds_read2_b32 v[56:57], v34 offset0:231 offset1:239
	v_lshlrev_b32_e32 v4, 1, v51
	v_lshl_add_u64 v[58:59], v[10:11], 0, v[4:5]
	v_or_b32_e32 v4, v62, v33
	v_lshlrev_b32_e32 v4, 11, v4
	s_waitcnt lgkmcnt(6)
	v_cvt_pk_bf16_f32 v18, v24, v22
	s_waitcnt lgkmcnt(4)
	v_cvt_pk_bf16_f32 v19, v26, v28
	s_waitcnt lgkmcnt(2)
	v_cvt_pk_bf16_f32 v20, v30, v52
	s_waitcnt lgkmcnt(0)
	v_cvt_pk_bf16_f32 v21, v54, v56
	v_lshl_add_u64 v[60:61], v[58:59], 0, v[4:5]
	global_store_dwordx4 v[60:61], v[18:21], off
	v_or_b32_e32 v4, v62, v35
	v_lshlrev_b32_e32 v4, 11, v4
	v_cvt_pk_bf16_f32 v18, v25, v23
	v_cvt_pk_bf16_f32 v19, v27, v29
	v_cvt_pk_bf16_f32 v20, v31, v53
	v_cvt_pk_bf16_f32 v21, v55, v57
	ds_read2_b32 v[24:25], v34 offset0:49 offset1:57
	ds_read2_b32 v[26:27], v34 offset0:16 offset1:24
	ds_read2_b32 v[28:29], v34 offset0:82 offset1:90
	ds_read2_b32 v[30:31], v34 offset0:115 offset1:123
	ds_read2_b32 v[52:53], v34 offset0:148 offset1:156
	ds_read2_b32 v[54:55], v34 offset0:181 offset1:189
	ds_read2_b32 v[56:57], v34 offset0:214 offset1:222
	ds_read2_b32 v[60:61], v34 offset0:247 offset1:255
	v_lshl_add_u64 v[22:23], v[58:59], 0, v[4:5]
	v_or_b32_e32 v4, v62, v36
	v_lshlrev_b32_e32 v4, 11, v4
	global_store_dwordx4 v[22:23], v[18:21], off
	v_lshl_add_u64 v[22:23], v[58:59], 0, v[4:5]
	v_or_b32_e32 v4, v62, v37
	s_waitcnt lgkmcnt(6)
	v_cvt_pk_bf16_f32 v18, v26, v24
	s_waitcnt lgkmcnt(4)
	v_cvt_pk_bf16_f32 v19, v28, v30
	s_waitcnt lgkmcnt(2)
	v_cvt_pk_bf16_f32 v20, v52, v54
	s_waitcnt lgkmcnt(0)
	v_cvt_pk_bf16_f32 v21, v56, v60
	v_lshlrev_b32_e32 v4, 11, v4
	global_store_dwordx4 v[22:23], v[18:21], off
	v_lshl_add_u64 v[22:23], v[58:59], 0, v[4:5]
	s_nop 0
	v_cvt_pk_bf16_f32 v18, v27, v25
	v_cvt_pk_bf16_f32 v19, v29, v31
	v_cvt_pk_bf16_f32 v20, v53, v55
	v_cvt_pk_bf16_f32 v21, v57, v61
	global_store_dwordx4 v[22:23], v[18:21], off
	s_waitcnt lgkmcnt(0)

.LBB0_102:
	s_andn2_saveexec_b64 s[22:23], s[4:5]
	s_cbranch_execz .LBB0_91
	v_mul_hi_i32 v4, v2, s35
	v_lshrrev_b32_e32 v18, 31, v4
	v_ashrrev_i32_e32 v4, 4, v4
	v_add_u32_e32 v4, v4, v18
	v_mad_u64_u32 v[22:23], s[4:5], v4, s46, v[16:17]
	v_lshlrev_b32_e32 v18, 6, v4
	v_add_u32_e32 v20, 0x600, v22
	v_or_b32_e32 v19, v18, v3
	v_ashrrev_i32_e32 v21, 31, v20
	v_lshl_add_u64 v[24:25], v[20:21], 2, v[14:15]
	v_or_b32_e32 v21, 2, v19
	v_mad_i64_i32 v[28:29], s[4:5], v21, s47, v[24:25]
	v_or_b32_e32 v21, 4, v19
	v_mad_i64_i32 v[30:31], s[4:5], v21, s47, v[24:25]
	v_or_b32_e32 v21, 6, v19
	v_mad_i64_i32 v[52:53], s[4:5], v21, s47, v[24:25]
	v_or_b32_e32 v21, 8, v19
	v_mad_i64_i32 v[54:55], s[4:5], v21, s47, v[24:25]
	v_or_b32_e32 v21, 10, v19
	v_mad_i64_i32 v[56:57], s[4:5], v21, s47, v[24:25]
	v_or_b32_e32 v21, 12, v19
	v_mad_i64_i32 v[58:59], s[4:5], v21, s47, v[24:25]
	v_or_b32_e32 v21, 14, v19
	v_mad_i64_i32 v[26:27], s[4:5], v19, s47, v[24:25]
	v_mad_i64_i32 v[60:61], s[4:5], v21, s47, v[24:25]
	global_load_dword v21, v[26:27], off nt
	global_load_dword v23, v[28:29], off nt
	global_load_dword v51, v[30:31], off nt
	global_load_dword v62, v[52:53], off nt
	global_load_dword v63, v[54:55], off nt
	global_load_dword v64, v[56:57], off nt
	global_load_dword v65, v[58:59], off nt
	global_load_dword v66, v[60:61], off nt
	v_or_b32_e32 v26, 16, v19
	v_or_b32_e32 v28, 18, v19
	v_or_b32_e32 v30, 20, v19
	v_or_b32_e32 v52, 22, v19
	v_or_b32_e32 v60, 30, v19
	v_mad_i64_i32 v[26:27], s[4:5], v26, s47, v[24:25]
	v_mad_i64_i32 v[28:29], s[4:5], v28, s47, v[24:25]
	v_mad_i64_i32 v[30:31], s[4:5], v30, s47, v[24:25]
	v_mad_i64_i32 v[52:53], s[4:5], v52, s47, v[24:25]
	v_or_b32_e32 v54, 24, v19
	v_or_b32_e32 v56, 26, v19
	v_or_b32_e32 v58, 28, v19
	v_mad_i64_i32 v[60:61], s[4:5], v60, s47, v[24:25]
	v_mad_i64_i32 v[54:55], s[4:5], v54, s47, v[24:25]
	v_mad_i64_i32 v[56:57], s[4:5], v56, s47, v[24:25]
	v_mad_i64_i32 v[58:59], s[4:5], v58, s47, v[24:25]
	global_load_dword v67, v[26:27], off nt
	global_load_dword v68, v[28:29], off nt
	global_load_dword v69, v[30:31], off nt
	global_load_dword v70, v[52:53], off nt
	global_load_dword v71, v[54:55], off nt
	global_load_dword v72, v[56:57], off nt
	global_load_dword v73, v[58:59], off nt
	global_load_dword v74, v[60:61], off nt
	v_or_b32_e32 v26, 32, v19
	v_or_b32_e32 v28, 34, v19
	v_or_b32_e32 v30, 36, v19
	v_or_b32_e32 v52, 38, v19
	v_or_b32_e32 v60, 46, v19
	v_mad_i64_i32 v[26:27], s[4:5], v26, s47, v[24:25]
	v_mad_i64_i32 v[28:29], s[4:5], v28, s47, v[24:25]
	v_mad_i64_i32 v[30:31], s[4:5], v30, s47, v[24:25]
	v_mad_i64_i32 v[52:53], s[4:5], v52, s47, v[24:25]
	v_or_b32_e32 v54, 40, v19
	v_or_b32_e32 v56, 42, v19
	v_or_b32_e32 v58, 44, v19
	v_mad_i64_i32 v[60:61], s[4:5], v60, s47, v[24:25]
	v_mad_i64_i32 v[54:55], s[4:5], v54, s47, v[24:25]
	v_mad_i64_i32 v[56:57], s[4:5], v56, s47, v[24:25]
	v_mad_i64_i32 v[58:59], s[4:5], v58, s47, v[24:25]
	global_load_dword v75, v[26:27], off nt
	global_load_dword v76, v[28:29], off nt
	global_load_dword v77, v[30:31], off nt
	global_load_dword v78, v[52:53], off nt
	global_load_dword v79, v[54:55], off nt
	global_load_dword v80, v[56:57], off nt
	global_load_dword v81, v[58:59], off nt
	s_nop 0
	global_load_dword v60, v[60:61], off nt
	v_or_b32_e32 v26, 48, v19
	v_or_b32_e32 v28, 50, v19
	v_or_b32_e32 v30, 52, v19
	v_or_b32_e32 v52, 54, v19
	v_mad_i64_i32 v[26:27], s[4:5], v26, s47, v[24:25]
	v_mad_i64_i32 v[28:29], s[4:5], v28, s47, v[24:25]
	v_or_b32_e32 v54, 56, v19
	v_or_b32_e32 v56, 58, v19
	v_or_b32_e32 v58, 60, v19
	v_or_b32_e32 v19, 62, v19
	v_mad_i64_i32 v[30:31], s[4:5], v30, s47, v[24:25]
	v_mad_i64_i32 v[52:53], s[4:5], v52, s47, v[24:25]
	v_mad_i64_i32 v[54:55], s[4:5], v54, s47, v[24:25]
	v_mad_i64_i32 v[56:57], s[4:5], v56, s47, v[24:25]
	v_mad_i64_i32 v[58:59], s[4:5], v58, s47, v[24:25]
	v_mad_i64_i32 v[24:25], s[4:5], v19, s47, v[24:25]
	global_load_dword v19, v[26:27], off nt
	s_nop 0
	global_load_dword v26, v[28:29], off nt
	global_load_dword v27, v[30:31], off nt
	s_nop 0
	global_load_dword v28, v[52:53], off nt
	global_load_dword v29, v[54:55], off nt
	global_load_dword v30, v[56:57], off nt
	global_load_dword v31, v[58:59], off nt
	s_nop 0
	global_load_dword v52, v[24:25], off nt
	s_waitcnt vmcnt(30)
	ds_write2_b32 v32, v21, v23 offset1:66
	s_waitcnt vmcnt(28)
	ds_write2_b32 v32, v51, v62 offset0:132 offset1:198
	s_waitcnt vmcnt(26)
	ds_write2_b32 v43, v63, v64 offset0:8 offset1:74
	s_waitcnt vmcnt(24)
	ds_write2_b32 v43, v65, v66 offset0:140 offset1:206
	s_waitcnt vmcnt(22)
	ds_write2_b32 v44, v67, v68 offset0:16 offset1:82
	s_waitcnt vmcnt(20)
	ds_write2_b32 v44, v69, v70 offset0:148 offset1:214
	s_waitcnt vmcnt(18)
	ds_write2_b32 v46, v71, v72 offset0:24 offset1:90
	s_waitcnt vmcnt(16)
	ds_write2_b32 v46, v73, v74 offset0:156 offset1:222
	s_waitcnt vmcnt(14)
	ds_write2_b32 v47, v75, v76 offset0:32 offset1:98
	s_waitcnt vmcnt(12)
	ds_write2_b32 v47, v77, v78 offset0:164 offset1:230
	s_waitcnt vmcnt(10)
	ds_write2_b32 v48, v79, v80 offset0:40 offset1:106
	s_waitcnt vmcnt(8)
	ds_write2_b32 v48, v81, v60 offset0:172 offset1:238
	s_waitcnt vmcnt(6)
	ds_write2_b32 v49, v19, v26 offset0:48 offset1:114
	s_waitcnt vmcnt(4)
	ds_write2_b32 v49, v27, v28 offset0:180 offset1:246
	s_waitcnt vmcnt(2)
	ds_write2_b32 v50, v29, v30 offset0:56 offset1:122
	s_waitcnt vmcnt(0)
	ds_write2_b32 v50, v31, v52 offset0:188 offset1:254
	v_mad_u64_u32 v[24:25], s[4:5], v4, s45, v[2:3]
	s_waitcnt lgkmcnt(0)
	v_and_b32_e32 v4, 0x7fffff0, v24
	ds_read2_b32 v[24:25], v34 offset1:33
	ds_read2_b32 v[26:27], v34 offset0:66 offset1:99
	ds_read2_b32 v[28:29], v34 offset0:132 offset1:165
	ds_read2_b32 v[30:31], v34 offset0:198 offset1:231
	v_add_u32_e32 v52, v22, v33
	v_cmp_eq_u32_e32 vcc, 64, v4
	v_and_b32_e32 v4, 0x9e0, v20
	v_add_u32_e32 v19, 0x600, v52
	v_cmp_lt_u32_e64 s[4:5], s48, v22
	s_and_saveexec_b64 s[6:7], s[4:5]
	s_xor_b64 s[6:7], exec, s[6:7]
	v_or_b32_e32 v21, v4, v38
	v_cndmask_b32_e32 v22, v19, v21, vcc
	s_or_saveexec_b64 s[24:25], s[6:7]
	v_and_b32_e32 v51, 0x7c0, v20
	s_xor_b64 exec, exec, s[24:25]
	v_and_b32_e32 v19, 39, v19
	v_lshlrev_b32_e32 v20, 1, v19
	v_subrev_u32_e32 v21, 63, v20
	v_cmp_gt_u32_e64 s[6:7], 32, v19
	s_nop 1
	v_cndmask_b32_e64 v19, v21, v20, s[6:7]
	v_add_u32_e32 v22, v19, v51
	s_or_b64 exec, exec, s[24:25]
	s_waitcnt lgkmcnt(3)
	v_cvt_pk_bf16_f32 v54, v24, v25
	s_waitcnt lgkmcnt(2)
	v_cvt_pk_bf16_f32 v55, v26, v27
	s_waitcnt lgkmcnt(1)
	v_cvt_pk_bf16_f32 v56, v28, v29
	s_waitcnt lgkmcnt(0)
	v_cvt_pk_bf16_f32 v57, v30, v31
	ds_read2_b32 v[24:25], v34 offset0:8 offset1:41
	ds_read2_b32 v[26:27], v34 offset0:74 offset1:107
	ds_read2_b32 v[28:29], v34 offset0:140 offset1:173
	ds_read2_b32 v[30:31], v34 offset0:206 offset1:239
	v_ashrrev_i32_e32 v19, 31, v18
	v_ashrrev_i32_e32 v23, 31, v22
	v_lshl_add_u64 v[18:19], v[18:19], 1, v[12:13]
	v_lshlrev_b64 v[20:21], 11, v[22:23]
	v_lshl_add_u64 v[20:21], v[18:19], 0, v[20:21]
	global_store_dwordx4 v[20:21], v[54:57], off
	v_add_u32_e32 v21, 0x608, v52
	s_and_saveexec_b64 s[6:7], s[4:5]
	s_xor_b64 s[6:7], exec, s[6:7]
	v_or_b32_e32 v20, v4, v39
	v_cndmask_b32_e32 v20, v21, v20, vcc
	s_andn2_saveexec_b64 s[24:25], s[6:7]
	v_and_b32_e32 v20, 47, v21
	v_lshlrev_b32_e32 v21, 1, v20
	v_subrev_u32_e32 v22, 63, v21
	v_cmp_gt_u32_e64 s[6:7], 32, v20
	s_nop 1
	v_cndmask_b32_e64 v20, v22, v21, s[6:7]
	v_add_u32_e32 v20, v20, v51
	s_or_b64 exec, exec, s[24:25]
	s_waitcnt lgkmcnt(3)
	v_cvt_pk_bf16_f32 v54, v24, v25
	s_waitcnt lgkmcnt(2)
	v_cvt_pk_bf16_f32 v55, v26, v27
	s_waitcnt lgkmcnt(0)
	v_cvt_pk_bf16_f32 v57, v30, v31
	ds_read2_b32 v[22:23], v34 offset0:16 offset1:49
	ds_read2_b32 v[24:25], v34 offset0:82 offset1:115
	ds_read2_b32 v[26:27], v34 offset0:148 offset1:181
	ds_read2_b32 v[30:31], v34 offset0:214 offset1:247
	v_ashrrev_i32_e32 v21, 31, v20
	v_lshlrev_b64 v[20:21], 11, v[20:21]
	v_cvt_pk_bf16_f32 v56, v28, v29
	v_lshl_add_u64 v[20:21], v[18:19], 0, v[20:21]
	global_store_dwordx4 v[20:21], v[54:57], off
	v_add_u32_e32 v20, 0x610, v52
	s_and_saveexec_b64 s[6:7], s[4:5]
	s_xor_b64 s[6:7], exec, s[6:7]
	v_or_b32_e32 v21, v4, v40
	v_cndmask_b32_e32 v28, v20, v21, vcc
	s_andn2_saveexec_b64 s[24:25], s[6:7]
	v_and_b32_e32 v20, 55, v20
	v_lshlrev_b32_e32 v21, 1, v20
	v_subrev_u32_e32 v28, 63, v21
	v_cmp_gt_u32_e64 s[6:7], 32, v20
	s_nop 1
	v_cndmask_b32_e64 v20, v28, v21, s[6:7]
	v_add_u32_e32 v28, v20, v51
	s_or_b64 exec, exec, s[24:25]
	s_waitcnt lgkmcnt(3)
	v_cvt_pk_bf16_f32 v54, v22, v23
	s_waitcnt lgkmcnt(2)
	v_cvt_pk_bf16_f32 v55, v24, v25
	s_waitcnt lgkmcnt(1)
	v_cvt_pk_bf16_f32 v56, v26, v27
	ds_read2_b32 v[20:21], v34 offset0:24 offset1:57
	ds_read2_b32 v[22:23], v34 offset0:90 offset1:123
	ds_read2_b32 v[24:25], v34 offset0:156 offset1:189
	ds_read2_b32 v[26:27], v34 offset0:222 offset1:255
	v_ashrrev_i32_e32 v29, 31, v28
	v_lshlrev_b64 v[28:29], 11, v[28:29]
	s_waitcnt lgkmcnt(4)
	v_cvt_pk_bf16_f32 v57, v30, v31
	v_lshl_add_u64 v[28:29], v[18:19], 0, v[28:29]
	global_store_dwordx4 v[28:29], v[54:57], off
	v_add_u32_e32 v29, 0x618, v52
	s_and_saveexec_b64 s[6:7], s[4:5]
	s_xor_b64 s[4:5], exec, s[6:7]
	v_or_b32_e32 v4, v4, v41
	v_cndmask_b32_e32 v28, v29, v4, vcc
	s_andn2_saveexec_b64 s[4:5], s[4:5]
	s_cbranch_execz .LBB0_90
	v_and_b32_e32 v4, 63, v29
	v_lshlrev_b32_e32 v28, 1, v4
	v_subrev_u32_e32 v29, 63, v28
	v_cmp_gt_u32_e32 vcc, 32, v4
	s_nop 1
	v_cndmask_b32_e32 v4, v29, v28, vcc
	v_add_u32_e32 v28, v4, v51
	s_branch .LBB0_90

.LBB0_218:
	s_lshl_b32 s58, s55, 6
	s_cmp_gt_i32 s55, 43
	s_mov_b64 s[4:5], -1
	s_cbranch_scc0 .LBB0_306
	v_mov_b32_e32 v14, v228
	s_nop 0
	v_and_b32_e32 v0, 0x3ff, v14
	v_cmp_lt_u32_e32 vcc, s44, v14
	v_lshlrev_b32_e32 v6, 2, v0
	s_barrier
	s_and_saveexec_b64 s[4:5], vcc
	s_xor_b64 s[4:5], exec, s[4:5]
	v_ashrrev_i32_e32 v0, 10, v14
	v_add_u32_e32 v0, -1, v0
	v_mul_hi_i32_i24_e32 v1, 0x6000, v0
	v_mul_i32_i24_e32 v0, 0x6000, v0
	v_lshl_add_u64 v[0:1], s[6:7], 0, v[0:1]
	v_lshl_add_u64 v[0:1], v[0:1], 0, v[6:7]
	s_andn2_saveexec_b64 s[4:5], s[4:5]
	v_lshl_add_u64 v[0:1], s[0:1], 0, v[6:7]
	s_or_b64 exec, exec, s[4:5]
	global_load_dword v4, v[0:1], off nt
	v_add_u32_e32 v15, 0x200, v14
	v_and_b32_e32 v0, 0x3ff, v15
	v_cmp_lt_u32_e32 vcc, s44, v15
	v_lshlrev_b32_e32 v0, 2, v0
	s_and_saveexec_b64 s[4:5], vcc
	s_xor_b64 s[4:5], exec, s[4:5]
	v_ashrrev_i32_e32 v1, 10, v15
	v_add_u32_e32 v1, -1, v1
	v_mul_hi_i32_i24_e32 v3, 0x6000, v1
	v_mul_i32_i24_e32 v2, 0x6000, v1
	v_lshl_add_u64 v[2:3], s[6:7], 0, v[2:3]
	v_mov_b32_e32 v1, v7
	v_lshl_add_u64 v[2:3], v[2:3], 0, v[0:1]
	s_andn2_saveexec_b64 s[4:5], s[4:5]
	v_mov_b32_e32 v1, v7
	v_lshl_add_u64 v[2:3], s[0:1], 0, v[0:1]
	s_or_b64 exec, exec, s[4:5]
	global_load_dword v5, v[2:3], off nt
	v_cmp_gt_u32_e32 vcc, s45, v14
	s_and_saveexec_b64 s[4:5], vcc
	s_xor_b64 s[4:5], exec, s[4:5]
	v_add_u32_e32 v0, 0x400, v14
	v_ashrrev_i32_e32 v0, 10, v0
	v_add_u32_e32 v0, -1, v0
	v_mul_hi_i32_i24_e32 v1, 0x6000, v0
	v_mul_i32_i24_e32 v0, 0x6000, v0
	v_lshl_add_u64 v[0:1], s[6:7], 0, v[0:1]
	v_lshl_add_u64 v[0:1], v[0:1], 0, v[6:7]
	s_andn2_saveexec_b64 s[4:5], s[4:5]
	v_lshl_add_u64 v[0:1], s[0:1], 0, v[6:7]
	s_or_b64 exec, exec, s[4:5]
	global_load_dword v9, v[0:1], off nt
	v_add_u32_e32 v1, 0x600, v14
	v_and_b32_e32 v0, 0x3ff, v1
	v_cmp_lt_u32_e32 vcc, s44, v1
	v_lshlrev_b32_e32 v0, 2, v0
	s_and_saveexec_b64 s[4:5], vcc
	s_xor_b64 s[4:5], exec, s[4:5]
	v_ashrrev_i32_e32 v1, 10, v1
	v_add_u32_e32 v1, -1, v1
	v_mul_hi_i32_i24_e32 v3, 0x6000, v1
	v_mul_i32_i24_e32 v2, 0x6000, v1
	v_lshl_add_u64 v[2:3], s[6:7], 0, v[2:3]
	v_mov_b32_e32 v1, v7
	v_lshl_add_u64 v[2:3], v[2:3], 0, v[0:1]
	s_andn2_saveexec_b64 s[4:5], s[4:5]
	v_mov_b32_e32 v1, v7
	v_lshl_add_u64 v[2:3], s[0:1], 0, v[0:1]
	s_or_b64 exec, exec, s[4:5]
	global_load_dword v10, v[2:3], off nt
	v_add_u32_e32 v2, 0x800, v14
	v_cmp_lt_u32_e32 vcc, s44, v2
	s_and_saveexec_b64 s[4:5], vcc
	s_xor_b64 s[4:5], exec, s[4:5]
	v_ashrrev_i32_e32 v0, 10, v2
	v_add_u32_e32 v0, -1, v0
	v_mul_hi_i32_i24_e32 v1, 0x6000, v0
	v_mul_i32_i24_e32 v0, 0x6000, v0
	v_lshl_add_u64 v[0:1], s[6:7], 0, v[0:1]
	v_lshl_add_u64 v[0:1], v[0:1], 0, v[6:7]
	s_andn2_saveexec_b64 s[4:5], s[4:5]
	v_lshl_add_u64 v[0:1], s[0:1], 0, v[6:7]
	s_or_b64 exec, exec, s[4:5]
	global_load_dword v11, v[0:1], off nt
	v_add_u32_e32 v1, 0xa00, v14
	v_and_b32_e32 v0, 0x3ff, v1
	v_cmp_lt_u32_e32 vcc, s44, v1
	v_lshlrev_b32_e32 v0, 2, v0
	s_and_saveexec_b64 s[4:5], vcc
	s_xor_b64 s[4:5], exec, s[4:5]
	v_ashrrev_i32_e32 v1, 10, v1
	v_add_u32_e32 v1, -1, v1
	v_mul_hi_i32_i24_e32 v3, 0x6000, v1
	v_mul_i32_i24_e32 v2, 0x6000, v1
	v_lshl_add_u64 v[2:3], s[6:7], 0, v[2:3]
	v_mov_b32_e32 v1, v7
	v_lshl_add_u64 v[2:3], v[2:3], 0, v[0:1]
	s_andn2_saveexec_b64 s[4:5], s[4:5]
	v_mov_b32_e32 v1, v7
	v_lshl_add_u64 v[2:3], s[0:1], 0, v[0:1]
	s_or_b64 exec, exec, s[4:5]
	global_load_dword v16, v[2:3], off nt
	v_add_u32_e32 v2, 0xc00, v14
	v_cmp_lt_u32_e32 vcc, s44, v2
	s_and_saveexec_b64 s[4:5], vcc
	s_xor_b64 s[4:5], exec, s[4:5]
	v_ashrrev_i32_e32 v0, 10, v2
	v_add_u32_e32 v0, -1, v0
	v_mul_hi_i32_i24_e32 v1, 0x6000, v0
	v_mul_i32_i24_e32 v0, 0x6000, v0
	v_lshl_add_u64 v[0:1], s[6:7], 0, v[0:1]
	v_lshl_add_u64 v[0:1], v[0:1], 0, v[6:7]
	s_andn2_saveexec_b64 s[4:5], s[4:5]
	v_lshl_add_u64 v[0:1], s[0:1], 0, v[6:7]
	s_or_b64 exec, exec, s[4:5]
	global_load_dword v17, v[0:1], off nt
	v_add_u32_e32 v1, 0xe00, v14
	v_and_b32_e32 v0, 0x3ff, v1
	v_cmp_lt_u32_e32 vcc, s44, v1
	v_lshlrev_b32_e32 v0, 2, v0
	s_and_saveexec_b64 s[4:5], vcc
	s_xor_b64 s[4:5], exec, s[4:5]
	v_ashrrev_i32_e32 v1, 10, v1
	v_add_u32_e32 v1, -1, v1
	v_mul_hi_i32_i24_e32 v3, 0x6000, v1
	v_mul_i32_i24_e32 v2, 0x6000, v1
	v_lshl_add_u64 v[2:3], s[6:7], 0, v[2:3]
	v_mov_b32_e32 v1, v7
	v_lshl_add_u64 v[2:3], v[2:3], 0, v[0:1]
	s_andn2_saveexec_b64 s[4:5], s[4:5]
	v_mov_b32_e32 v1, v7
	v_lshl_add_u64 v[2:3], s[0:1], 0, v[0:1]
	s_or_b64 exec, exec, s[4:5]
	global_load_dword v18, v[2:3], off nt
	v_add_u32_e32 v2, 0x1000, v14
	v_cmp_lt_u32_e32 vcc, s44, v2
	s_and_saveexec_b64 s[4:5], vcc
	s_xor_b64 s[4:5], exec, s[4:5]
	v_ashrrev_i32_e32 v0, 10, v2
	v_add_u32_e32 v0, -1, v0
	v_mul_hi_i32_i24_e32 v1, 0x6000, v0
	v_mul_i32_i24_e32 v0, 0x6000, v0
	v_lshl_add_u64 v[0:1], s[6:7], 0, v[0:1]
	v_lshl_add_u64 v[0:1], v[0:1], 0, v[6:7]
	s_andn2_saveexec_b64 s[4:5], s[4:5]
	v_lshl_add_u64 v[0:1], s[0:1], 0, v[6:7]
	s_or_b64 exec, exec, s[4:5]
	global_load_dword v19, v[0:1], off nt
	v_add_u32_e32 v1, 0x1200, v14
	v_and_b32_e32 v0, 0x3ff, v1
	v_cmp_lt_u32_e32 vcc, s44, v1
	v_lshlrev_b32_e32 v0, 2, v0
	s_and_saveexec_b64 s[4:5], vcc
	s_xor_b64 s[4:5], exec, s[4:5]
	v_ashrrev_i32_e32 v1, 10, v1
	v_add_u32_e32 v1, -1, v1
	v_mul_hi_i32_i24_e32 v3, 0x6000, v1
	v_mul_i32_i24_e32 v2, 0x6000, v1
	v_lshl_add_u64 v[2:3], s[6:7], 0, v[2:3]
	v_mov_b32_e32 v1, v7
	v_lshl_add_u64 v[2:3], v[2:3], 0, v[0:1]
	s_andn2_saveexec_b64 s[4:5], s[4:5]
	v_mov_b32_e32 v1, v7
	v_lshl_add_u64 v[2:3], s[0:1], 0, v[0:1]
	s_or_b64 exec, exec, s[4:5]
	global_load_dword v20, v[2:3], off nt
	v_add_u32_e32 v2, 0x1400, v14
	v_cmp_lt_u32_e32 vcc, s44, v2
	s_and_saveexec_b64 s[4:5], vcc
	s_xor_b64 s[4:5], exec, s[4:5]
	v_ashrrev_i32_e32 v0, 10, v2
	v_add_u32_e32 v0, -1, v0
	v_mul_hi_i32_i24_e32 v1, 0x6000, v0
	v_mul_i32_i24_e32 v0, 0x6000, v0
	v_lshl_add_u64 v[0:1], s[6:7], 0, v[0:1]
	v_lshl_add_u64 v[0:1], v[0:1], 0, v[6:7]
	s_andn2_saveexec_b64 s[4:5], s[4:5]
	v_lshl_add_u64 v[0:1], s[0:1], 0, v[6:7]
	s_or_b64 exec, exec, s[4:5]
	global_load_dword v22, v[0:1], off nt
	v_add_u32_e32 v1, 0x1600, v14
	v_and_b32_e32 v0, 0x3ff, v1
	v_cmp_lt_u32_e32 vcc, s44, v1
	v_lshlrev_b32_e32 v0, 2, v0
	s_and_saveexec_b64 s[4:5], vcc
	s_xor_b64 s[4:5], exec, s[4:5]
	v_ashrrev_i32_e32 v1, 10, v1
	v_add_u32_e32 v1, -1, v1
	v_mul_hi_i32_i24_e32 v3, 0x6000, v1
	v_mul_i32_i24_e32 v2, 0x6000, v1
	v_lshl_add_u64 v[2:3], s[6:7], 0, v[2:3]
	v_mov_b32_e32 v1, v7
	v_lshl_add_u64 v[2:3], v[2:3], 0, v[0:1]
	s_andn2_saveexec_b64 s[4:5], s[4:5]
	v_mov_b32_e32 v1, v7
	v_lshl_add_u64 v[2:3], s[0:1], 0, v[0:1]
	s_or_b64 exec, exec, s[4:5]
	global_load_dword v23, v[2:3], off nt
	v_add_u32_e32 v2, 0x1800, v14
	v_cmp_lt_u32_e32 vcc, s44, v2
	s_and_saveexec_b64 s[4:5], vcc
	s_xor_b64 s[4:5], exec, s[4:5]
	v_ashrrev_i32_e32 v0, 10, v2
	v_add_u32_e32 v0, -1, v0
	v_mul_hi_i32_i24_e32 v1, 0x6000, v0
	v_mul_i32_i24_e32 v0, 0x6000, v0
	v_lshl_add_u64 v[0:1], s[6:7], 0, v[0:1]
	v_lshl_add_u64 v[0:1], v[0:1], 0, v[6:7]
	s_andn2_saveexec_b64 s[4:5], s[4:5]
	v_lshl_add_u64 v[0:1], s[0:1], 0, v[6:7]
	s_or_b64 exec, exec, s[4:5]
	global_load_dword v24, v[0:1], off nt
	v_add_u32_e32 v1, 0x1a00, v14
	v_and_b32_e32 v0, 0x3ff, v1
	v_cmp_lt_u32_e32 vcc, s44, v1
	v_lshlrev_b32_e32 v0, 2, v0
	s_and_saveexec_b64 s[4:5], vcc
	s_xor_b64 s[4:5], exec, s[4:5]
	v_ashrrev_i32_e32 v1, 10, v1
	v_add_u32_e32 v1, -1, v1
	v_mul_hi_i32_i24_e32 v3, 0x6000, v1
	v_mul_i32_i24_e32 v2, 0x6000, v1
	v_lshl_add_u64 v[2:3], s[6:7], 0, v[2:3]
	v_mov_b32_e32 v1, v7
	v_lshl_add_u64 v[2:3], v[2:3], 0, v[0:1]
	s_andn2_saveexec_b64 s[4:5], s[4:5]
	v_mov_b32_e32 v1, v7
	v_lshl_add_u64 v[2:3], s[0:1], 0, v[0:1]
	s_or_b64 exec, exec, s[4:5]
	global_load_dword v26, v[2:3], off nt
	v_add_u32_e32 v2, 0x1c00, v14
	v_cmp_lt_u32_e32 vcc, s44, v2
	s_and_saveexec_b64 s[4:5], vcc
	s_xor_b64 s[4:5], exec, s[4:5]
	v_ashrrev_i32_e32 v0, 10, v2
	v_add_u32_e32 v0, -1, v0
	v_mul_hi_i32_i24_e32 v1, 0x6000, v0
	v_mul_i32_i24_e32 v0, 0x6000, v0
	v_lshl_add_u64 v[0:1], s[6:7], 0, v[0:1]
	v_lshl_add_u64 v[0:1], v[0:1], 0, v[6:7]
	s_andn2_saveexec_b64 s[4:5], s[4:5]
	v_lshl_add_u64 v[0:1], s[0:1], 0, v[6:7]
	s_or_b64 exec, exec, s[4:5]
	global_load_dword v27, v[0:1], off nt
	v_add_u32_e32 v1, 0x1e00, v14
	v_and_b32_e32 v0, 0x3ff, v1
	v_cmp_lt_u32_e32 vcc, s44, v1
	v_lshlrev_b32_e32 v0, 2, v0
	s_and_saveexec_b64 s[4:5], vcc
	s_xor_b64 s[4:5], exec, s[4:5]
	v_ashrrev_i32_e32 v1, 10, v1
	v_add_u32_e32 v1, -1, v1
	v_mul_hi_i32_i24_e32 v3, 0x6000, v1
	v_mul_i32_i24_e32 v2, 0x6000, v1
	v_lshl_add_u64 v[2:3], s[6:7], 0, v[2:3]
	v_mov_b32_e32 v1, v7
	v_lshl_add_u64 v[2:3], v[2:3], 0, v[0:1]
	s_andn2_saveexec_b64 s[4:5], s[4:5]
	v_mov_b32_e32 v1, v7
	v_lshl_add_u64 v[2:3], s[0:1], 0, v[0:1]
	s_or_b64 exec, exec, s[4:5]
	global_load_dword v2, v[2:3], off nt
	v_add_u32_e32 v3, 0x2000, v14
	v_cmp_lt_u32_e32 vcc, s44, v3
	s_and_saveexec_b64 s[4:5], vcc
	s_xor_b64 s[4:5], exec, s[4:5]
	v_ashrrev_i32_e32 v0, 10, v3
	v_add_u32_e32 v0, -1, v0
	v_mul_hi_i32_i24_e32 v1, 0x6000, v0
	v_mul_i32_i24_e32 v0, 0x6000, v0
	v_lshl_add_u64 v[0:1], s[6:7], 0, v[0:1]
	v_lshl_add_u64 v[0:1], v[0:1], 0, v[6:7]
	s_andn2_saveexec_b64 s[4:5], s[4:5]
	v_lshl_add_u64 v[0:1], s[0:1], 0, v[6:7]
	s_or_b64 exec, exec, s[4:5]
	global_load_dword v3, v[0:1], off nt
	v_add_u32_e32 v8, 0x2200, v14
	v_and_b32_e32 v0, 0x3ff, v8
	v_cmp_lt_u32_e32 vcc, s44, v8
	v_lshlrev_b32_e32 v6, 2, v0
	s_and_saveexec_b64 s[4:5], vcc
	s_xor_b64 s[4:5], exec, s[4:5]
	v_ashrrev_i32_e32 v0, 10, v8
	v_add_u32_e32 v0, -1, v0
	v_mul_hi_i32_i24_e32 v1, 0x6000, v0
	v_mul_i32_i24_e32 v0, 0x6000, v0
	v_lshl_add_u64 v[0:1], s[6:7], 0, v[0:1]
	v_lshl_add_u64 v[0:1], v[0:1], 0, v[6:7]
	s_andn2_saveexec_b64 s[4:5], s[4:5]
	v_lshl_add_u64 v[0:1], s[0:1], 0, v[6:7]
	s_or_b64 exec, exec, s[4:5]
	global_load_dword v28, v[0:1], off nt
	v_ashrrev_i32_e32 v25, 6, v14
	v_lshlrev_b32_e32 v0, 7, v25
	s_load_dwordx8 s[60:67], s[80:81], 0xd0
	v_ashrrev_i32_e32 v1, 31, v0
	v_and_b32_e32 v21, 63, v14
	v_lshlrev_b64 v[0:1], 14, v[0:1]
	v_lshlrev_b32_e32 v6, 2, v21
	v_lshl_add_u64 v[0:1], s[22:23], 2, v[0:1]
	v_lshl_add_u32 v29, v14, 2, 0
	v_mov_b32_e32 v8, 0
	v_lshl_add_u64 v[0:1], v[0:1], 0, v[6:7]
	s_movk_i32 s4, 0xffe0
	s_waitcnt vmcnt(16)
	ds_write2st64_b32 v29, v4, v5 offset1:8
	s_waitcnt vmcnt(14)
	ds_write2st64_b32 v29, v9, v10 offset0:16 offset1:24
	s_waitcnt vmcnt(12)
	ds_write2st64_b32 v29, v11, v16 offset0:32 offset1:40
	s_waitcnt vmcnt(10)
	ds_write2st64_b32 v29, v17, v18 offset0:48 offset1:56
	s_waitcnt vmcnt(8)
	ds_write2st64_b32 v29, v19, v20 offset0:64 offset1:72
	s_waitcnt vmcnt(6)
	ds_write2st64_b32 v29, v22, v23 offset0:80 offset1:88
	s_waitcnt vmcnt(4)
	ds_write2st64_b32 v29, v24, v26 offset0:96 offset1:104
	s_waitcnt vmcnt(2)
	ds_write2st64_b32 v29, v27, v2 offset0:112 offset1:120
	v_lshl_add_u32 v47, v25, 9, 0
	v_mov_b32_e32 v9, v8
	v_mov_b32_e32 v32, v8
	v_mov_b32_e32 v33, v8
	v_mov_b32_e32 v34, v8
	v_mov_b32_e32 v35, v8
	v_mov_b32_e32 v36, v8
	v_mov_b32_e32 v37, v8
	s_waitcnt lgkmcnt(0)
	v_lshl_add_u64 v[16:17], s[64:65], 0, v[0:1]
	v_mov_b32_e32 v19, v8
	s_waitcnt vmcnt(0)
	ds_write2st64_b32 v29, v3, v28 offset0:128 offset1:136
	s_waitcnt lgkmcnt(0)
	s_barrier
.LBB0_292:
	v_add_co_u32_e32 v0, vcc, 0x4000, v16
	global_load_dword v72, v[16:17], off nt
	s_nop 0
	v_addc_co_u32_e32 v1, vcc, 0, v17, vcc
	global_load_dword v74, v[0:1], off nt
	v_add_co_u32_e32 v0, vcc, 0x8000, v16
	v_add_u32_e32 v43, 0x402c, v47
	s_nop 0
	v_addc_co_u32_e32 v1, vcc, 0, v17, vcc
	global_load_dword v76, v[0:1], off nt
	v_add_co_u32_e32 v0, vcc, 0xc000, v16
	v_add_u32_e32 v41, 0x302c, v47
	s_nop 0
	v_addc_co_u32_e32 v1, vcc, 0, v17, vcc
	global_load_dword v78, v[0:1], off nt
	v_add_co_u32_e32 v0, vcc, 0x10000, v16
	v_add_u32_e32 v55, 0x1034, v47
	s_nop 0
	v_addc_co_u32_e32 v1, vcc, 0, v17, vcc
	global_load_dword v60, v[0:1], off nt
	v_add_co_u32_e32 v0, vcc, 0x14000, v16
	v_add_u32_e32 v51, 0x602c, v47
	s_nop 0
	v_addc_co_u32_e32 v1, vcc, 0, v17, vcc
	global_load_dword v62, v[0:1], off nt
	v_add_co_u32_e32 v0, vcc, 0x18000, v16
	v_add_u32_e32 v49, 0x502c, v47
	s_nop 0
	v_addc_co_u32_e32 v1, vcc, 0, v17, vcc
	global_load_dword v64, v[0:1], off nt
	v_add_co_u32_e32 v0, vcc, 0x1c000, v16
	v_add_u32_e32 v53, 0x702c, v47
	s_nop 0
	v_addc_co_u32_e32 v1, vcc, 0, v17, vcc
	global_load_dword v68, v[0:1], off nt
	v_add_co_u32_e32 v0, vcc, 0x20000, v16
	v_add_u32_e32 v59, 0x3034, v47
	s_nop 0
	v_addc_co_u32_e32 v1, vcc, 0, v17, vcc
	global_load_dword v66, v[0:1], off nt
	v_add_co_u32_e32 v0, vcc, 0x24000, v16
	v_add_u32_e32 v57, 0x2034, v47
	s_nop 0
	v_addc_co_u32_e32 v1, vcc, 0, v17, vcc
	global_load_dword v70, v[0:1], off nt
	v_add_co_u32_e32 v0, vcc, 0x28000, v16
	v_add_u32_e32 v39, 0x202c, v47
	s_nop 0
	v_addc_co_u32_e32 v1, vcc, 0, v17, vcc
	global_load_dword v42, v[0:1], off nt
	v_add_co_u32_e32 v0, vcc, 0x2c000, v16
	s_add_i32 s4, s4, 32
	s_nop 0
	v_addc_co_u32_e32 v1, vcc, 0, v17, vcc
	global_load_dword v40, v[0:1], off nt
	v_add_co_u32_e32 v0, vcc, 0x30000, v16
	s_cmpk_gt_u32 s4, 0x5f
	s_nop 0
	v_addc_co_u32_e32 v1, vcc, 0, v17, vcc
	global_load_dword v46, v[0:1], off nt
	v_add_co_u32_e32 v0, vcc, 0x34000, v16
	s_nop 1
	v_addc_co_u32_e32 v1, vcc, 0, v17, vcc
	global_load_dword v44, v[0:1], off nt
	v_add_co_u32_e32 v0, vcc, 0x38000, v16
	s_nop 1
	v_addc_co_u32_e32 v1, vcc, 0, v17, vcc
	global_load_dword v50, v[0:1], off nt
	v_add_co_u32_e32 v0, vcc, 0x3c000, v16
	s_nop 1
	v_addc_co_u32_e32 v1, vcc, 0, v17, vcc
	global_load_dword v48, v[0:1], off nt
	v_add_co_u32_e32 v0, vcc, 0x40000, v16
	s_nop 1
	v_addc_co_u32_e32 v1, vcc, 0, v17, vcc
	global_load_dword v54, v[0:1], off nt
	v_add_co_u32_e32 v0, vcc, 0x44000, v16
	s_nop 1
	v_addc_co_u32_e32 v1, vcc, 0, v17, vcc
	global_load_dword v52, v[0:1], off nt
	v_add_co_u32_e32 v0, vcc, 0x48000, v16
	s_nop 1
	v_addc_co_u32_e32 v1, vcc, 0, v17, vcc
	global_load_dword v58, v[0:1], off nt
	v_add_co_u32_e32 v0, vcc, 0x4c000, v16
	s_nop 1
	v_addc_co_u32_e32 v1, vcc, 0, v17, vcc
	global_load_dword v56, v[0:1], off nt
	v_add_co_u32_e32 v0, vcc, 0x50000, v16
	s_nop 1
	v_addc_co_u32_e32 v1, vcc, 0, v17, vcc
	global_load_dword v38, v[0:1], off nt
	v_add_co_u32_e32 v0, vcc, 0x54000, v16
	s_nop 1
	v_addc_co_u32_e32 v1, vcc, 0, v17, vcc
	global_load_dword v24, v[0:1], off nt
	v_add_co_u32_e32 v0, vcc, 0x58000, v16
	s_nop 1
	v_addc_co_u32_e32 v1, vcc, 0, v17, vcc
	global_load_dword v22, v[0:1], off nt
	v_add_co_u32_e32 v0, vcc, 0x5c000, v16
	s_nop 1
	v_addc_co_u32_e32 v1, vcc, 0, v17, vcc
	global_load_dword v23, v[0:1], off nt
	v_add_co_u32_e32 v0, vcc, 0x60000, v16
	s_nop 1
	v_addc_co_u32_e32 v1, vcc, 0, v17, vcc
	global_load_dword v26, v[0:1], off nt
	v_add_co_u32_e32 v0, vcc, 0x64000, v16
	s_nop 1
	v_addc_co_u32_e32 v1, vcc, 0, v17, vcc
	global_load_dword v27, v[0:1], off nt
	v_add_co_u32_e32 v0, vcc, 0x68000, v16
	s_nop 1
	v_addc_co_u32_e32 v1, vcc, 0, v17, vcc
	global_load_dword v28, v[0:1], off nt
	v_add_co_u32_e32 v0, vcc, 0x6c000, v16
	s_nop 1
	v_addc_co_u32_e32 v1, vcc, 0, v17, vcc
	global_load_dword v29, v[0:1], off nt
	v_add_co_u32_e32 v0, vcc, 0x70000, v16
	s_nop 1
	v_addc_co_u32_e32 v1, vcc, 0, v17, vcc
	global_load_dword v30, v[0:1], off nt
	v_add_co_u32_e32 v0, vcc, 0x74000, v16
	s_nop 1
	v_addc_co_u32_e32 v1, vcc, 0, v17, vcc
	global_load_dword v31, v[0:1], off nt
	v_add_co_u32_e32 v0, vcc, 0x78000, v16
	s_nop 1
	v_addc_co_u32_e32 v1, vcc, 0, v17, vcc
	global_load_dword v18, v[0:1], off nt
	v_add_co_u32_e32 v0, vcc, 0x7c000, v16
	s_nop 1
	v_addc_co_u32_e32 v1, vcc, 0, v17, vcc
	global_load_dword v20, v[0:1], off nt
	ds_read_b128 v[0:3], v47 offset:32768
	v_lshl_add_u64 v[16:17], v[16:17], 0, s[24:25]
	s_waitcnt vmcnt(31) lgkmcnt(0)
	v_fmac_f32_e32 v19, v72, v0
	s_waitcnt vmcnt(30)
	v_fmac_f32_e32 v19, v74, v1
	s_waitcnt vmcnt(29)
	v_fmac_f32_e32 v19, v76, v2
	s_waitcnt vmcnt(28)
	v_fmac_f32_e32 v19, v78, v3
	ds_read_b128 v[0:3], v47 offset:32784
	s_waitcnt vmcnt(27) lgkmcnt(0)
	v_fmac_f32_e32 v19, v60, v0
	s_waitcnt vmcnt(26)
	v_fmac_f32_e32 v19, v62, v1
	s_waitcnt vmcnt(25)
	v_fmac_f32_e32 v19, v64, v2
	s_waitcnt vmcnt(24)
	v_fmac_f32_e32 v19, v68, v3
	ds_read_b128 v[0:3], v47 offset:32800
	ds_read_b128 v[80:83], v47
	ds_read_b128 v[84:87], v47 offset:16
	ds_read_b96 v[4:6], v47 offset:32
	ds_read_b128 v[88:91], v47 offset:4096
	s_waitcnt lgkmcnt(3)
	v_mov_b32_e32 v10, v80
	s_waitcnt vmcnt(23)
	v_fmac_f32_e32 v19, v66, v0
	s_waitcnt lgkmcnt(0)
	v_mov_b32_e32 v11, v88
	v_pk_fma_f32 v[8:9], v[72:73], v[10:11], v[8:9] op_sel_hi:[0,1,1]
	v_mov_b32_e32 v88, v81
	v_pk_fma_f32 v[8:9], v[74:75], v[88:89], v[8:9] op_sel_hi:[0,1,1]
	v_mov_b32_e32 v10, v82
	v_mov_b32_e32 v11, v90
	v_pk_fma_f32 v[8:9], v[76:77], v[10:11], v[8:9] op_sel_hi:[0,1,1]
	v_mov_b32_e32 v90, v83
	v_pk_fma_f32 v[80:81], v[78:79], v[90:91], v[8:9] op_sel_hi:[0,1,1]
	ds_read_b128 v[8:11], v47 offset:4112
	v_mov_b32_e32 v82, v84
	s_waitcnt vmcnt(22)
	v_fmac_f32_e32 v19, v70, v1
	s_waitcnt vmcnt(21)
	v_fmac_f32_e32 v19, v42, v2
	s_waitcnt vmcnt(20)
	v_fmac_f32_e32 v19, v40, v3
	s_waitcnt lgkmcnt(0)
	v_mov_b32_e32 v83, v8
	v_pk_fma_f32 v[80:81], v[60:61], v[82:83], v[80:81] op_sel_hi:[0,1,1]
	v_mov_b32_e32 v8, v85
	v_pk_fma_f32 v[8:9], v[62:63], v[8:9], v[80:81] op_sel_hi:[0,1,1]
	v_mov_b32_e32 v80, v86
	v_mov_b32_e32 v81, v10
	v_pk_fma_f32 v[8:9], v[64:65], v[80:81], v[8:9] op_sel_hi:[0,1,1]
	v_mov_b32_e32 v10, v87
	v_pk_fma_f32 v[80:81], v[68:69], v[10:11], v[8:9] op_sel_hi:[0,1,1]
	ds_read_b96 v[8:10], v47 offset:4128
	v_mov_b32_e32 v82, v4
	v_add_u32_e32 v89, 0x604c, v47
	s_waitcnt lgkmcnt(0)
	v_mov_b32_e32 v83, v8
	v_pk_fma_f32 v[80:81], v[66:67], v[82:83], v[80:81] op_sel_hi:[0,1,1]
	v_mov_b32_e32 v8, v5
	v_pk_fma_f32 v[8:9], v[70:71], v[8:9], v[80:81] op_sel_hi:[0,1,1]
	ds_read_b128 v[80:83], v47 offset:8192
	ds_read_b128 v[84:87], v47 offset:12288
	s_waitcnt lgkmcnt(1)
	v_mov_b32_e32 v4, v80
	s_waitcnt lgkmcnt(0)
	v_mov_b32_e32 v5, v84
	v_pk_fma_f32 v[4:5], v[72:73], v[4:5], v[32:33] op_sel_hi:[0,1,1]
	v_mov_b32_e32 v84, v81
	v_pk_fma_f32 v[4:5], v[74:75], v[84:85], v[4:5] op_sel_hi:[0,1,1]
	v_mov_b32_e32 v32, v82
	v_mov_b32_e32 v33, v86
	v_pk_fma_f32 v[4:5], v[76:77], v[32:33], v[4:5] op_sel_hi:[0,1,1]
	v_mov_b32_e32 v86, v83
	v_pk_fma_f32 v[4:5], v[78:79], v[86:87], v[4:5] op_sel_hi:[0,1,1]
	ds_read_b128 v[80:83], v47 offset:8208
	ds_read_b128 v[84:87], v47 offset:12304
	s_waitcnt lgkmcnt(1)
	v_mov_b32_e32 v32, v80
	s_waitcnt lgkmcnt(0)
	v_mov_b32_e32 v33, v84
	v_pk_fma_f32 v[4:5], v[60:61], v[32:33], v[4:5] op_sel_hi:[0,1,1]
	v_mov_b32_e32 v84, v81
	v_pk_fma_f32 v[4:5], v[62:63], v[84:85], v[4:5] op_sel_hi:[0,1,1]
	v_mov_b32_e32 v32, v82
	v_mov_b32_e32 v33, v86
	v_pk_fma_f32 v[4:5], v[64:65], v[32:33], v[4:5] op_sel_hi:[0,1,1]
	v_mov_b32_e32 v86, v83
	v_pk_fma_f32 v[4:5], v[68:69], v[86:87], v[4:5] op_sel_hi:[0,1,1]
	ds_read_b96 v[86:88], v47 offset:8224
	ds_read_b96 v[90:92], v47 offset:12320
	s_waitcnt lgkmcnt(1)
	v_mov_b32_e32 v32, v86
	s_waitcnt lgkmcnt(0)
	v_mov_b32_e32 v33, v90
	v_mov_b32_e32 v90, v87
	ds_read_b128 v[80:83], v47 offset:16384
	ds_read_b128 v[84:87], v47 offset:20480
	v_pk_fma_f32 v[4:5], v[66:67], v[32:33], v[4:5] op_sel_hi:[0,1,1]
	v_pk_fma_f32 v[4:5], v[70:71], v[90:91], v[4:5] op_sel_hi:[0,1,1]
	v_add_u32_e32 v90, 0x704c, v47
	s_waitcnt lgkmcnt(1)
	v_mov_b32_e32 v32, v80
	s_waitcnt lgkmcnt(0)
	v_mov_b32_e32 v33, v84
	v_pk_fma_f32 v[32:33], v[72:73], v[32:33], v[34:35] op_sel_hi:[0,1,1]
	v_mov_b32_e32 v84, v81
	v_pk_fma_f32 v[32:33], v[74:75], v[84:85], v[32:33] op_sel_hi:[0,1,1]
	v_mov_b32_e32 v34, v82
	v_mov_b32_e32 v35, v86
	v_pk_fma_f32 v[32:33], v[76:77], v[34:35], v[32:33] op_sel_hi:[0,1,1]
	v_mov_b32_e32 v86, v83
	v_pk_fma_f32 v[84:85], v[78:79], v[86:87], v[32:33] op_sel_hi:[0,1,1]
	ds_read_b128 v[32:35], v47 offset:16400
	ds_read_b128 v[80:83], v47 offset:20496
	ds_read_b96 v[94:96], v47 offset:16416
	ds_read_b96 v[98:100], v47 offset:20512
	s_waitcnt lgkmcnt(3)
	v_mov_b32_e32 v86, v32
	s_waitcnt lgkmcnt(2)
	v_mov_b32_e32 v87, v80
	v_pk_fma_f32 v[84:85], v[60:61], v[86:87], v[84:85] op_sel_hi:[0,1,1]
	v_mov_b32_e32 v80, v33
	v_pk_fma_f32 v[32:33], v[62:63], v[80:81], v[84:85] op_sel_hi:[0,1,1]
	v_mov_b32_e32 v80, v34
	v_mov_b32_e32 v81, v82
	v_pk_fma_f32 v[32:33], v[64:65], v[80:81], v[32:33] op_sel_hi:[0,1,1]
	v_mov_b32_e32 v82, v35
	v_pk_fma_f32 v[32:33], v[68:69], v[82:83], v[32:33] op_sel_hi:[0,1,1]
	ds_read_b128 v[80:83], v47 offset:24576
	ds_read_b128 v[84:87], v47 offset:28672
	s_waitcnt lgkmcnt(3)
	v_mov_b32_e32 v34, v94
	s_waitcnt lgkmcnt(2)
	v_mov_b32_e32 v35, v98
	v_pk_fma_f32 v[32:33], v[66:67], v[34:35], v[32:33] op_sel_hi:[0,1,1]
	v_mov_b32_e32 v98, v95
	v_pk_fma_f32 v[34:35], v[70:71], v[98:99], v[32:33] op_sel_hi:[0,1,1]
	s_waitcnt lgkmcnt(1)
	v_mov_b32_e32 v32, v80
	s_waitcnt lgkmcnt(0)
	v_mov_b32_e32 v33, v84
	v_pk_fma_f32 v[32:33], v[72:73], v[32:33], v[36:37] op_sel_hi:[0,1,1]
	v_mov_b32_e32 v84, v81
	v_pk_fma_f32 v[32:33], v[74:75], v[84:85], v[32:33] op_sel_hi:[0,1,1]
	v_mov_b32_e32 v36, v82
	v_mov_b32_e32 v37, v86
	v_pk_fma_f32 v[32:33], v[76:77], v[36:37], v[32:33] op_sel_hi:[0,1,1]
	v_mov_b32_e32 v86, v83
	v_pk_fma_f32 v[32:33], v[78:79], v[86:87], v[32:33] op_sel_hi:[0,1,1]
	ds_read_b128 v[72:75], v47 offset:24592
	ds_read_b128 v[76:79], v47 offset:28688
	v_add_u32_e32 v84, 0x104c, v47
	v_add_u32_e32 v85, 0x204c, v47
	v_add_u32_e32 v86, 0x304c, v47
	s_waitcnt lgkmcnt(1)
	v_mov_b32_e32 v36, v72
	s_waitcnt lgkmcnt(0)
	v_mov_b32_e32 v37, v76
	v_pk_fma_f32 v[32:33], v[60:61], v[36:37], v[32:33] op_sel_hi:[0,1,1]
	v_mov_b32_e32 v76, v73
	v_pk_fma_f32 v[32:33], v[62:63], v[76:77], v[32:33] op_sel_hi:[0,1,1]
	v_mov_b32_e32 v36, v74
	ds_read_b96 v[60:62], v47 offset:24608
	ds_read_b96 v[72:74], v47 offset:28704
	v_mov_b32_e32 v37, v78
	v_pk_fma_f32 v[32:33], v[64:65], v[36:37], v[32:33] op_sel_hi:[0,1,1]
	v_mov_b32_e32 v64, v6
	s_waitcnt lgkmcnt(1)
	v_mov_b32_e32 v36, v60
	s_waitcnt lgkmcnt(0)
	v_mov_b32_e32 v37, v72
	v_mov_b32_e32 v72, v61
	v_mov_b32_e32 v0, v62
	ds_read_b128 v[60:63], v47 offset:32816
	v_mov_b32_e32 v65, v10
	v_add_u32_e32 v6, 0x102c, v47
	v_pk_fma_f32 v[2:3], v[42:43], v[64:65], v[8:9] op_sel_hi:[0,1,1]
	v_mov_b32_e32 v78, v75
	s_waitcnt vmcnt(19) lgkmcnt(0)
	v_fmac_f32_e32 v19, v46, v60
	s_waitcnt vmcnt(18)
	v_fmac_f32_e32 v19, v44, v61
	s_waitcnt vmcnt(17)
	v_fmac_f32_e32 v19, v50, v62
	s_waitcnt vmcnt(16)
	v_fmac_f32_e32 v19, v48, v63
	ds_read_b128 v[60:63], v47 offset:32832
	v_pk_fma_f32 v[32:33], v[68:69], v[78:79], v[32:33] op_sel_hi:[0,1,1]
	v_pk_fma_f32 v[32:33], v[66:67], v[36:37], v[32:33] op_sel_hi:[0,1,1]
	v_pk_fma_f32 v[36:37], v[70:71], v[72:73], v[32:33] op_sel_hi:[0,1,1]
	v_add_u32_e32 v70, 0x103c, v47
	s_waitcnt vmcnt(15) lgkmcnt(0)
	v_fmac_f32_e32 v19, v54, v60
	s_waitcnt vmcnt(14)
	v_fmac_f32_e32 v19, v52, v61
	ds_read2_b32 v[8:9], v47 offset0:11 offset1:12
	ds_read2_b32 v[60:61], v6 offset1:1
	s_waitcnt vmcnt(13)
	v_fmac_f32_e32 v19, v58, v62
	s_waitcnt vmcnt(12)
	v_fmac_f32_e32 v19, v56, v63
	v_add_u32_e32 v77, 0x1044, v47
	s_waitcnt lgkmcnt(1)
	v_mov_b32_e32 v62, v8
	s_waitcnt lgkmcnt(0)
	v_mov_b32_e32 v63, v60
	v_pk_fma_f32 v[2:3], v[40:41], v[62:63], v[2:3] op_sel_hi:[0,1,1]
	v_mov_b32_e32 v60, v9
	v_pk_fma_f32 v[2:3], v[46:47], v[60:61], v[2:3] op_sel_hi:[0,1,1]
	ds_read2_b32 v[8:9], v47 offset0:13 offset1:14
	ds_read2_b32 v[60:61], v55 offset1:1
	v_mov_b32_e32 v32, v88
	v_mov_b32_e32 v33, v92
	v_add_u32_e32 v71, 0x203c, v47
	s_waitcnt lgkmcnt(1)
	v_mov_b32_e32 v62, v8
	s_waitcnt lgkmcnt(0)
	v_mov_b32_e32 v63, v60
	v_pk_fma_f32 v[2:3], v[44:45], v[62:63], v[2:3] op_sel_hi:[0,1,1]
	v_mov_b32_e32 v60, v9
	v_pk_fma_f32 v[2:3], v[50:51], v[60:61], v[2:3] op_sel_hi:[0,1,1]
	ds_read2_b32 v[8:9], v47 offset0:15 offset1:16
	ds_read2_b32 v[60:61], v70 offset1:1
	v_add_u32_e32 v72, 0x303c, v47
	v_add_u32_e32 v78, 0x2044, v47
	v_add_u32_e32 v79, 0x3044, v47
	s_waitcnt lgkmcnt(1)
	v_mov_b32_e32 v62, v8
	s_waitcnt lgkmcnt(0)
	v_mov_b32_e32 v63, v60
	v_pk_fma_f32 v[2:3], v[48:49], v[62:63], v[2:3] op_sel_hi:[0,1,1]
	v_mov_b32_e32 v60, v9
	v_pk_fma_f32 v[2:3], v[54:55], v[60:61], v[2:3] op_sel_hi:[0,1,1]
	ds_read2_b32 v[8:9], v47 offset0:17 offset1:18
	ds_read2_b32 v[60:61], v77 offset1:1
	v_mov_b32_e32 v10, v96
	v_mov_b32_e32 v11, v100
	v_add_u32_e32 v66, 0x4034, v47
	s_waitcnt lgkmcnt(1)
	v_mov_b32_e32 v62, v8
	s_waitcnt lgkmcnt(0)
	v_mov_b32_e32 v63, v60
	v_pk_fma_f32 v[2:3], v[52:53], v[62:63], v[2:3] op_sel_hi:[0,1,1]
	v_mov_b32_e32 v60, v9
	v_pk_fma_f32 v[2:3], v[58:59], v[60:61], v[2:3] op_sel_hi:[0,1,1]
	ds_read2_b32 v[8:9], v47 offset0:19 offset1:20
	ds_read2_b32 v[60:61], v84 offset1:1
	v_add_u32_e32 v67, 0x5034, v47
	v_add_u32_e32 v73, 0x403c, v47
	v_mov_b32_e32 v1, v74
	s_waitcnt lgkmcnt(1)
	v_mov_b32_e32 v62, v8
	s_waitcnt lgkmcnt(0)
	v_mov_b32_e32 v63, v60
	v_pk_fma_f32 v[2:3], v[56:57], v[62:63], v[2:3] op_sel_hi:[0,1,1]
	v_mov_b32_e32 v60, v9
	s_waitcnt vmcnt(11)
	v_pk_fma_f32 v[8:9], v[38:39], v[60:61], v[2:3] op_sel_hi:[0,1,1]
	v_pk_fma_f32 v[2:3], v[42:43], v[32:33], v[4:5] op_sel_hi:[0,1,1]
	ds_read2_b32 v[4:5], v39 offset1:1
	ds_read2_b32 v[32:33], v41 offset1:1
	v_add_u32_e32 v74, 0x503c, v47
	v_add_u32_e32 v80, 0x4044, v47
	v_add_u32_e32 v81, 0x5044, v47
	s_waitcnt lgkmcnt(1)
	v_mov_b32_e32 v60, v4
	s_waitcnt lgkmcnt(0)
	v_mov_b32_e32 v61, v32
	v_pk_fma_f32 v[2:3], v[40:41], v[60:61], v[2:3] op_sel_hi:[0,1,1]
	v_mov_b32_e32 v32, v5
	v_pk_fma_f32 v[2:3], v[46:47], v[32:33], v[2:3] op_sel_hi:[0,1,1]
	ds_read2_b32 v[4:5], v57 offset1:1
	ds_read2_b32 v[32:33], v59 offset1:1
	v_add_u32_e32 v87, 0x404c, v47
	v_add_u32_e32 v88, 0x504c, v47
	v_pk_fma_f32 v[0:1], v[42:43], v[0:1], v[36:37] op_sel_hi:[0,1,1]
	s_waitcnt lgkmcnt(1)
	v_mov_b32_e32 v60, v4
	s_waitcnt lgkmcnt(0)
	v_mov_b32_e32 v61, v32
	v_pk_fma_f32 v[2:3], v[44:45], v[60:61], v[2:3] op_sel_hi:[0,1,1]
	v_mov_b32_e32 v32, v5
	v_pk_fma_f32 v[2:3], v[50:51], v[32:33], v[2:3] op_sel_hi:[0,1,1]
	ds_read2_b32 v[4:5], v71 offset1:1
	ds_read2_b32 v[32:33], v72 offset1:1
	v_add_u32_e32 v68, 0x6034, v47
	v_add_u32_e32 v69, 0x7034, v47
	v_add_u32_e32 v75, 0x603c, v47
	s_waitcnt lgkmcnt(1)
	v_mov_b32_e32 v60, v4
	s_waitcnt lgkmcnt(0)
	v_mov_b32_e32 v61, v32
	v_pk_fma_f32 v[2:3], v[48:49], v[60:61], v[2:3] op_sel_hi:[0,1,1]
	v_mov_b32_e32 v32, v5
	v_pk_fma_f32 v[2:3], v[54:55], v[32:33], v[2:3] op_sel_hi:[0,1,1]
	ds_read2_b32 v[4:5], v78 offset1:1
	ds_read2_b32 v[32:33], v79 offset1:1
	v_add_u32_e32 v76, 0x703c, v47
	v_add_u32_e32 v82, 0x6044, v47
	v_add_u32_e32 v83, 0x7044, v47
	s_waitcnt lgkmcnt(1)
	v_mov_b32_e32 v60, v4
	s_waitcnt lgkmcnt(0)
	v_mov_b32_e32 v61, v32
	v_pk_fma_f32 v[2:3], v[52:53], v[60:61], v[2:3] op_sel_hi:[0,1,1]
	v_mov_b32_e32 v32, v5
	v_pk_fma_f32 v[2:3], v[58:59], v[32:33], v[2:3] op_sel_hi:[0,1,1]
	ds_read2_b32 v[4:5], v85 offset1:1
	ds_read2_b32 v[32:33], v86 offset1:1
	v_add_u32_e32 v62, 0x4068, v47
	v_add_u32_e32 v63, 0x5068, v47
	v_add_u32_e32 v64, 0x6068, v47
	s_waitcnt lgkmcnt(1)
	v_mov_b32_e32 v60, v4
	s_waitcnt lgkmcnt(0)
	v_mov_b32_e32 v61, v32
	v_pk_fma_f32 v[2:3], v[56:57], v[60:61], v[2:3] op_sel_hi:[0,1,1]
	v_mov_b32_e32 v32, v5
	v_pk_fma_f32 v[32:33], v[38:39], v[32:33], v[2:3] op_sel_hi:[0,1,1]
	v_pk_fma_f32 v[2:3], v[42:43], v[10:11], v[34:35] op_sel_hi:[0,1,1]
	ds_read2_b32 v[4:5], v43 offset1:1
	ds_read2_b32 v[10:11], v49 offset1:1
	v_add_u32_e32 v60, 0x2068, v47
	v_add_u32_e32 v61, 0x3068, v47
	v_add_u32_e32 v65, 0x7068, v47
	s_waitcnt lgkmcnt(1)
	v_mov_b32_e32 v34, v4
	s_waitcnt lgkmcnt(0)
	v_mov_b32_e32 v35, v10
	v_pk_fma_f32 v[2:3], v[40:41], v[34:35], v[2:3] op_sel_hi:[0,1,1]
	v_mov_b32_e32 v10, v5
	v_pk_fma_f32 v[2:3], v[46:47], v[10:11], v[2:3] op_sel_hi:[0,1,1]
	ds_read2_b32 v[4:5], v66 offset1:1
	ds_read2_b32 v[10:11], v67 offset1:1
	s_waitcnt lgkmcnt(1)
	v_mov_b32_e32 v34, v4
	s_waitcnt lgkmcnt(0)
	v_mov_b32_e32 v35, v10
	v_pk_fma_f32 v[2:3], v[44:45], v[34:35], v[2:3] op_sel_hi:[0,1,1]
	v_mov_b32_e32 v10, v5
	v_pk_fma_f32 v[2:3], v[50:51], v[10:11], v[2:3] op_sel_hi:[0,1,1]
	ds_read2_b32 v[4:5], v73 offset1:1
	ds_read2_b32 v[10:11], v74 offset1:1
	s_waitcnt lgkmcnt(1)
	v_mov_b32_e32 v34, v4
	s_waitcnt lgkmcnt(0)
	v_mov_b32_e32 v35, v10
	v_pk_fma_f32 v[2:3], v[48:49], v[34:35], v[2:3] op_sel_hi:[0,1,1]
	v_mov_b32_e32 v10, v5
	v_pk_fma_f32 v[2:3], v[54:55], v[10:11], v[2:3] op_sel_hi:[0,1,1]
	ds_read2_b32 v[4:5], v80 offset1:1
	ds_read2_b32 v[10:11], v81 offset1:1
	s_waitcnt lgkmcnt(1)
	v_mov_b32_e32 v34, v4
	s_waitcnt lgkmcnt(0)
	v_mov_b32_e32 v35, v10
	v_pk_fma_f32 v[2:3], v[52:53], v[34:35], v[2:3] op_sel_hi:[0,1,1]
	v_mov_b32_e32 v10, v5
	v_pk_fma_f32 v[2:3], v[58:59], v[10:11], v[2:3] op_sel_hi:[0,1,1]
	ds_read2_b32 v[4:5], v87 offset1:1
	ds_read2_b32 v[10:11], v88 offset1:1
	s_waitcnt lgkmcnt(1)
	v_mov_b32_e32 v34, v4
	s_waitcnt lgkmcnt(0)
	v_mov_b32_e32 v35, v10
	v_pk_fma_f32 v[2:3], v[56:57], v[34:35], v[2:3] op_sel_hi:[0,1,1]
	v_mov_b32_e32 v10, v5
	v_pk_fma_f32 v[34:35], v[38:39], v[10:11], v[2:3] op_sel_hi:[0,1,1]
	ds_read2_b32 v[2:3], v51 offset1:1
	ds_read2_b32 v[4:5], v53 offset1:1
	s_waitcnt lgkmcnt(1)
	v_mov_b32_e32 v10, v2
	s_waitcnt lgkmcnt(0)
	v_mov_b32_e32 v11, v4
	v_pk_fma_f32 v[0:1], v[40:41], v[10:11], v[0:1] op_sel_hi:[0,1,1]
	v_mov_b32_e32 v4, v3
	v_pk_fma_f32 v[0:1], v[46:47], v[4:5], v[0:1] op_sel_hi:[0,1,1]
	ds_read2_b32 v[2:3], v68 offset1:1
	ds_read2_b32 v[4:5], v69 offset1:1
	v_add_u32_e32 v46, 0x3058, v47
	s_waitcnt lgkmcnt(1)
	v_mov_b32_e32 v10, v2
	s_waitcnt lgkmcnt(0)
	v_mov_b32_e32 v11, v4
	v_pk_fma_f32 v[0:1], v[44:45], v[10:11], v[0:1] op_sel_hi:[0,1,1]
	v_mov_b32_e32 v4, v3
	v_pk_fma_f32 v[0:1], v[50:51], v[4:5], v[0:1] op_sel_hi:[0,1,1]
	ds_read2_b32 v[2:3], v75 offset1:1
	ds_read2_b32 v[4:5], v76 offset1:1
	v_add_u32_e32 v44, 0x2058, v47
	s_waitcnt lgkmcnt(1)
	v_mov_b32_e32 v10, v2
	s_waitcnt lgkmcnt(0)
	v_mov_b32_e32 v11, v4
	v_pk_fma_f32 v[0:1], v[48:49], v[10:11], v[0:1] op_sel_hi:[0,1,1]
	v_mov_b32_e32 v4, v3
	v_pk_fma_f32 v[0:1], v[54:55], v[4:5], v[0:1] op_sel_hi:[0,1,1]
	ds_read2_b32 v[2:3], v82 offset1:1
	ds_read2_b32 v[4:5], v83 offset1:1
	s_waitcnt lgkmcnt(1)
	v_mov_b32_e32 v10, v2
	s_waitcnt lgkmcnt(0)
	v_mov_b32_e32 v11, v4
	v_pk_fma_f32 v[0:1], v[52:53], v[10:11], v[0:1] op_sel_hi:[0,1,1]
	v_mov_b32_e32 v4, v3
	v_pk_fma_f32 v[0:1], v[58:59], v[4:5], v[0:1] op_sel_hi:[0,1,1]
	ds_read2_b32 v[2:3], v89 offset1:1
	ds_read2_b32 v[4:5], v90 offset1:1
	v_add_u32_e32 v58, 0x6058, v47
	v_add_u32_e32 v59, 0x7058, v47
	s_waitcnt lgkmcnt(1)
	v_mov_b32_e32 v10, v2
	s_waitcnt lgkmcnt(0)
	v_mov_b32_e32 v11, v4
	v_pk_fma_f32 v[0:1], v[56:57], v[10:11], v[0:1] op_sel_hi:[0,1,1]
	v_mov_b32_e32 v4, v3
	v_pk_fma_f32 v[4:5], v[38:39], v[4:5], v[0:1] op_sel_hi:[0,1,1]
	ds_read_b32 v42, v47 offset:84
	ds_read_b32 v43, v47 offset:4180
	ds_read_b32 v40, v47 offset:8276
	ds_read_b32 v41, v47 offset:12372
	ds_read_b32 v36, v47 offset:16468
	ds_read_b32 v37, v47 offset:20564
	ds_read_b32 v10, v47 offset:24660
	ds_read_b32 v11, v47 offset:28756
	ds_read_b128 v[0:3], v47 offset:32848
	s_waitcnt vmcnt(10)
	v_mov_b32_e32 v39, v24
	s_waitcnt lgkmcnt(5)
	v_pk_fma_f32 v[32:33], v[24:25], v[40:41], v[32:33] op_sel_hi:[0,1,1]
	v_add_u32_e32 v56, 0x4058, v47
	v_add_u32_e32 v57, 0x5058, v47
	s_waitcnt lgkmcnt(0)
	v_pk_mul_f32 v[0:1], v[38:39], v[0:1]
	v_add_u32_e32 v38, 0x1068, v47
	v_add_f32_e32 v0, v19, v0
	v_add_f32_e32 v6, v0, v1
	s_waitcnt vmcnt(8)
	v_pk_mul_f32 v[0:1], v[22:23], v[2:3]
	v_add_u32_e32 v19, 0x1058, v47
	v_add_f32_e32 v0, v6, v0
	v_add_f32_e32 v6, v0, v1
	ds_read_b128 v[0:3], v47 offset:32864
	v_pk_fma_f32 v[4:5], v[24:25], v[10:11], v[4:5] op_sel_hi:[0,1,1]
	s_waitcnt vmcnt(6) lgkmcnt(0)
	v_pk_mul_f32 v[0:1], v[26:27], v[0:1]
	s_nop 0
	v_add_f32_e32 v0, v6, v0
	v_add_f32_e32 v6, v0, v1
	s_waitcnt vmcnt(4)
	v_pk_mul_f32 v[0:1], v[28:29], v[2:3]
	s_nop 0
	v_add_f32_e32 v0, v6, v0
	v_add_f32_e32 v6, v0, v1
	ds_read_b128 v[0:3], v47 offset:32880
	ds_read2_b64 v[48:51], v47 offset0:11 offset1:12
	ds_read2_b64 v[52:55], v19 offset1:1
	s_waitcnt vmcnt(2) lgkmcnt(2)
	v_pk_mul_f32 v[0:1], v[30:31], v[0:1]
	s_nop 0
	v_add_f32_e32 v0, v6, v0
	v_add_f32_e32 v39, v0, v1
	v_pk_fma_f32 v[0:1], v[24:25], v[42:43], v[8:9] op_sel_hi:[0,1,1]
	s_waitcnt lgkmcnt(1)
	v_mov_b32_e32 v8, v48
	s_waitcnt lgkmcnt(0)
	v_mov_b32_e32 v9, v52
	v_pk_fma_f32 v[8:9], v[22:23], v[8:9], v[0:1] op_sel_hi:[0,1,1]
	v_mov_b32_e32 v0, v23
	v_mov_b32_e32 v52, v49
	v_pk_fma_f32 v[8:9], v[0:1], v[52:53], v[8:9] op_sel_hi:[0,1,1]
	v_mov_b32_e32 v42, v50
	v_mov_b32_e32 v43, v54
	v_pk_fma_f32 v[8:9], v[26:27], v[42:43], v[8:9] op_sel_hi:[0,1,1]
	v_mov_b32_e32 v6, v27
	v_mov_b32_e32 v54, v51
	v_pk_fma_f32 v[8:9], v[6:7], v[54:55], v[8:9] op_sel_hi:[0,1,1]
	ds_read2_b64 v[48:51], v47 offset0:13 offset1:14
	ds_read2_b64 v[52:55], v38 offset1:1
	v_mov_b32_e32 v38, v29
	s_waitcnt lgkmcnt(1)
	v_mov_b32_e32 v42, v48
	s_waitcnt lgkmcnt(0)
	v_mov_b32_e32 v43, v52
	v_pk_fma_f32 v[8:9], v[28:29], v[42:43], v[8:9] op_sel_hi:[0,1,1]
	v_mov_b32_e32 v52, v49
	v_mov_b32_e32 v42, v50
	v_mov_b32_e32 v43, v54
	v_mov_b32_e32 v54, v51
	ds_read_b64 v[48:49], v47 offset:120
	ds_read_b64 v[50:51], v47 offset:4216
	v_pk_fma_f32 v[8:9], v[38:39], v[52:53], v[8:9] op_sel_hi:[0,1,1]
	v_pk_fma_f32 v[8:9], v[30:31], v[42:43], v[8:9] op_sel_hi:[0,1,1]
	v_mov_b32_e32 v42, v31
	v_pk_fma_f32 v[8:9], v[42:43], v[54:55], v[8:9] op_sel_hi:[0,1,1]
	s_waitcnt lgkmcnt(1)
	v_mov_b32_e32 v52, v48
	s_waitcnt lgkmcnt(0)
	v_mov_b32_e32 v53, v50
	s_waitcnt vmcnt(1)
	v_pk_fma_f32 v[8:9], v[18:19], v[52:53], v[8:9] op_sel_hi:[0,1,1]
	v_mov_b32_e32 v50, v49
	s_waitcnt vmcnt(0)
	v_pk_fma_f32 v[8:9], v[20:21], v[50:51], v[8:9] op_sel_hi:[0,1,1]
	ds_read2_b64 v[48:51], v44 offset1:1
	ds_read2_b64 v[52:55], v46 offset1:1
	s_waitcnt lgkmcnt(1)
	v_mov_b32_e32 v40, v48
	s_waitcnt lgkmcnt(0)
	v_mov_b32_e32 v41, v52
	v_pk_fma_f32 v[32:33], v[22:23], v[40:41], v[32:33] op_sel_hi:[0,1,1]
	v_mov_b32_e32 v52, v49
	v_pk_fma_f32 v[32:33], v[0:1], v[52:53], v[32:33] op_sel_hi:[0,1,1]
	v_mov_b32_e32 v40, v50
	v_mov_b32_e32 v41, v54
	v_pk_fma_f32 v[32:33], v[26:27], v[40:41], v[32:33] op_sel_hi:[0,1,1]
	v_mov_b32_e32 v54, v51
	v_pk_fma_f32 v[32:33], v[6:7], v[54:55], v[32:33] op_sel_hi:[0,1,1]
	ds_read2_b64 v[48:51], v60 offset1:1
	ds_read2_b64 v[52:55], v61 offset1:1
	s_waitcnt lgkmcnt(1)
	v_mov_b32_e32 v40, v48
	s_waitcnt lgkmcnt(0)
	v_mov_b32_e32 v41, v52
	v_pk_fma_f32 v[32:33], v[28:29], v[40:41], v[32:33] op_sel_hi:[0,1,1]
	v_mov_b32_e32 v52, v49
	v_pk_fma_f32 v[32:33], v[38:39], v[52:53], v[32:33] op_sel_hi:[0,1,1]
	v_mov_b32_e32 v40, v50
	v_mov_b32_e32 v41, v54
	v_pk_fma_f32 v[32:33], v[30:31], v[40:41], v[32:33] op_sel_hi:[0,1,1]
	ds_read_b64 v[40:41], v47 offset:8312
	ds_read_b64 v[48:49], v47 offset:12408
	v_mov_b32_e32 v54, v51
	v_pk_fma_f32 v[32:33], v[42:43], v[54:55], v[32:33] op_sel_hi:[0,1,1]
	s_waitcnt lgkmcnt(1)
	v_mov_b32_e32 v50, v40
	s_waitcnt lgkmcnt(0)
	v_mov_b32_e32 v51, v48
	v_pk_fma_f32 v[32:33], v[18:19], v[50:51], v[32:33] op_sel_hi:[0,1,1]
	v_mov_b32_e32 v48, v41
	v_pk_fma_f32 v[32:33], v[20:21], v[48:49], v[32:33] op_sel_hi:[0,1,1]
	v_pk_fma_f32 v[40:41], v[24:25], v[36:37], v[34:35] op_sel_hi:[0,1,1]
	ds_read2_b64 v[34:37], v56 offset1:1
	ds_read2_b64 v[48:51], v57 offset1:1
	s_waitcnt lgkmcnt(1)
	v_mov_b32_e32 v52, v34
	s_waitcnt lgkmcnt(0)
	v_mov_b32_e32 v53, v48
	v_pk_fma_f32 v[40:41], v[22:23], v[52:53], v[40:41] op_sel_hi:[0,1,1]
	v_mov_b32_e32 v48, v35
	v_pk_fma_f32 v[34:35], v[0:1], v[48:49], v[40:41] op_sel_hi:[0,1,1]
	v_mov_b32_e32 v40, v36
	v_mov_b32_e32 v41, v50
	v_pk_fma_f32 v[34:35], v[26:27], v[40:41], v[34:35] op_sel_hi:[0,1,1]
	v_mov_b32_e32 v50, v37
	v_pk_fma_f32 v[40:41], v[6:7], v[50:51], v[34:35] op_sel_hi:[0,1,1]
	ds_read2_b64 v[34:37], v62 offset1:1
	ds_read2_b64 v[48:51], v63 offset1:1
	s_waitcnt lgkmcnt(1)
	v_mov_b32_e32 v52, v34
	s_waitcnt lgkmcnt(0)
	v_mov_b32_e32 v53, v48
	v_pk_fma_f32 v[40:41], v[28:29], v[52:53], v[40:41] op_sel_hi:[0,1,1]
	v_mov_b32_e32 v48, v35
	v_pk_fma_f32 v[34:35], v[38:39], v[48:49], v[40:41] op_sel_hi:[0,1,1]
	v_mov_b32_e32 v40, v36
	v_mov_b32_e32 v41, v50
	v_pk_fma_f32 v[34:35], v[30:31], v[40:41], v[34:35] op_sel_hi:[0,1,1]
	v_mov_b32_e32 v50, v37
	ds_read_b64 v[36:37], v47 offset:16504
	ds_read_b64 v[40:41], v47 offset:20600
	v_pk_fma_f32 v[34:35], v[42:43], v[50:51], v[34:35] op_sel_hi:[0,1,1]
	s_waitcnt lgkmcnt(1)
	v_mov_b32_e32 v48, v36
	s_waitcnt lgkmcnt(0)
	v_mov_b32_e32 v49, v40
	v_pk_fma_f32 v[34:35], v[18:19], v[48:49], v[34:35] op_sel_hi:[0,1,1]
	ds_read2_b64 v[48:51], v58 offset1:1
	ds_read2_b64 v[52:55], v59 offset1:1
	v_mov_b32_e32 v40, v37
	v_pk_fma_f32 v[34:35], v[20:21], v[40:41], v[34:35] op_sel_hi:[0,1,1]
	s_waitcnt lgkmcnt(1)
	v_mov_b32_e32 v10, v48
	s_waitcnt lgkmcnt(0)
	v_mov_b32_e32 v11, v52
	v_pk_fma_f32 v[4:5], v[22:23], v[10:11], v[4:5] op_sel_hi:[0,1,1]
	v_mov_b32_e32 v52, v49
	v_pk_fma_f32 v[0:1], v[0:1], v[52:53], v[4:5] op_sel_hi:[0,1,1]
	v_mov_b32_e32 v4, v50
	v_mov_b32_e32 v5, v54
	v_pk_fma_f32 v[0:1], v[26:27], v[4:5], v[0:1] op_sel_hi:[0,1,1]
	v_mov_b32_e32 v54, v51
	v_pk_fma_f32 v[0:1], v[6:7], v[54:55], v[0:1] op_sel_hi:[0,1,1]
	ds_read2_b64 v[48:51], v64 offset1:1
	ds_read2_b64 v[52:55], v65 offset1:1
	s_waitcnt lgkmcnt(1)
	v_mov_b32_e32 v4, v48
	s_waitcnt lgkmcnt(0)
	v_mov_b32_e32 v5, v52
	v_pk_fma_f32 v[0:1], v[28:29], v[4:5], v[0:1] op_sel_hi:[0,1,1]
	v_mov_b32_e32 v52, v49
	v_pk_fma_f32 v[0:1], v[38:39], v[52:53], v[0:1] op_sel_hi:[0,1,1]
	v_mov_b32_e32 v4, v50
	v_mov_b32_e32 v5, v54
	v_pk_fma_f32 v[0:1], v[30:31], v[4:5], v[0:1] op_sel_hi:[0,1,1]
	ds_read_b64 v[4:5], v47 offset:24696
	ds_read_b64 v[10:11], v47 offset:28792
	v_mov_b32_e32 v54, v51
	v_pk_fma_f32 v[0:1], v[42:43], v[54:55], v[0:1] op_sel_hi:[0,1,1]
	v_add_u32_e32 v47, 0x80, v47
	s_waitcnt lgkmcnt(1)
	v_mov_b32_e32 v22, v4
	s_waitcnt lgkmcnt(0)
	v_mov_b32_e32 v23, v10
	v_pk_fma_f32 v[0:1], v[18:19], v[22:23], v[0:1] op_sel_hi:[0,1,1]
	v_mov_b32_e32 v10, v5
	v_mov_b32_e32 v19, v20
	v_pk_fma_f32 v[36:37], v[20:21], v[10:11], v[0:1] op_sel_hi:[0,1,1]
	v_pk_mul_f32 v[0:1], v[18:19], v[2:3]
	s_nop 0
	v_add_f32_e32 v0, v39, v0
	v_add_f32_e32 v19, v0, v1
	s_cbranch_scc0 .LBB0_292
	v_lshl_add_u32 v0, v21, 2, 0
	v_mad_u64_u32 v[2:3], s[4:5], v25, s50, v[0:1]
	v_cmp_gt_i32_e32 vcc, s51, v14
	ds_write2st64_b32 v2, v8, v9 offset0:144 offset1:145
	ds_write2st64_b32 v2, v32, v33 offset0:146 offset1:147
	ds_write2st64_b32 v2, v34, v35 offset0:148 offset1:149
	ds_write2st64_b32 v2, v36, v37 offset0:150 offset1:151
	ds_write_b32 v2, v19 offset:38912
	s_waitcnt lgkmcnt(0)
	s_barrier
	s_and_saveexec_b64 s[4:5], vcc
	s_cbranch_execz .LBB0_305
	v_max_i32_e32 v1, 64, v14
	s_add_i32 s21, s58, 0xfffff500
	v_sub_u32_e32 v1, v1, v14
	v_or_b32_e32 v6, s21, v21
	v_add_u32_e32 v1, 0x1ff, v1
	v_lshl_add_u64 v[2:3], v[6:7], 2, s[8:9]
	v_cmp_lt_u32_e32 vcc, s52, v1
	s_mov_b64 s[34:35], -1
	s_and_saveexec_b64 s[30:31], vcc
	s_cbranch_execz .LBB0_302
	v_lshrrev_b32_e32 v1, 9, v1
	v_add_u32_e32 v6, -1, v1
	v_cmp_lt_u32_e32 vcc, 1, v6
	v_mov_b64_e32 v[4:5], v[14:15]
	s_and_saveexec_b64 s[34:35], vcc
	s_cbranch_execz .LBB0_299
	v_lshrrev_b32_e32 v4, 1, v6
	v_add_u32_e32 v4, 1, v4
	v_and_b32_e32 v8, -2, v4
	s_mov_b64 s[56:57], 0
	v_mov_b64_e32 v[4:5], v[14:15]

.LBB0_306:
	s_and_b64 vcc, exec, s[4:5]
	s_cbranch_vccz .LBB0_217
	v_mov_b32_e32 v14, v228
	s_nop 0
	v_and_b32_e32 v0, 0x3ff, v14
	v_cmp_lt_u32_e32 vcc, s44, v14
	v_lshlrev_b32_e32 v6, 2, v0
	s_barrier
	s_and_saveexec_b64 s[4:5], vcc
	s_xor_b64 s[4:5], exec, s[4:5]
	v_ashrrev_i32_e32 v0, 10, v14
	v_add_u32_e32 v0, -1, v0
	v_mul_hi_i32_i24_e32 v1, 0x6000, v0
	v_mul_i32_i24_e32 v0, 0x6000, v0
	v_lshl_add_u64 v[0:1], s[10:11], 0, v[0:1]
	v_lshl_add_u64 v[0:1], v[0:1], 0, v[6:7]
	s_andn2_saveexec_b64 s[4:5], s[4:5]
	v_lshl_add_u64 v[0:1], s[74:75], 0, v[6:7]
	s_or_b64 exec, exec, s[4:5]
	global_load_dword v4, v[0:1], off nt
	v_add_u32_e32 v15, 0x200, v14
	v_and_b32_e32 v0, 0x3ff, v15
	v_cmp_lt_u32_e32 vcc, s44, v15
	v_lshlrev_b32_e32 v0, 2, v0
	s_and_saveexec_b64 s[4:5], vcc
	s_xor_b64 s[4:5], exec, s[4:5]
	v_ashrrev_i32_e32 v1, 10, v15
	v_add_u32_e32 v1, -1, v1
	v_mul_hi_i32_i24_e32 v3, 0x6000, v1
	v_mul_i32_i24_e32 v2, 0x6000, v1
	v_lshl_add_u64 v[2:3], s[10:11], 0, v[2:3]
	v_mov_b32_e32 v1, v7
	v_lshl_add_u64 v[2:3], v[2:3], 0, v[0:1]
	s_andn2_saveexec_b64 s[4:5], s[4:5]
	v_mov_b32_e32 v1, v7
	v_lshl_add_u64 v[2:3], s[74:75], 0, v[0:1]
	s_or_b64 exec, exec, s[4:5]
	global_load_dword v5, v[2:3], off nt
	v_cmp_gt_u32_e32 vcc, s45, v14
	s_and_saveexec_b64 s[4:5], vcc
	s_xor_b64 s[4:5], exec, s[4:5]
	v_add_u32_e32 v0, 0x400, v14
	v_ashrrev_i32_e32 v0, 10, v0
	v_add_u32_e32 v0, -1, v0
	v_mul_hi_i32_i24_e32 v1, 0x6000, v0
	v_mul_i32_i24_e32 v0, 0x6000, v0
	v_lshl_add_u64 v[0:1], s[10:11], 0, v[0:1]
	v_lshl_add_u64 v[0:1], v[0:1], 0, v[6:7]
	s_andn2_saveexec_b64 s[4:5], s[4:5]
	v_lshl_add_u64 v[0:1], s[74:75], 0, v[6:7]
	s_or_b64 exec, exec, s[4:5]
	global_load_dword v9, v[0:1], off nt
	v_add_u32_e32 v1, 0x600, v14
	v_and_b32_e32 v0, 0x3ff, v1
	v_cmp_lt_u32_e32 vcc, s44, v1
	v_lshlrev_b32_e32 v0, 2, v0
	s_and_saveexec_b64 s[4:5], vcc
	s_xor_b64 s[4:5], exec, s[4:5]
	v_ashrrev_i32_e32 v1, 10, v1
	v_add_u32_e32 v1, -1, v1
	v_mul_hi_i32_i24_e32 v3, 0x6000, v1
	v_mul_i32_i24_e32 v2, 0x6000, v1
	v_lshl_add_u64 v[2:3], s[10:11], 0, v[2:3]
	v_mov_b32_e32 v1, v7
	v_lshl_add_u64 v[2:3], v[2:3], 0, v[0:1]
	s_andn2_saveexec_b64 s[4:5], s[4:5]
	v_mov_b32_e32 v1, v7
	v_lshl_add_u64 v[2:3], s[74:75], 0, v[0:1]
	s_or_b64 exec, exec, s[4:5]
	global_load_dword v10, v[2:3], off nt
	v_add_u32_e32 v2, 0x800, v14
	v_cmp_lt_u32_e32 vcc, s44, v2
	s_and_saveexec_b64 s[4:5], vcc
	s_xor_b64 s[4:5], exec, s[4:5]
	v_ashrrev_i32_e32 v0, 10, v2
	v_add_u32_e32 v0, -1, v0
	v_mul_hi_i32_i24_e32 v1, 0x6000, v0
	v_mul_i32_i24_e32 v0, 0x6000, v0
	v_lshl_add_u64 v[0:1], s[10:11], 0, v[0:1]
	v_lshl_add_u64 v[0:1], v[0:1], 0, v[6:7]
	s_andn2_saveexec_b64 s[4:5], s[4:5]
	v_lshl_add_u64 v[0:1], s[74:75], 0, v[6:7]
	s_or_b64 exec, exec, s[4:5]
	global_load_dword v11, v[0:1], off nt
	v_add_u32_e32 v1, 0xa00, v14
	v_and_b32_e32 v0, 0x3ff, v1
	v_cmp_lt_u32_e32 vcc, s44, v1
	v_lshlrev_b32_e32 v0, 2, v0
	s_and_saveexec_b64 s[4:5], vcc
	s_xor_b64 s[4:5], exec, s[4:5]
	v_ashrrev_i32_e32 v1, 10, v1
	v_add_u32_e32 v1, -1, v1
	v_mul_hi_i32_i24_e32 v3, 0x6000, v1
	v_mul_i32_i24_e32 v2, 0x6000, v1
	v_lshl_add_u64 v[2:3], s[10:11], 0, v[2:3]
	v_mov_b32_e32 v1, v7
	v_lshl_add_u64 v[2:3], v[2:3], 0, v[0:1]
	s_andn2_saveexec_b64 s[4:5], s[4:5]
	v_mov_b32_e32 v1, v7
	v_lshl_add_u64 v[2:3], s[74:75], 0, v[0:1]
	s_or_b64 exec, exec, s[4:5]
	global_load_dword v16, v[2:3], off nt
	v_add_u32_e32 v2, 0xc00, v14
	v_cmp_lt_u32_e32 vcc, s44, v2
	s_and_saveexec_b64 s[4:5], vcc
	s_xor_b64 s[4:5], exec, s[4:5]
	v_ashrrev_i32_e32 v0, 10, v2
	v_add_u32_e32 v0, -1, v0
	v_mul_hi_i32_i24_e32 v1, 0x6000, v0
	v_mul_i32_i24_e32 v0, 0x6000, v0
	v_lshl_add_u64 v[0:1], s[10:11], 0, v[0:1]
	v_lshl_add_u64 v[0:1], v[0:1], 0, v[6:7]
	s_andn2_saveexec_b64 s[4:5], s[4:5]
	v_lshl_add_u64 v[0:1], s[74:75], 0, v[6:7]
	s_or_b64 exec, exec, s[4:5]
	global_load_dword v17, v[0:1], off nt
	v_add_u32_e32 v1, 0xe00, v14
	v_and_b32_e32 v0, 0x3ff, v1
	v_cmp_lt_u32_e32 vcc, s44, v1
	v_lshlrev_b32_e32 v0, 2, v0
	s_and_saveexec_b64 s[4:5], vcc
	s_xor_b64 s[4:5], exec, s[4:5]
	v_ashrrev_i32_e32 v1, 10, v1
	v_add_u32_e32 v1, -1, v1
	v_mul_hi_i32_i24_e32 v3, 0x6000, v1
	v_mul_i32_i24_e32 v2, 0x6000, v1
	v_lshl_add_u64 v[2:3], s[10:11], 0, v[2:3]
	v_mov_b32_e32 v1, v7
	v_lshl_add_u64 v[2:3], v[2:3], 0, v[0:1]
	s_andn2_saveexec_b64 s[4:5], s[4:5]
	v_mov_b32_e32 v1, v7
	v_lshl_add_u64 v[2:3], s[74:75], 0, v[0:1]
	s_or_b64 exec, exec, s[4:5]
	global_load_dword v18, v[2:3], off nt
	v_add_u32_e32 v2, 0x1000, v14
	v_cmp_lt_u32_e32 vcc, s44, v2
	s_and_saveexec_b64 s[4:5], vcc
	s_xor_b64 s[4:5], exec, s[4:5]
	v_ashrrev_i32_e32 v0, 10, v2
	v_add_u32_e32 v0, -1, v0
	v_mul_hi_i32_i24_e32 v1, 0x6000, v0
	v_mul_i32_i24_e32 v0, 0x6000, v0
	v_lshl_add_u64 v[0:1], s[10:11], 0, v[0:1]
	v_lshl_add_u64 v[0:1], v[0:1], 0, v[6:7]
	s_andn2_saveexec_b64 s[4:5], s[4:5]
	v_lshl_add_u64 v[0:1], s[74:75], 0, v[6:7]
	s_or_b64 exec, exec, s[4:5]
	global_load_dword v19, v[0:1], off nt
	v_add_u32_e32 v1, 0x1200, v14
	v_and_b32_e32 v0, 0x3ff, v1
	v_cmp_lt_u32_e32 vcc, s44, v1
	v_lshlrev_b32_e32 v0, 2, v0
	s_and_saveexec_b64 s[4:5], vcc
	s_xor_b64 s[4:5], exec, s[4:5]
	v_ashrrev_i32_e32 v1, 10, v1
	v_add_u32_e32 v1, -1, v1
	v_mul_hi_i32_i24_e32 v3, 0x6000, v1
	v_mul_i32_i24_e32 v2, 0x6000, v1
	v_lshl_add_u64 v[2:3], s[10:11], 0, v[2:3]
	v_mov_b32_e32 v1, v7
	v_lshl_add_u64 v[2:3], v[2:3], 0, v[0:1]
	s_andn2_saveexec_b64 s[4:5], s[4:5]
	v_mov_b32_e32 v1, v7
	v_lshl_add_u64 v[2:3], s[74:75], 0, v[0:1]
	s_or_b64 exec, exec, s[4:5]
	global_load_dword v20, v[2:3], off nt
	v_add_u32_e32 v2, 0x1400, v14
	v_cmp_lt_u32_e32 vcc, s44, v2
	s_and_saveexec_b64 s[4:5], vcc
	s_xor_b64 s[4:5], exec, s[4:5]
	v_ashrrev_i32_e32 v0, 10, v2
	v_add_u32_e32 v0, -1, v0
	v_mul_hi_i32_i24_e32 v1, 0x6000, v0
	v_mul_i32_i24_e32 v0, 0x6000, v0
	v_lshl_add_u64 v[0:1], s[10:11], 0, v[0:1]
	v_lshl_add_u64 v[0:1], v[0:1], 0, v[6:7]
	s_andn2_saveexec_b64 s[4:5], s[4:5]
	v_lshl_add_u64 v[0:1], s[74:75], 0, v[6:7]
	s_or_b64 exec, exec, s[4:5]
	global_load_dword v22, v[0:1], off nt
	v_add_u32_e32 v1, 0x1600, v14
	v_and_b32_e32 v0, 0x3ff, v1
	v_cmp_lt_u32_e32 vcc, s44, v1
	v_lshlrev_b32_e32 v0, 2, v0
	s_and_saveexec_b64 s[4:5], vcc
	s_xor_b64 s[4:5], exec, s[4:5]
	v_ashrrev_i32_e32 v1, 10, v1
	v_add_u32_e32 v1, -1, v1
	v_mul_hi_i32_i24_e32 v3, 0x6000, v1
	v_mul_i32_i24_e32 v2, 0x6000, v1
	v_lshl_add_u64 v[2:3], s[10:11], 0, v[2:3]
	v_mov_b32_e32 v1, v7
	v_lshl_add_u64 v[2:3], v[2:3], 0, v[0:1]
	s_andn2_saveexec_b64 s[4:5], s[4:5]
	v_mov_b32_e32 v1, v7
	v_lshl_add_u64 v[2:3], s[74:75], 0, v[0:1]
	s_or_b64 exec, exec, s[4:5]
	global_load_dword v23, v[2:3], off nt
	v_add_u32_e32 v2, 0x1800, v14
	v_cmp_lt_u32_e32 vcc, s44, v2
	s_and_saveexec_b64 s[4:5], vcc
	s_xor_b64 s[4:5], exec, s[4:5]
	v_ashrrev_i32_e32 v0, 10, v2
	v_add_u32_e32 v0, -1, v0
	v_mul_hi_i32_i24_e32 v1, 0x6000, v0
	v_mul_i32_i24_e32 v0, 0x6000, v0
	v_lshl_add_u64 v[0:1], s[10:11], 0, v[0:1]
	v_lshl_add_u64 v[0:1], v[0:1], 0, v[6:7]
	s_andn2_saveexec_b64 s[4:5], s[4:5]
	v_lshl_add_u64 v[0:1], s[74:75], 0, v[6:7]
	s_or_b64 exec, exec, s[4:5]
	global_load_dword v24, v[0:1], off nt
	v_add_u32_e32 v1, 0x1a00, v14
	v_and_b32_e32 v0, 0x3ff, v1
	v_cmp_lt_u32_e32 vcc, s44, v1
	v_lshlrev_b32_e32 v0, 2, v0
	s_and_saveexec_b64 s[4:5], vcc
	s_xor_b64 s[4:5], exec, s[4:5]
	v_ashrrev_i32_e32 v1, 10, v1
	v_add_u32_e32 v1, -1, v1
	v_mul_hi_i32_i24_e32 v3, 0x6000, v1
	v_mul_i32_i24_e32 v2, 0x6000, v1
	v_lshl_add_u64 v[2:3], s[10:11], 0, v[2:3]
	v_mov_b32_e32 v1, v7
	v_lshl_add_u64 v[2:3], v[2:3], 0, v[0:1]
	s_andn2_saveexec_b64 s[4:5], s[4:5]
	v_mov_b32_e32 v1, v7
	v_lshl_add_u64 v[2:3], s[74:75], 0, v[0:1]
	s_or_b64 exec, exec, s[4:5]
	global_load_dword v26, v[2:3], off nt
	v_add_u32_e32 v2, 0x1c00, v14
	v_cmp_lt_u32_e32 vcc, s44, v2
	s_and_saveexec_b64 s[4:5], vcc
	s_xor_b64 s[4:5], exec, s[4:5]
	v_ashrrev_i32_e32 v0, 10, v2
	v_add_u32_e32 v0, -1, v0
	v_mul_hi_i32_i24_e32 v1, 0x6000, v0
	v_mul_i32_i24_e32 v0, 0x6000, v0
	v_lshl_add_u64 v[0:1], s[10:11], 0, v[0:1]
	v_lshl_add_u64 v[0:1], v[0:1], 0, v[6:7]
	s_andn2_saveexec_b64 s[4:5], s[4:5]
	v_lshl_add_u64 v[0:1], s[74:75], 0, v[6:7]
	s_or_b64 exec, exec, s[4:5]
	global_load_dword v27, v[0:1], off nt
	v_add_u32_e32 v1, 0x1e00, v14
	v_and_b32_e32 v0, 0x3ff, v1
	v_cmp_lt_u32_e32 vcc, s44, v1
	v_lshlrev_b32_e32 v0, 2, v0
	s_and_saveexec_b64 s[4:5], vcc
	s_xor_b64 s[4:5], exec, s[4:5]
	v_ashrrev_i32_e32 v1, 10, v1
	v_add_u32_e32 v1, -1, v1
	v_mul_hi_i32_i24_e32 v3, 0x6000, v1
	v_mul_i32_i24_e32 v2, 0x6000, v1
	v_lshl_add_u64 v[2:3], s[10:11], 0, v[2:3]
	v_mov_b32_e32 v1, v7
	v_lshl_add_u64 v[2:3], v[2:3], 0, v[0:1]
	s_andn2_saveexec_b64 s[4:5], s[4:5]
	v_mov_b32_e32 v1, v7
	v_lshl_add_u64 v[2:3], s[74:75], 0, v[0:1]
	s_or_b64 exec, exec, s[4:5]
	global_load_dword v2, v[2:3], off nt
	v_add_u32_e32 v3, 0x2000, v14
	v_cmp_lt_u32_e32 vcc, s44, v3
	s_and_saveexec_b64 s[4:5], vcc
	s_xor_b64 s[4:5], exec, s[4:5]
	v_ashrrev_i32_e32 v0, 10, v3
	v_add_u32_e32 v0, -1, v0
	v_mul_hi_i32_i24_e32 v1, 0x6000, v0
	v_mul_i32_i24_e32 v0, 0x6000, v0
	v_lshl_add_u64 v[0:1], s[10:11], 0, v[0:1]
	v_lshl_add_u64 v[0:1], v[0:1], 0, v[6:7]
	s_andn2_saveexec_b64 s[4:5], s[4:5]
	v_lshl_add_u64 v[0:1], s[74:75], 0, v[6:7]
	s_or_b64 exec, exec, s[4:5]
	global_load_dword v3, v[0:1], off nt
	v_add_u32_e32 v8, 0x2200, v14
	v_and_b32_e32 v0, 0x3ff, v8
	v_cmp_lt_u32_e32 vcc, s44, v8
	v_lshlrev_b32_e32 v6, 2, v0
	s_and_saveexec_b64 s[4:5], vcc
	s_xor_b64 s[4:5], exec, s[4:5]
	v_ashrrev_i32_e32 v0, 10, v8
	v_add_u32_e32 v0, -1, v0
	v_mul_hi_i32_i24_e32 v1, 0x6000, v0
	v_mul_i32_i24_e32 v0, 0x6000, v0
	v_lshl_add_u64 v[0:1], s[10:11], 0, v[0:1]
	v_lshl_add_u64 v[0:1], v[0:1], 0, v[6:7]
	s_andn2_saveexec_b64 s[4:5], s[4:5]
	v_lshl_add_u64 v[0:1], s[74:75], 0, v[6:7]
	s_or_b64 exec, exec, s[4:5]
	global_load_dword v28, v[0:1], off nt
	s_ashr_i32 s21, s20, 31
	v_lshl_add_u32 v29, v14, 2, 0
	v_ashrrev_i32_e32 v25, 6, v14
	s_lshl_b64 s[30:31], s[20:21], 2
	s_waitcnt vmcnt(16)
	ds_write2st64_b32 v29, v4, v5 offset1:8
	s_waitcnt vmcnt(14)
	ds_write2st64_b32 v29, v9, v10 offset0:16 offset1:24
	s_waitcnt vmcnt(12)
	ds_write2st64_b32 v29, v11, v16 offset0:32 offset1:40
	s_waitcnt vmcnt(10)
	ds_write2st64_b32 v29, v17, v18 offset0:48 offset1:56
	s_waitcnt vmcnt(8)
	ds_write2st64_b32 v29, v19, v20 offset0:64 offset1:72
	s_waitcnt vmcnt(6)
	ds_write2st64_b32 v29, v22, v23 offset0:80 offset1:88
	s_waitcnt vmcnt(4)
	ds_write2st64_b32 v29, v24, v26 offset0:96 offset1:104
	s_waitcnt vmcnt(2)
	ds_write2st64_b32 v29, v27, v2 offset0:112 offset1:120
	v_lshlrev_b32_e32 v2, 7, v25
	v_mov_b64_e32 v[0:1], s[30:31]
	v_mad_i64_i32 v[0:1], s[30:31], v2, s53, v[0:1]
	s_load_dwordx2 s[30:31], s[80:81], 0x68
	v_and_b32_e32 v21, 63, v14
	v_lshlrev_b32_e32 v6, 2, v21
	v_mov_b32_e32 v8, 0
	v_lshl_add_u64 v[0:1], v[0:1], 0, v[6:7]
	s_movk_i32 s4, 0xffe0
	v_lshl_add_u32 v47, v25, 9, 0
	v_mov_b32_e32 v9, v8
	v_mov_b32_e32 v32, v8
	v_mov_b32_e32 v33, v8
	v_mov_b32_e32 v34, v8
	v_mov_b32_e32 v35, v8
	v_mov_b32_e32 v36, v8
	v_mov_b32_e32 v37, v8
	s_waitcnt lgkmcnt(0)
	v_lshl_add_u64 v[16:17], s[30:31], 0, v[0:1]
	v_mov_b32_e32 v19, v8
	s_waitcnt vmcnt(0)
	ds_write2st64_b32 v29, v3, v28 offset0:128 offset1:136
	s_waitcnt lgkmcnt(0)
	s_barrier
.LBB0_380:
	v_add_co_u32_e32 v0, vcc, 0x2000, v16
	global_load_dword v72, v[16:17], off nt
	s_nop 0
	v_addc_co_u32_e32 v1, vcc, 0, v17, vcc
	global_load_dword v74, v[0:1], off offset:3072 nt
	v_add_co_u32_e32 v0, vcc, 0x5000, v16
	v_add_u32_e32 v43, 0x402c, v47
	s_nop 0
	v_addc_co_u32_e32 v1, vcc, 0, v17, vcc
	global_load_dword v76, v[0:1], off offset:2048 nt
	v_add_co_u32_e32 v0, vcc, 0x8000, v16
	v_add_u32_e32 v41, 0x302c, v47
	s_nop 0
	v_addc_co_u32_e32 v1, vcc, 0, v17, vcc
	global_load_dword v78, v[0:1], off offset:1024 nt
	v_add_co_u32_e32 v0, vcc, 0xb000, v16
	v_add_u32_e32 v55, 0x1034, v47
	s_nop 0
	v_addc_co_u32_e32 v1, vcc, 0, v17, vcc
	global_load_dword v60, v[0:1], off nt
	v_add_co_u32_e32 v0, vcc, 0xd000, v16
	v_add_u32_e32 v51, 0x602c, v47
	s_nop 0
	v_addc_co_u32_e32 v1, vcc, 0, v17, vcc
	global_load_dword v62, v[0:1], off offset:3072 nt
	v_add_co_u32_e32 v0, vcc, 0x10000, v16
	v_add_u32_e32 v49, 0x502c, v47
	s_nop 0
	v_addc_co_u32_e32 v1, vcc, 0, v17, vcc
	global_load_dword v64, v[0:1], off offset:2048 nt
	v_add_co_u32_e32 v0, vcc, 0x13000, v16
	v_add_u32_e32 v53, 0x702c, v47
	s_nop 0
	v_addc_co_u32_e32 v1, vcc, 0, v17, vcc
	global_load_dword v68, v[0:1], off offset:1024 nt
	v_add_co_u32_e32 v0, vcc, 0x16000, v16
	v_add_u32_e32 v59, 0x3034, v47
	s_nop 0
	v_addc_co_u32_e32 v1, vcc, 0, v17, vcc
	global_load_dword v66, v[0:1], off nt
	v_add_co_u32_e32 v0, vcc, 0x18000, v16
	v_add_u32_e32 v57, 0x2034, v47
	s_nop 0
	v_addc_co_u32_e32 v1, vcc, 0, v17, vcc
	global_load_dword v70, v[0:1], off offset:3072 nt
	v_add_co_u32_e32 v0, vcc, 0x1b000, v16
	v_add_u32_e32 v39, 0x202c, v47
	s_nop 0
	v_addc_co_u32_e32 v1, vcc, 0, v17, vcc
	global_load_dword v42, v[0:1], off offset:2048 nt
	v_add_co_u32_e32 v0, vcc, 0x1e000, v16
	s_add_i32 s4, s4, 32
	s_nop 0
	v_addc_co_u32_e32 v1, vcc, 0, v17, vcc
	global_load_dword v40, v[0:1], off offset:1024 nt
	v_add_co_u32_e32 v0, vcc, 0x21000, v16
	s_cmpk_gt_u32 s4, 0x5f
	s_nop 0
	v_addc_co_u32_e32 v1, vcc, 0, v17, vcc
	global_load_dword v46, v[0:1], off nt
	v_add_co_u32_e32 v0, vcc, 0x23000, v16
	s_nop 1
	v_addc_co_u32_e32 v1, vcc, 0, v17, vcc
	global_load_dword v44, v[0:1], off offset:3072 nt
	v_add_co_u32_e32 v0, vcc, 0x26000, v16
	s_nop 1
	v_addc_co_u32_e32 v1, vcc, 0, v17, vcc
	global_load_dword v50, v[0:1], off offset:2048 nt
	v_add_co_u32_e32 v0, vcc, 0x29000, v16
	s_nop 1
	v_addc_co_u32_e32 v1, vcc, 0, v17, vcc
	global_load_dword v48, v[0:1], off offset:1024 nt
	v_add_co_u32_e32 v0, vcc, s46, v16
	s_nop 1
	v_addc_co_u32_e32 v1, vcc, 0, v17, vcc
	global_load_dword v54, v[0:1], off nt
	v_add_co_u32_e32 v0, vcc, 0x2e000, v16
	s_nop 1
	v_addc_co_u32_e32 v1, vcc, 0, v17, vcc
	global_load_dword v52, v[0:1], off offset:3072 nt
	v_add_co_u32_e32 v0, vcc, 0x31000, v16
	s_nop 1
	v_addc_co_u32_e32 v1, vcc, 0, v17, vcc
	global_load_dword v58, v[0:1], off offset:2048 nt
	v_add_co_u32_e32 v0, vcc, s47, v16
	s_nop 1
	v_addc_co_u32_e32 v1, vcc, 0, v17, vcc
	global_load_dword v56, v[0:1], off offset:1024 nt
	v_add_co_u32_e32 v0, vcc, 0x37000, v16
	s_nop 1
	v_addc_co_u32_e32 v1, vcc, 0, v17, vcc
	global_load_dword v38, v[0:1], off nt
	v_add_co_u32_e32 v0, vcc, 0x39000, v16
	s_nop 1
	v_addc_co_u32_e32 v1, vcc, 0, v17, vcc
	global_load_dword v24, v[0:1], off offset:3072 nt
	v_add_co_u32_e32 v0, vcc, s48, v16
	s_nop 1
	v_addc_co_u32_e32 v1, vcc, 0, v17, vcc
	global_load_dword v22, v[0:1], off offset:2048 nt
	v_add_co_u32_e32 v0, vcc, 0x3f000, v16
	s_nop 1
	v_addc_co_u32_e32 v1, vcc, 0, v17, vcc
	global_load_dword v23, v[0:1], off offset:1024 nt
	v_add_co_u32_e32 v0, vcc, 0x42000, v16
	s_nop 1
	v_addc_co_u32_e32 v1, vcc, 0, v17, vcc
	global_load_dword v26, v[0:1], off nt
	v_add_co_u32_e32 v0, vcc, s49, v16
	s_nop 1
	v_addc_co_u32_e32 v1, vcc, 0, v17, vcc
	global_load_dword v27, v[0:1], off offset:3072 nt
	v_add_co_u32_e32 v0, vcc, 0x47000, v16
	s_nop 1
	v_addc_co_u32_e32 v1, vcc, 0, v17, vcc
	global_load_dword v28, v[0:1], off offset:2048 nt
	v_add_co_u32_e32 v0, vcc, 0x4a000, v16
	s_nop 1
	v_addc_co_u32_e32 v1, vcc, 0, v17, vcc
	global_load_dword v29, v[0:1], off offset:1024 nt
	v_add_co_u32_e32 v0, vcc, 0x4d000, v16
	s_nop 1
	v_addc_co_u32_e32 v1, vcc, 0, v17, vcc
	global_load_dword v30, v[0:1], off nt
	v_add_co_u32_e32 v0, vcc, 0x4f000, v16
	s_nop 1
	v_addc_co_u32_e32 v1, vcc, 0, v17, vcc
	global_load_dword v31, v[0:1], off offset:3072 nt
	v_add_co_u32_e32 v0, vcc, 0x52000, v16
	s_nop 1
	v_addc_co_u32_e32 v1, vcc, 0, v17, vcc
	global_load_dword v18, v[0:1], off offset:2048 nt
	v_add_co_u32_e32 v0, vcc, 0x55000, v16
	s_nop 1
	v_addc_co_u32_e32 v1, vcc, 0, v17, vcc
	global_load_dword v20, v[0:1], off offset:1024 nt
	ds_read_b128 v[0:3], v47 offset:32768
	v_lshl_add_u64 v[16:17], v[16:17], 0, s[28:29]
	s_waitcnt vmcnt(31) lgkmcnt(0)
	v_fmac_f32_e32 v19, v72, v0
	s_waitcnt vmcnt(30)
	v_fmac_f32_e32 v19, v74, v1
	s_waitcnt vmcnt(29)
	v_fmac_f32_e32 v19, v76, v2
	s_waitcnt vmcnt(28)
	v_fmac_f32_e32 v19, v78, v3
	ds_read_b128 v[0:3], v47 offset:32784
	s_waitcnt vmcnt(27) lgkmcnt(0)
	v_fmac_f32_e32 v19, v60, v0
	s_waitcnt vmcnt(26)
	v_fmac_f32_e32 v19, v62, v1
	s_waitcnt vmcnt(25)
	v_fmac_f32_e32 v19, v64, v2
	s_waitcnt vmcnt(24)
	v_fmac_f32_e32 v19, v68, v3
	ds_read_b128 v[0:3], v47 offset:32800
	ds_read_b128 v[80:83], v47
	ds_read_b128 v[84:87], v47 offset:16
	ds_read_b96 v[4:6], v47 offset:32
	ds_read_b128 v[88:91], v47 offset:4096
	s_waitcnt lgkmcnt(3)
	v_mov_b32_e32 v10, v80
	s_waitcnt vmcnt(23)
	v_fmac_f32_e32 v19, v66, v0
	s_waitcnt lgkmcnt(0)
	v_mov_b32_e32 v11, v88
	v_pk_fma_f32 v[8:9], v[72:73], v[10:11], v[8:9] op_sel_hi:[0,1,1]
	v_mov_b32_e32 v88, v81
	v_pk_fma_f32 v[8:9], v[74:75], v[88:89], v[8:9] op_sel_hi:[0,1,1]
	v_mov_b32_e32 v10, v82
	v_mov_b32_e32 v11, v90
	v_pk_fma_f32 v[8:9], v[76:77], v[10:11], v[8:9] op_sel_hi:[0,1,1]
	v_mov_b32_e32 v90, v83
	v_pk_fma_f32 v[80:81], v[78:79], v[90:91], v[8:9] op_sel_hi:[0,1,1]
	ds_read_b128 v[8:11], v47 offset:4112
	v_mov_b32_e32 v82, v84
	s_waitcnt vmcnt(22)
	v_fmac_f32_e32 v19, v70, v1
	s_waitcnt vmcnt(21)
	v_fmac_f32_e32 v19, v42, v2
	s_waitcnt vmcnt(20)
	v_fmac_f32_e32 v19, v40, v3
	s_waitcnt lgkmcnt(0)
	v_mov_b32_e32 v83, v8
	v_pk_fma_f32 v[80:81], v[60:61], v[82:83], v[80:81] op_sel_hi:[0,1,1]
	v_mov_b32_e32 v8, v85
	v_pk_fma_f32 v[8:9], v[62:63], v[8:9], v[80:81] op_sel_hi:[0,1,1]
	v_mov_b32_e32 v80, v86
	v_mov_b32_e32 v81, v10
	v_pk_fma_f32 v[8:9], v[64:65], v[80:81], v[8:9] op_sel_hi:[0,1,1]
	v_mov_b32_e32 v10, v87
	v_pk_fma_f32 v[80:81], v[68:69], v[10:11], v[8:9] op_sel_hi:[0,1,1]
	ds_read_b96 v[8:10], v47 offset:4128
	v_mov_b32_e32 v82, v4
	v_add_u32_e32 v89, 0x604c, v47
	s_waitcnt lgkmcnt(0)
	v_mov_b32_e32 v83, v8
	v_pk_fma_f32 v[80:81], v[66:67], v[82:83], v[80:81] op_sel_hi:[0,1,1]
	v_mov_b32_e32 v8, v5
	v_pk_fma_f32 v[8:9], v[70:71], v[8:9], v[80:81] op_sel_hi:[0,1,1]
	ds_read_b128 v[80:83], v47 offset:8192
	ds_read_b128 v[84:87], v47 offset:12288
	s_waitcnt lgkmcnt(1)
	v_mov_b32_e32 v4, v80
	s_waitcnt lgkmcnt(0)
	v_mov_b32_e32 v5, v84
	v_pk_fma_f32 v[4:5], v[72:73], v[4:5], v[32:33] op_sel_hi:[0,1,1]
	v_mov_b32_e32 v84, v81
	v_pk_fma_f32 v[4:5], v[74:75], v[84:85], v[4:5] op_sel_hi:[0,1,1]
	v_mov_b32_e32 v32, v82
	v_mov_b32_e32 v33, v86
	v_pk_fma_f32 v[4:5], v[76:77], v[32:33], v[4:5] op_sel_hi:[0,1,1]
	v_mov_b32_e32 v86, v83
	v_pk_fma_f32 v[4:5], v[78:79], v[86:87], v[4:5] op_sel_hi:[0,1,1]
	ds_read_b128 v[80:83], v47 offset:8208
	ds_read_b128 v[84:87], v47 offset:12304
	s_waitcnt lgkmcnt(1)
	v_mov_b32_e32 v32, v80
	s_waitcnt lgkmcnt(0)
	v_mov_b32_e32 v33, v84
	v_pk_fma_f32 v[4:5], v[60:61], v[32:33], v[4:5] op_sel_hi:[0,1,1]
	v_mov_b32_e32 v84, v81
	v_pk_fma_f32 v[4:5], v[62:63], v[84:85], v[4:5] op_sel_hi:[0,1,1]
	v_mov_b32_e32 v32, v82
	v_mov_b32_e32 v33, v86
	v_pk_fma_f32 v[4:5], v[64:65], v[32:33], v[4:5] op_sel_hi:[0,1,1]
	v_mov_b32_e32 v86, v83
	v_pk_fma_f32 v[4:5], v[68:69], v[86:87], v[4:5] op_sel_hi:[0,1,1]
	ds_read_b96 v[86:88], v47 offset:8224
	ds_read_b96 v[90:92], v47 offset:12320
	s_waitcnt lgkmcnt(1)
	v_mov_b32_e32 v32, v86
	s_waitcnt lgkmcnt(0)
	v_mov_b32_e32 v33, v90
	v_mov_b32_e32 v90, v87
	ds_read_b128 v[80:83], v47 offset:16384
	ds_read_b128 v[84:87], v47 offset:20480
	v_pk_fma_f32 v[4:5], v[66:67], v[32:33], v[4:5] op_sel_hi:[0,1,1]
	v_pk_fma_f32 v[4:5], v[70:71], v[90:91], v[4:5] op_sel_hi:[0,1,1]
	v_add_u32_e32 v90, 0x704c, v47
	s_waitcnt lgkmcnt(1)
	v_mov_b32_e32 v32, v80
	s_waitcnt lgkmcnt(0)
	v_mov_b32_e32 v33, v84
	v_pk_fma_f32 v[32:33], v[72:73], v[32:33], v[34:35] op_sel_hi:[0,1,1]
	v_mov_b32_e32 v84, v81
	v_pk_fma_f32 v[32:33], v[74:75], v[84:85], v[32:33] op_sel_hi:[0,1,1]
	v_mov_b32_e32 v34, v82
	v_mov_b32_e32 v35, v86
	v_pk_fma_f32 v[32:33], v[76:77], v[34:35], v[32:33] op_sel_hi:[0,1,1]
	v_mov_b32_e32 v86, v83
	v_pk_fma_f32 v[84:85], v[78:79], v[86:87], v[32:33] op_sel_hi:[0,1,1]
	ds_read_b128 v[32:35], v47 offset:16400
	ds_read_b128 v[80:83], v47 offset:20496
	ds_read_b96 v[94:96], v47 offset:16416
	ds_read_b96 v[98:100], v47 offset:20512
	s_waitcnt lgkmcnt(3)
	v_mov_b32_e32 v86, v32
	s_waitcnt lgkmcnt(2)
	v_mov_b32_e32 v87, v80
	v_pk_fma_f32 v[84:85], v[60:61], v[86:87], v[84:85] op_sel_hi:[0,1,1]
	v_mov_b32_e32 v80, v33
	v_pk_fma_f32 v[32:33], v[62:63], v[80:81], v[84:85] op_sel_hi:[0,1,1]
	v_mov_b32_e32 v80, v34
	v_mov_b32_e32 v81, v82
	v_pk_fma_f32 v[32:33], v[64:65], v[80:81], v[32:33] op_sel_hi:[0,1,1]
	v_mov_b32_e32 v82, v35
	v_pk_fma_f32 v[32:33], v[68:69], v[82:83], v[32:33] op_sel_hi:[0,1,1]
	ds_read_b128 v[80:83], v47 offset:24576
	ds_read_b128 v[84:87], v47 offset:28672
	s_waitcnt lgkmcnt(3)
	v_mov_b32_e32 v34, v94
	s_waitcnt lgkmcnt(2)
	v_mov_b32_e32 v35, v98
	v_pk_fma_f32 v[32:33], v[66:67], v[34:35], v[32:33] op_sel_hi:[0,1,1]
	v_mov_b32_e32 v98, v95
	v_pk_fma_f32 v[34:35], v[70:71], v[98:99], v[32:33] op_sel_hi:[0,1,1]
	s_waitcnt lgkmcnt(1)
	v_mov_b32_e32 v32, v80
	s_waitcnt lgkmcnt(0)
	v_mov_b32_e32 v33, v84
	v_pk_fma_f32 v[32:33], v[72:73], v[32:33], v[36:37] op_sel_hi:[0,1,1]
	v_mov_b32_e32 v84, v81
	v_pk_fma_f32 v[32:33], v[74:75], v[84:85], v[32:33] op_sel_hi:[0,1,1]
	v_mov_b32_e32 v36, v82
	v_mov_b32_e32 v37, v86
	v_pk_fma_f32 v[32:33], v[76:77], v[36:37], v[32:33] op_sel_hi:[0,1,1]
	v_mov_b32_e32 v86, v83
	v_pk_fma_f32 v[32:33], v[78:79], v[86:87], v[32:33] op_sel_hi:[0,1,1]
	ds_read_b128 v[72:75], v47 offset:24592
	ds_read_b128 v[76:79], v47 offset:28688
	v_add_u32_e32 v84, 0x104c, v47
	v_add_u32_e32 v85, 0x204c, v47
	v_add_u32_e32 v86, 0x304c, v47
	s_waitcnt lgkmcnt(1)
	v_mov_b32_e32 v36, v72
	s_waitcnt lgkmcnt(0)
	v_mov_b32_e32 v37, v76
	v_pk_fma_f32 v[32:33], v[60:61], v[36:37], v[32:33] op_sel_hi:[0,1,1]
	v_mov_b32_e32 v76, v73
	v_pk_fma_f32 v[32:33], v[62:63], v[76:77], v[32:33] op_sel_hi:[0,1,1]
	v_mov_b32_e32 v36, v74
	ds_read_b96 v[60:62], v47 offset:24608
	ds_read_b96 v[72:74], v47 offset:28704
	v_mov_b32_e32 v37, v78
	v_pk_fma_f32 v[32:33], v[64:65], v[36:37], v[32:33] op_sel_hi:[0,1,1]
	v_mov_b32_e32 v64, v6
	s_waitcnt lgkmcnt(1)
	v_mov_b32_e32 v36, v60
	s_waitcnt lgkmcnt(0)
	v_mov_b32_e32 v37, v72
	v_mov_b32_e32 v72, v61
	v_mov_b32_e32 v0, v62
	ds_read_b128 v[60:63], v47 offset:32816
	v_mov_b32_e32 v65, v10
	v_add_u32_e32 v6, 0x102c, v47
	v_pk_fma_f32 v[2:3], v[42:43], v[64:65], v[8:9] op_sel_hi:[0,1,1]
	v_mov_b32_e32 v78, v75
	s_waitcnt vmcnt(19) lgkmcnt(0)
	v_fmac_f32_e32 v19, v46, v60
	s_waitcnt vmcnt(18)
	v_fmac_f32_e32 v19, v44, v61
	s_waitcnt vmcnt(17)
	v_fmac_f32_e32 v19, v50, v62
	s_waitcnt vmcnt(16)
	v_fmac_f32_e32 v19, v48, v63
	ds_read_b128 v[60:63], v47 offset:32832
	v_pk_fma_f32 v[32:33], v[68:69], v[78:79], v[32:33] op_sel_hi:[0,1,1]
	v_pk_fma_f32 v[32:33], v[66:67], v[36:37], v[32:33] op_sel_hi:[0,1,1]
	v_pk_fma_f32 v[36:37], v[70:71], v[72:73], v[32:33] op_sel_hi:[0,1,1]
	v_add_u32_e32 v70, 0x103c, v47
	s_waitcnt vmcnt(15) lgkmcnt(0)
	v_fmac_f32_e32 v19, v54, v60
	s_waitcnt vmcnt(14)
	v_fmac_f32_e32 v19, v52, v61
	ds_read2_b32 v[8:9], v47 offset0:11 offset1:12
	ds_read2_b32 v[60:61], v6 offset1:1
	s_waitcnt vmcnt(13)
	v_fmac_f32_e32 v19, v58, v62
	s_waitcnt vmcnt(12)
	v_fmac_f32_e32 v19, v56, v63
	v_add_u32_e32 v77, 0x1044, v47
	s_waitcnt lgkmcnt(1)
	v_mov_b32_e32 v62, v8
	s_waitcnt lgkmcnt(0)
	v_mov_b32_e32 v63, v60
	v_pk_fma_f32 v[2:3], v[40:41], v[62:63], v[2:3] op_sel_hi:[0,1,1]
	v_mov_b32_e32 v60, v9
	v_pk_fma_f32 v[2:3], v[46:47], v[60:61], v[2:3] op_sel_hi:[0,1,1]
	ds_read2_b32 v[8:9], v47 offset0:13 offset1:14
	ds_read2_b32 v[60:61], v55 offset1:1
	v_mov_b32_e32 v32, v88
	v_mov_b32_e32 v33, v92
	v_add_u32_e32 v71, 0x203c, v47
	s_waitcnt lgkmcnt(1)
	v_mov_b32_e32 v62, v8
	s_waitcnt lgkmcnt(0)
	v_mov_b32_e32 v63, v60
	v_pk_fma_f32 v[2:3], v[44:45], v[62:63], v[2:3] op_sel_hi:[0,1,1]
	v_mov_b32_e32 v60, v9
	v_pk_fma_f32 v[2:3], v[50:51], v[60:61], v[2:3] op_sel_hi:[0,1,1]
	ds_read2_b32 v[8:9], v47 offset0:15 offset1:16
	ds_read2_b32 v[60:61], v70 offset1:1
	v_add_u32_e32 v72, 0x303c, v47
	v_add_u32_e32 v78, 0x2044, v47
	v_add_u32_e32 v79, 0x3044, v47
	s_waitcnt lgkmcnt(1)
	v_mov_b32_e32 v62, v8
	s_waitcnt lgkmcnt(0)
	v_mov_b32_e32 v63, v60
	v_pk_fma_f32 v[2:3], v[48:49], v[62:63], v[2:3] op_sel_hi:[0,1,1]
	v_mov_b32_e32 v60, v9
	v_pk_fma_f32 v[2:3], v[54:55], v[60:61], v[2:3] op_sel_hi:[0,1,1]
	ds_read2_b32 v[8:9], v47 offset0:17 offset1:18
	ds_read2_b32 v[60:61], v77 offset1:1
	v_mov_b32_e32 v10, v96
	v_mov_b32_e32 v11, v100
	v_add_u32_e32 v66, 0x4034, v47
	s_waitcnt lgkmcnt(1)
	v_mov_b32_e32 v62, v8
	s_waitcnt lgkmcnt(0)
	v_mov_b32_e32 v63, v60
	v_pk_fma_f32 v[2:3], v[52:53], v[62:63], v[2:3] op_sel_hi:[0,1,1]
	v_mov_b32_e32 v60, v9
	v_pk_fma_f32 v[2:3], v[58:59], v[60:61], v[2:3] op_sel_hi:[0,1,1]
	ds_read2_b32 v[8:9], v47 offset0:19 offset1:20
	ds_read2_b32 v[60:61], v84 offset1:1
	v_add_u32_e32 v67, 0x5034, v47
	v_add_u32_e32 v73, 0x403c, v47
	v_mov_b32_e32 v1, v74
	s_waitcnt lgkmcnt(1)
	v_mov_b32_e32 v62, v8
	s_waitcnt lgkmcnt(0)
	v_mov_b32_e32 v63, v60
	v_pk_fma_f32 v[2:3], v[56:57], v[62:63], v[2:3] op_sel_hi:[0,1,1]
	v_mov_b32_e32 v60, v9
	s_waitcnt vmcnt(11)
	v_pk_fma_f32 v[8:9], v[38:39], v[60:61], v[2:3] op_sel_hi:[0,1,1]
	v_pk_fma_f32 v[2:3], v[42:43], v[32:33], v[4:5] op_sel_hi:[0,1,1]
	ds_read2_b32 v[4:5], v39 offset1:1
	ds_read2_b32 v[32:33], v41 offset1:1
	v_add_u32_e32 v74, 0x503c, v47
	v_add_u32_e32 v80, 0x4044, v47
	v_add_u32_e32 v81, 0x5044, v47
	s_waitcnt lgkmcnt(1)
	v_mov_b32_e32 v60, v4
	s_waitcnt lgkmcnt(0)
	v_mov_b32_e32 v61, v32
	v_pk_fma_f32 v[2:3], v[40:41], v[60:61], v[2:3] op_sel_hi:[0,1,1]
	v_mov_b32_e32 v32, v5
	v_pk_fma_f32 v[2:3], v[46:47], v[32:33], v[2:3] op_sel_hi:[0,1,1]
	ds_read2_b32 v[4:5], v57 offset1:1
	ds_read2_b32 v[32:33], v59 offset1:1
	v_add_u32_e32 v87, 0x404c, v47
	v_add_u32_e32 v88, 0x504c, v47
	v_pk_fma_f32 v[0:1], v[42:43], v[0:1], v[36:37] op_sel_hi:[0,1,1]
	s_waitcnt lgkmcnt(1)
	v_mov_b32_e32 v60, v4
	s_waitcnt lgkmcnt(0)
	v_mov_b32_e32 v61, v32
	v_pk_fma_f32 v[2:3], v[44:45], v[60:61], v[2:3] op_sel_hi:[0,1,1]
	v_mov_b32_e32 v32, v5
	v_pk_fma_f32 v[2:3], v[50:51], v[32:33], v[2:3] op_sel_hi:[0,1,1]
	ds_read2_b32 v[4:5], v71 offset1:1
	ds_read2_b32 v[32:33], v72 offset1:1
	v_add_u32_e32 v68, 0x6034, v47
	v_add_u32_e32 v69, 0x7034, v47
	v_add_u32_e32 v75, 0x603c, v47
	s_waitcnt lgkmcnt(1)
	v_mov_b32_e32 v60, v4
	s_waitcnt lgkmcnt(0)
	v_mov_b32_e32 v61, v32
	v_pk_fma_f32 v[2:3], v[48:49], v[60:61], v[2:3] op_sel_hi:[0,1,1]
	v_mov_b32_e32 v32, v5
	v_pk_fma_f32 v[2:3], v[54:55], v[32:33], v[2:3] op_sel_hi:[0,1,1]
	ds_read2_b32 v[4:5], v78 offset1:1
	ds_read2_b32 v[32:33], v79 offset1:1
	v_add_u32_e32 v76, 0x703c, v47
	v_add_u32_e32 v82, 0x6044, v47
	v_add_u32_e32 v83, 0x7044, v47
	s_waitcnt lgkmcnt(1)
	v_mov_b32_e32 v60, v4
	s_waitcnt lgkmcnt(0)
	v_mov_b32_e32 v61, v32
	v_pk_fma_f32 v[2:3], v[52:53], v[60:61], v[2:3] op_sel_hi:[0,1,1]
	v_mov_b32_e32 v32, v5
	v_pk_fma_f32 v[2:3], v[58:59], v[32:33], v[2:3] op_sel_hi:[0,1,1]
	ds_read2_b32 v[4:5], v85 offset1:1
	ds_read2_b32 v[32:33], v86 offset1:1
	v_add_u32_e32 v62, 0x4068, v47
	v_add_u32_e32 v63, 0x5068, v47
	v_add_u32_e32 v64, 0x6068, v47
	s_waitcnt lgkmcnt(1)
	v_mov_b32_e32 v60, v4
	s_waitcnt lgkmcnt(0)
	v_mov_b32_e32 v61, v32
	v_pk_fma_f32 v[2:3], v[56:57], v[60:61], v[2:3] op_sel_hi:[0,1,1]
	v_mov_b32_e32 v32, v5
	v_pk_fma_f32 v[32:33], v[38:39], v[32:33], v[2:3] op_sel_hi:[0,1,1]
	v_pk_fma_f32 v[2:3], v[42:43], v[10:11], v[34:35] op_sel_hi:[0,1,1]
	ds_read2_b32 v[4:5], v43 offset1:1
	ds_read2_b32 v[10:11], v49 offset1:1
	v_add_u32_e32 v60, 0x2068, v47
	v_add_u32_e32 v61, 0x3068, v47
	v_add_u32_e32 v65, 0x7068, v47
	s_waitcnt lgkmcnt(1)
	v_mov_b32_e32 v34, v4
	s_waitcnt lgkmcnt(0)
	v_mov_b32_e32 v35, v10
	v_pk_fma_f32 v[2:3], v[40:41], v[34:35], v[2:3] op_sel_hi:[0,1,1]
	v_mov_b32_e32 v10, v5
	v_pk_fma_f32 v[2:3], v[46:47], v[10:11], v[2:3] op_sel_hi:[0,1,1]
	ds_read2_b32 v[4:5], v66 offset1:1
	ds_read2_b32 v[10:11], v67 offset1:1
	s_waitcnt lgkmcnt(1)
	v_mov_b32_e32 v34, v4
	s_waitcnt lgkmcnt(0)
	v_mov_b32_e32 v35, v10
	v_pk_fma_f32 v[2:3], v[44:45], v[34:35], v[2:3] op_sel_hi:[0,1,1]
	v_mov_b32_e32 v10, v5
	v_pk_fma_f32 v[2:3], v[50:51], v[10:11], v[2:3] op_sel_hi:[0,1,1]
	ds_read2_b32 v[4:5], v73 offset1:1
	ds_read2_b32 v[10:11], v74 offset1:1
	s_waitcnt lgkmcnt(1)
	v_mov_b32_e32 v34, v4
	s_waitcnt lgkmcnt(0)
	v_mov_b32_e32 v35, v10
	v_pk_fma_f32 v[2:3], v[48:49], v[34:35], v[2:3] op_sel_hi:[0,1,1]
	v_mov_b32_e32 v10, v5
	v_pk_fma_f32 v[2:3], v[54:55], v[10:11], v[2:3] op_sel_hi:[0,1,1]
	ds_read2_b32 v[4:5], v80 offset1:1
	ds_read2_b32 v[10:11], v81 offset1:1
	s_waitcnt lgkmcnt(1)
	v_mov_b32_e32 v34, v4
	s_waitcnt lgkmcnt(0)
	v_mov_b32_e32 v35, v10
	v_pk_fma_f32 v[2:3], v[52:53], v[34:35], v[2:3] op_sel_hi:[0,1,1]
	v_mov_b32_e32 v10, v5
	v_pk_fma_f32 v[2:3], v[58:59], v[10:11], v[2:3] op_sel_hi:[0,1,1]
	ds_read2_b32 v[4:5], v87 offset1:1
	ds_read2_b32 v[10:11], v88 offset1:1
	s_waitcnt lgkmcnt(1)
	v_mov_b32_e32 v34, v4
	s_waitcnt lgkmcnt(0)
	v_mov_b32_e32 v35, v10
	v_pk_fma_f32 v[2:3], v[56:57], v[34:35], v[2:3] op_sel_hi:[0,1,1]
	v_mov_b32_e32 v10, v5
	v_pk_fma_f32 v[34:35], v[38:39], v[10:11], v[2:3] op_sel_hi:[0,1,1]
	ds_read2_b32 v[2:3], v51 offset1:1
	ds_read2_b32 v[4:5], v53 offset1:1
	s_waitcnt lgkmcnt(1)
	v_mov_b32_e32 v10, v2
	s_waitcnt lgkmcnt(0)
	v_mov_b32_e32 v11, v4
	v_pk_fma_f32 v[0:1], v[40:41], v[10:11], v[0:1] op_sel_hi:[0,1,1]
	v_mov_b32_e32 v4, v3
	v_pk_fma_f32 v[0:1], v[46:47], v[4:5], v[0:1] op_sel_hi:[0,1,1]
	ds_read2_b32 v[2:3], v68 offset1:1
	ds_read2_b32 v[4:5], v69 offset1:1
	v_add_u32_e32 v46, 0x3058, v47
	s_waitcnt lgkmcnt(1)
	v_mov_b32_e32 v10, v2
	s_waitcnt lgkmcnt(0)
	v_mov_b32_e32 v11, v4
	v_pk_fma_f32 v[0:1], v[44:45], v[10:11], v[0:1] op_sel_hi:[0,1,1]
	v_mov_b32_e32 v4, v3
	v_pk_fma_f32 v[0:1], v[50:51], v[4:5], v[0:1] op_sel_hi:[0,1,1]
	ds_read2_b32 v[2:3], v75 offset1:1
	ds_read2_b32 v[4:5], v76 offset1:1
	v_add_u32_e32 v44, 0x2058, v47
	s_waitcnt lgkmcnt(1)
	v_mov_b32_e32 v10, v2
	s_waitcnt lgkmcnt(0)
	v_mov_b32_e32 v11, v4
	v_pk_fma_f32 v[0:1], v[48:49], v[10:11], v[0:1] op_sel_hi:[0,1,1]
	v_mov_b32_e32 v4, v3
	v_pk_fma_f32 v[0:1], v[54:55], v[4:5], v[0:1] op_sel_hi:[0,1,1]
	ds_read2_b32 v[2:3], v82 offset1:1
	ds_read2_b32 v[4:5], v83 offset1:1
	s_waitcnt lgkmcnt(1)
	v_mov_b32_e32 v10, v2
	s_waitcnt lgkmcnt(0)
	v_mov_b32_e32 v11, v4
	v_pk_fma_f32 v[0:1], v[52:53], v[10:11], v[0:1] op_sel_hi:[0,1,1]
	v_mov_b32_e32 v4, v3
	v_pk_fma_f32 v[0:1], v[58:59], v[4:5], v[0:1] op_sel_hi:[0,1,1]
	ds_read2_b32 v[2:3], v89 offset1:1
	ds_read2_b32 v[4:5], v90 offset1:1
	v_add_u32_e32 v58, 0x6058, v47
	v_add_u32_e32 v59, 0x7058, v47
	s_waitcnt lgkmcnt(1)
	v_mov_b32_e32 v10, v2
	s_waitcnt lgkmcnt(0)
	v_mov_b32_e32 v11, v4
	v_pk_fma_f32 v[0:1], v[56:57], v[10:11], v[0:1] op_sel_hi:[0,1,1]
	v_mov_b32_e32 v4, v3
	v_pk_fma_f32 v[4:5], v[38:39], v[4:5], v[0:1] op_sel_hi:[0,1,1]
	ds_read_b32 v42, v47 offset:84
	ds_read_b32 v43, v47 offset:4180
	ds_read_b32 v40, v47 offset:8276
	ds_read_b32 v41, v47 offset:12372
	ds_read_b32 v36, v47 offset:16468
	ds_read_b32 v37, v47 offset:20564
	ds_read_b32 v10, v47 offset:24660
	ds_read_b32 v11, v47 offset:28756
	ds_read_b128 v[0:3], v47 offset:32848
	s_waitcnt vmcnt(10)
	v_mov_b32_e32 v39, v24
	s_waitcnt lgkmcnt(5)
	v_pk_fma_f32 v[32:33], v[24:25], v[40:41], v[32:33] op_sel_hi:[0,1,1]
	v_add_u32_e32 v56, 0x4058, v47
	v_add_u32_e32 v57, 0x5058, v47
	s_waitcnt lgkmcnt(0)
	v_pk_mul_f32 v[0:1], v[38:39], v[0:1]
	v_add_u32_e32 v38, 0x1068, v47
	v_add_f32_e32 v0, v19, v0
	v_add_f32_e32 v6, v0, v1
	s_waitcnt vmcnt(8)
	v_pk_mul_f32 v[0:1], v[22:23], v[2:3]
	v_add_u32_e32 v19, 0x1058, v47
	v_add_f32_e32 v0, v6, v0
	v_add_f32_e32 v6, v0, v1
	ds_read_b128 v[0:3], v47 offset:32864
	v_pk_fma_f32 v[4:5], v[24:25], v[10:11], v[4:5] op_sel_hi:[0,1,1]
	s_waitcnt vmcnt(6) lgkmcnt(0)
	v_pk_mul_f32 v[0:1], v[26:27], v[0:1]
	s_nop 0
	v_add_f32_e32 v0, v6, v0
	v_add_f32_e32 v6, v0, v1
	s_waitcnt vmcnt(4)
	v_pk_mul_f32 v[0:1], v[28:29], v[2:3]
	s_nop 0
	v_add_f32_e32 v0, v6, v0
	v_add_f32_e32 v6, v0, v1
	ds_read_b128 v[0:3], v47 offset:32880
	ds_read2_b64 v[48:51], v47 offset0:11 offset1:12
	ds_read2_b64 v[52:55], v19 offset1:1
	s_waitcnt vmcnt(2) lgkmcnt(2)
	v_pk_mul_f32 v[0:1], v[30:31], v[0:1]
	s_nop 0
	v_add_f32_e32 v0, v6, v0
	v_add_f32_e32 v39, v0, v1
	v_pk_fma_f32 v[0:1], v[24:25], v[42:43], v[8:9] op_sel_hi:[0,1,1]
	s_waitcnt lgkmcnt(1)
	v_mov_b32_e32 v8, v48
	s_waitcnt lgkmcnt(0)
	v_mov_b32_e32 v9, v52
	v_pk_fma_f32 v[8:9], v[22:23], v[8:9], v[0:1] op_sel_hi:[0,1,1]
	v_mov_b32_e32 v0, v23
	v_mov_b32_e32 v52, v49
	v_pk_fma_f32 v[8:9], v[0:1], v[52:53], v[8:9] op_sel_hi:[0,1,1]
	v_mov_b32_e32 v42, v50
	v_mov_b32_e32 v43, v54
	v_pk_fma_f32 v[8:9], v[26:27], v[42:43], v[8:9] op_sel_hi:[0,1,1]
	v_mov_b32_e32 v6, v27
	v_mov_b32_e32 v54, v51
	v_pk_fma_f32 v[8:9], v[6:7], v[54:55], v[8:9] op_sel_hi:[0,1,1]
	ds_read2_b64 v[48:51], v47 offset0:13 offset1:14
	ds_read2_b64 v[52:55], v38 offset1:1
	v_mov_b32_e32 v38, v29
	s_waitcnt lgkmcnt(1)
	v_mov_b32_e32 v42, v48
	s_waitcnt lgkmcnt(0)
	v_mov_b32_e32 v43, v52
	v_pk_fma_f32 v[8:9], v[28:29], v[42:43], v[8:9] op_sel_hi:[0,1,1]
	v_mov_b32_e32 v52, v49
	v_mov_b32_e32 v42, v50
	v_mov_b32_e32 v43, v54
	v_mov_b32_e32 v54, v51
	ds_read_b64 v[48:49], v47 offset:120
	ds_read_b64 v[50:51], v47 offset:4216
	v_pk_fma_f32 v[8:9], v[38:39], v[52:53], v[8:9] op_sel_hi:[0,1,1]
	v_pk_fma_f32 v[8:9], v[30:31], v[42:43], v[8:9] op_sel_hi:[0,1,1]
	v_mov_b32_e32 v42, v31
	v_pk_fma_f32 v[8:9], v[42:43], v[54:55], v[8:9] op_sel_hi:[0,1,1]
	s_waitcnt lgkmcnt(1)
	v_mov_b32_e32 v52, v48
	s_waitcnt lgkmcnt(0)
	v_mov_b32_e32 v53, v50
	s_waitcnt vmcnt(1)
	v_pk_fma_f32 v[8:9], v[18:19], v[52:53], v[8:9] op_sel_hi:[0,1,1]
	v_mov_b32_e32 v50, v49
	s_waitcnt vmcnt(0)
	v_pk_fma_f32 v[8:9], v[20:21], v[50:51], v[8:9] op_sel_hi:[0,1,1]
	ds_read2_b64 v[48:51], v44 offset1:1
	ds_read2_b64 v[52:55], v46 offset1:1
	s_waitcnt lgkmcnt(1)
	v_mov_b32_e32 v40, v48
	s_waitcnt lgkmcnt(0)
	v_mov_b32_e32 v41, v52
	v_pk_fma_f32 v[32:33], v[22:23], v[40:41], v[32:33] op_sel_hi:[0,1,1]
	v_mov_b32_e32 v52, v49
	v_pk_fma_f32 v[32:33], v[0:1], v[52:53], v[32:33] op_sel_hi:[0,1,1]
	v_mov_b32_e32 v40, v50
	v_mov_b32_e32 v41, v54
	v_pk_fma_f32 v[32:33], v[26:27], v[40:41], v[32:33] op_sel_hi:[0,1,1]
	v_mov_b32_e32 v54, v51
	v_pk_fma_f32 v[32:33], v[6:7], v[54:55], v[32:33] op_sel_hi:[0,1,1]
	ds_read2_b64 v[48:51], v60 offset1:1
	ds_read2_b64 v[52:55], v61 offset1:1
	s_waitcnt lgkmcnt(1)
	v_mov_b32_e32 v40, v48
	s_waitcnt lgkmcnt(0)
	v_mov_b32_e32 v41, v52
	v_pk_fma_f32 v[32:33], v[28:29], v[40:41], v[32:33] op_sel_hi:[0,1,1]
	v_mov_b32_e32 v52, v49
	v_pk_fma_f32 v[32:33], v[38:39], v[52:53], v[32:33] op_sel_hi:[0,1,1]
	v_mov_b32_e32 v40, v50
	v_mov_b32_e32 v41, v54
	v_pk_fma_f32 v[32:33], v[30:31], v[40:41], v[32:33] op_sel_hi:[0,1,1]
	ds_read_b64 v[40:41], v47 offset:8312
	ds_read_b64 v[48:49], v47 offset:12408
	v_mov_b32_e32 v54, v51
	v_pk_fma_f32 v[32:33], v[42:43], v[54:55], v[32:33] op_sel_hi:[0,1,1]
	s_waitcnt lgkmcnt(1)
	v_mov_b32_e32 v50, v40
	s_waitcnt lgkmcnt(0)
	v_mov_b32_e32 v51, v48
	v_pk_fma_f32 v[32:33], v[18:19], v[50:51], v[32:33] op_sel_hi:[0,1,1]
	v_mov_b32_e32 v48, v41
	v_pk_fma_f32 v[32:33], v[20:21], v[48:49], v[32:33] op_sel_hi:[0,1,1]
	v_pk_fma_f32 v[40:41], v[24:25], v[36:37], v[34:35] op_sel_hi:[0,1,1]
	ds_read2_b64 v[34:37], v56 offset1:1
	ds_read2_b64 v[48:51], v57 offset1:1
	s_waitcnt lgkmcnt(1)
	v_mov_b32_e32 v52, v34
	s_waitcnt lgkmcnt(0)
	v_mov_b32_e32 v53, v48
	v_pk_fma_f32 v[40:41], v[22:23], v[52:53], v[40:41] op_sel_hi:[0,1,1]
	v_mov_b32_e32 v48, v35
	v_pk_fma_f32 v[34:35], v[0:1], v[48:49], v[40:41] op_sel_hi:[0,1,1]
	v_mov_b32_e32 v40, v36
	v_mov_b32_e32 v41, v50
	v_pk_fma_f32 v[34:35], v[26:27], v[40:41], v[34:35] op_sel_hi:[0,1,1]
	v_mov_b32_e32 v50, v37
	v_pk_fma_f32 v[40:41], v[6:7], v[50:51], v[34:35] op_sel_hi:[0,1,1]
	ds_read2_b64 v[34:37], v62 offset1:1
	ds_read2_b64 v[48:51], v63 offset1:1
	s_waitcnt lgkmcnt(1)
	v_mov_b32_e32 v52, v34
	s_waitcnt lgkmcnt(0)
	v_mov_b32_e32 v53, v48
	v_pk_fma_f32 v[40:41], v[28:29], v[52:53], v[40:41] op_sel_hi:[0,1,1]
	v_mov_b32_e32 v48, v35
	v_pk_fma_f32 v[34:35], v[38:39], v[48:49], v[40:41] op_sel_hi:[0,1,1]
	v_mov_b32_e32 v40, v36
	v_mov_b32_e32 v41, v50
	v_pk_fma_f32 v[34:35], v[30:31], v[40:41], v[34:35] op_sel_hi:[0,1,1]
	v_mov_b32_e32 v50, v37
	ds_read_b64 v[36:37], v47 offset:16504
	ds_read_b64 v[40:41], v47 offset:20600
	v_pk_fma_f32 v[34:35], v[42:43], v[50:51], v[34:35] op_sel_hi:[0,1,1]
	s_waitcnt lgkmcnt(1)
	v_mov_b32_e32 v48, v36
	s_waitcnt lgkmcnt(0)
	v_mov_b32_e32 v49, v40
	v_pk_fma_f32 v[34:35], v[18:19], v[48:49], v[34:35] op_sel_hi:[0,1,1]
	ds_read2_b64 v[48:51], v58 offset1:1
	ds_read2_b64 v[52:55], v59 offset1:1
	v_mov_b32_e32 v40, v37
	v_pk_fma_f32 v[34:35], v[20:21], v[40:41], v[34:35] op_sel_hi:[0,1,1]
	s_waitcnt lgkmcnt(1)
	v_mov_b32_e32 v10, v48
	s_waitcnt lgkmcnt(0)
	v_mov_b32_e32 v11, v52
	v_pk_fma_f32 v[4:5], v[22:23], v[10:11], v[4:5] op_sel_hi:[0,1,1]
	v_mov_b32_e32 v52, v49
	v_pk_fma_f32 v[0:1], v[0:1], v[52:53], v[4:5] op_sel_hi:[0,1,1]
	v_mov_b32_e32 v4, v50
	v_mov_b32_e32 v5, v54
	v_pk_fma_f32 v[0:1], v[26:27], v[4:5], v[0:1] op_sel_hi:[0,1,1]
	v_mov_b32_e32 v54, v51
	v_pk_fma_f32 v[0:1], v[6:7], v[54:55], v[0:1] op_sel_hi:[0,1,1]
	ds_read2_b64 v[48:51], v64 offset1:1
	ds_read2_b64 v[52:55], v65 offset1:1
	s_waitcnt lgkmcnt(1)
	v_mov_b32_e32 v4, v48
	s_waitcnt lgkmcnt(0)
	v_mov_b32_e32 v5, v52
	v_pk_fma_f32 v[0:1], v[28:29], v[4:5], v[0:1] op_sel_hi:[0,1,1]
	v_mov_b32_e32 v52, v49
	v_pk_fma_f32 v[0:1], v[38:39], v[52:53], v[0:1] op_sel_hi:[0,1,1]
	v_mov_b32_e32 v4, v50
	v_mov_b32_e32 v5, v54
	v_pk_fma_f32 v[0:1], v[30:31], v[4:5], v[0:1] op_sel_hi:[0,1,1]
	ds_read_b64 v[4:5], v47 offset:24696
	ds_read_b64 v[10:11], v47 offset:28792
	v_mov_b32_e32 v54, v51
	v_pk_fma_f32 v[0:1], v[42:43], v[54:55], v[0:1] op_sel_hi:[0,1,1]
	v_add_u32_e32 v47, 0x80, v47
	s_waitcnt lgkmcnt(1)
	v_mov_b32_e32 v22, v4
	s_waitcnt lgkmcnt(0)
	v_mov_b32_e32 v23, v10
	v_pk_fma_f32 v[0:1], v[18:19], v[22:23], v[0:1] op_sel_hi:[0,1,1]
	v_mov_b32_e32 v10, v5
	v_mov_b32_e32 v19, v20
	v_pk_fma_f32 v[36:37], v[20:21], v[10:11], v[0:1] op_sel_hi:[0,1,1]
	v_pk_mul_f32 v[0:1], v[18:19], v[2:3]
	s_nop 0
	v_add_f32_e32 v0, v39, v0
	v_add_f32_e32 v19, v0, v1
	s_cbranch_scc0 .LBB0_380
	v_lshl_add_u32 v0, v21, 2, 0
	v_mad_u64_u32 v[2:3], s[4:5], v25, s50, v[0:1]
	v_cmp_gt_i32_e32 vcc, s51, v14
	ds_write2st64_b32 v2, v8, v9 offset0:144 offset1:145
	ds_write2st64_b32 v2, v32, v33 offset0:146 offset1:147
	ds_write2st64_b32 v2, v34, v35 offset0:148 offset1:149
	ds_write2st64_b32 v2, v36, v37 offset0:150 offset1:151
	ds_write_b32 v2, v19 offset:38912
	s_waitcnt lgkmcnt(0)
	s_barrier
	s_and_saveexec_b64 s[30:31], vcc
	s_cbranch_execz .LBB0_216
	s_add_i32 s4, s58, 0xfffffa00
	s_cmpk_lt_u32 s4, 0x180
	v_and_b32_e32 v2, 31, v14
	s_cselect_b64 vcc, -1, 0
	s_and_b32 s4, s55, 0x3fffff8
	v_lshlrev_b32_e32 v4, 1, v2
	s_cmp_eq_u32 s4, 32
	v_mov_b32_e32 v3, s58
	v_subrev_u32_e32 v5, 31, v4
	v_cmp_gt_u32_e64 s[4:5], 16, v2
	v_bitop3_b32 v3, v21, s54, v3 bitop3:0xc8
	v_or_b32_e32 v1, s58, v21
	v_cndmask_b32_e64 v2, v5, v4, s[4:5]
	v_add_u32_e32 v2, v2, v3
	s_cselect_b64 s[4:5], -1, 0
	v_cndmask_b32_e64 v1, v1, v2, s[4:5]
	v_lshlrev_b32_e32 v2, 1, v21
	v_subrev_u32_e32 v3, 63, v2
	v_cmp_gt_u32_e64 s[4:5], 32, v21
	s_and_b32 s21, s58, 0x7c0
	s_mov_b64 s[34:35], -1
	v_cndmask_b32_e64 v2, v3, v2, s[4:5]
	v_add_u32_e32 v2, s21, v2
	v_cndmask_b32_e32 v2, v1, v2, vcc
	v_max_i32_e32 v1, 64, v14
	v_sub_u32_e32 v1, v1, v14
	v_ashrrev_i32_e32 v3, 31, v2
	v_add_u32_e32 v1, 0x1ff, v1
	v_lshl_add_u64 v[2:3], v[2:3], 2, s[12:13]
	v_cmp_lt_u32_e32 vcc, s52, v1
	s_and_saveexec_b64 s[4:5], vcc
	s_cbranch_execz .LBB0_390
	v_lshrrev_b32_e32 v1, 9, v1
	v_add_u32_e32 v6, -1, v1
	v_cmp_lt_u32_e32 vcc, 1, v6
	v_mov_b64_e32 v[4:5], v[14:15]
	s_and_saveexec_b64 s[34:35], vcc
	s_cbranch_execz .LBB0_387
	v_lshrrev_b32_e32 v4, 1, v6
	v_add_u32_e32 v4, 1, v4
	v_and_b32_e32 v8, -2, v4
	s_mov_b64 s[56:57], 0
	v_mov_b64_e32 v[4:5], v[14:15]

.LBB0_404:
	s_lshr_b32 s8, s8, 10
	s_add_i32 s8, s8, 1
	s_and_b64 s[28:29], s[28:29], exec
	s_cselect_b32 s8, 0, s8
	s_mul_hi_u32 s28, s8, 0x6000
	s_mulk_i32 s8, 0x6000
	s_add_u32 s8, s74, s8
	s_addc_u32 s29, s75, s28
	s_add_u32 s28, s8, 0x1000
	v_lshlrev_b32_e32 v96, 2, v80
	s_addc_u32 s29, s29, 0
	global_load_dwordx4 v[76:79], v96, s[24:25] nt
	global_load_dwordx4 v[72:75], v96, s[28:29]
	global_load_dwordx4 v[64:67], v96, s[24:25] offset:1024 nt
	global_load_dwordx4 v[60:63], v96, s[24:25] offset:2048 nt
	global_load_dwordx4 v[68:71], v81, s[28:29]
	global_load_dwordx4 v[56:59], v94, s[28:29]
	global_load_dwordx4 v[52:55], v96, s[24:25] offset:3072 nt
	global_load_dwordx4 v[48:51], v95, s[28:29]
	s_add_i32 s24, s76, s0
	s_cmpk_lt_i32 s24, 0x3000
	s_cselect_b64 s[28:29], -1, 0
	s_cmpk_gt_i32 s24, 0x2fff
	s_cbranch_scc1 .LBB0_410
	s_cmpk_lt_i32 s24, 0x1000
	s_cselect_b64 s[34:35], -1, 0
	s_mov_b64 s[46:47], -1
	s_and_b64 vcc, exec, s[34:35]
	s_cbranch_vccnz .LBB0_407
	s_add_i32 s8, s24, 0xfffff000
	s_lshl_b64 s[30:31], s[8:9], 12
	s_add_u32 s30, s18, s30
	s_addc_u32 s31, s19, s31
	s_mov_b64 s[46:47], 0

.LBB0_409:
	s_lshr_b32 s8, s8, 10
	s_add_i32 s8, s8, 1
	s_and_b64 s[34:35], exec, s[34:35]
	s_cselect_b32 s8, 0, s8
	s_mul_hi_u32 s25, s8, 0x6000
	s_mulk_i32 s8, 0x6000
	s_add_u32 s8, s74, s8
	s_addc_u32 s25, s75, s25
	s_add_u32 s34, s8, 0x1000
	s_addc_u32 s35, s25, 0
	global_load_dwordx4 v[4:7], v96, s[30:31] nt
	global_load_dwordx4 v[0:3], v96, s[34:35]
	global_load_dwordx4 v[12:15], v96, s[30:31] offset:1024 nt
	global_load_dwordx4 v[20:23], v96, s[30:31] offset:2048 nt
	global_load_dwordx4 v[8:11], v81, s[34:35]
	global_load_dwordx4 v[16:19], v94, s[34:35]
	global_load_dwordx4 v[28:31], v96, s[30:31] offset:3072 nt
	global_load_dwordx4 v[24:27], v95, s[34:35]
